# first K-step starts accumulators from C=0 (zero-init movs dropped) + dead log range handling removed in the lora decay epilogue
# speedup vs baseline: 1.0384x; 1.0039x over previous
.LBB0_111:
	v_mov_b64_e32 v[0:1], v[132:133]
	v_mov_b64_e32 v[2:3], v[132:133]
	v_mov_b32_e32 v6, v154
	s_lshl_b32 s46, s13, 8
	s_mov_b64 s[4:5], 0x11a00000
	v_ashrrev_i32_e32 v9, 3, v6
	v_add_u32_e32 v4, s46, v9
	v_lshl_add_u64 v[0:1], v[0:1], 0, s[4:5]
	v_lshrrev_b32_e32 v8, 4, v6
	v_ashrrev_i32_e32 v5, 31, v4
	v_xor_b32_e32 v10, v8, v6
	v_lshlrev_b64 v[4:5], 11, v[4:5]
	v_lshl_add_u64 v[0:1], v[0:1], 0, v[4:5]
	v_lshlrev_b32_e32 v4, 4, v10
	s_lshl_b32 s6, s39, 8
	v_and_b32_e32 v134, 0x70, v4
	v_lshl_add_u64 v[128:129], v[0:1], 0, v[134:135]
	v_add_u32_e32 v0, s6, v9
	v_ashrrev_i32_e32 v1, 31, v0
	v_lshlrev_b64 v[0:1], 11, v[0:1]
	v_ashrrev_i32_e32 v7, 6, v6
	v_lshl_add_u64 v[0:1], v[2:3], 0, v[0:1]
	v_lshl_add_u64 v[130:131], v[0:1], 0, v[134:135]
	v_ashrrev_i32_e32 v0, 1, v6
	v_and_b32_e32 v134, 0xffffffc0, v0
	v_lshlrev_b32_e32 v0, 7, v7
	v_and_b32_e32 v144, 0x80, v0
	v_lshlrev_b32_e32 v0, 10, v7
	v_add_u32_e32 v145, 0, v0
	v_add_u32_e32 v146, s79, v0
	v_readfirstlane_b32 s4, v145
	s_mov_b32 m0, s4
	v_readfirstlane_b32 s4, v146
	v_add_u32_e32 v147, 0x2000, v145
	global_load_lds_dwordx4 v[128:129], off
	s_mov_b32 m0, s4
	s_mov_b64 s[16:17], 0x20000
	v_readfirstlane_b32 s4, v147
	v_add_u32_e32 v148, 0x2000, v146
	global_load_lds_dwordx4 v[130:131], off
	v_lshl_add_u64 v[0:1], v[128:129], 0, s[16:17]
	s_mov_b32 m0, s4
	v_readfirstlane_b32 s4, v148
	v_add_u32_e32 v149, 0x4000, v145
	global_load_lds_dwordx4 v[0:1], off
	v_lshl_add_u64 v[0:1], v[130:131], 0, s[16:17]
	s_mov_b32 m0, s4
	s_mov_b64 s[16:17], 0x40000
	v_readfirstlane_b32 s4, v149
	v_add_u32_e32 v150, 0x4000, v146
	global_load_lds_dwordx4 v[0:1], off
	v_lshl_add_u64 v[0:1], v[128:129], 0, s[16:17]
	s_mov_b32 m0, s4
	v_readfirstlane_b32 s4, v150
	v_add_u32_e32 v151, 0x6000, v145
	global_load_lds_dwordx4 v[0:1], off
	v_lshl_add_u64 v[0:1], v[130:131], 0, s[16:17]
	s_mov_b32 m0, s4
	s_mov_b64 s[16:17], 0x60000
	v_readfirstlane_b32 s4, v151
	v_add_u32_e32 v152, 0x6000, v146
	global_load_lds_dwordx4 v[0:1], off
	v_lshl_add_u64 v[0:1], v[128:129], 0, s[16:17]
	s_mov_b32 m0, s4
	v_readfirstlane_b32 s4, v152
	global_load_lds_dwordx4 v[0:1], off
	v_lshl_add_u64 v[0:1], v[130:131], 0, s[16:17]
	s_mov_b32 m0, s4
	v_and_b32_e32 v143, 15, v6
	global_load_lds_dwordx4 v[0:1], off
	s_mov_b64 s[100:101], 0x80
	v_lshl_add_u64 v[240:241], v[128:129], 0, s[100:101]
	s_mov_b64 s[100:101], 0x20080
	v_lshl_add_u64 v[242:243], v[128:129], 0, s[100:101]
	s_mov_b64 s[100:101], 0x40080
	v_lshl_add_u64 v[244:245], v[128:129], 0, s[100:101]
	s_mov_b64 s[100:101], 0x60080
	v_lshl_add_u64 v[246:247], v[128:129], 0, s[100:101]
	s_mov_b64 s[100:101], 0x80
	v_lshl_add_u64 v[138:139], v[130:131], 0, s[100:101]
	s_mov_b64 s[100:101], 0x20080
	v_lshl_add_u64 v[140:141], v[130:131], 0, s[100:101]
	s_mov_b64 s[100:101], 0x40080
	v_lshl_add_u64 v[250:251], v[130:131], 0, s[100:101]
	s_mov_b64 s[100:101], 0x60080
	v_lshl_add_u64 v[252:253], v[130:131], 0, s[100:101]
	v_readfirstlane_b32 s100, v145
	v_readfirstlane_b32 s101, v146
	s_nop 3
	s_add_u32 m0, s100, 0x8000
	s_nop 0
	global_load_lds_dwordx4 v[240:241], off
	v_lshl_add_u64 v[240:241], v[240:241], 0, s[34:35]
	s_add_u32 m0, s100, 0xa000
	s_nop 0
	global_load_lds_dwordx4 v[242:243], off
	v_lshl_add_u64 v[242:243], v[242:243], 0, s[34:35]
	s_add_u32 m0, s100, 0xc000
	s_nop 0
	global_load_lds_dwordx4 v[244:245], off
	v_lshl_add_u64 v[244:245], v[244:245], 0, s[34:35]
	s_add_u32 m0, s100, 0xe000
	s_nop 0
	global_load_lds_dwordx4 v[246:247], off
	v_lshl_add_u64 v[246:247], v[246:247], 0, s[34:35]
	s_add_u32 m0, s101, 0x8000
	s_nop 0
	global_load_lds_dwordx4 v[138:139], off
	v_lshl_add_u64 v[138:139], v[138:139], 0, s[34:35]
	s_add_u32 m0, s101, 0xa000
	s_nop 0
	global_load_lds_dwordx4 v[140:141], off
	v_lshl_add_u64 v[140:141], v[140:141], 0, s[34:35]
	s_add_u32 m0, s101, 0xc000
	s_nop 0
	global_load_lds_dwordx4 v[250:251], off
	v_lshl_add_u64 v[250:251], v[250:251], 0, s[34:35]
	s_add_u32 m0, s101, 0xe000
	s_nop 0
	global_load_lds_dwordx4 v[252:253], off
	v_lshl_add_u64 v[252:253], v[252:253], 0, s[34:35]
	s_add_u32 m0, s100, 0x20000
	s_nop 0
	global_load_lds_dwordx4 v[240:241], off
	v_lshl_add_u64 v[240:241], v[240:241], 0, s[34:35]
	s_add_u32 m0, s100, 0x22000
	s_nop 0
	global_load_lds_dwordx4 v[242:243], off
	v_lshl_add_u64 v[242:243], v[242:243], 0, s[34:35]
	s_add_u32 m0, s100, 0x24000
	s_nop 0
	global_load_lds_dwordx4 v[244:245], off
	v_lshl_add_u64 v[244:245], v[244:245], 0, s[34:35]
	s_add_u32 m0, s100, 0x26000
	s_nop 0
	global_load_lds_dwordx4 v[246:247], off
	v_lshl_add_u64 v[246:247], v[246:247], 0, s[34:35]
	v_bfe_u32 v142, v6, 4, 2
	v_bfe_u32 v0, v6, 1, 3
	v_or_b32_e32 v2, v134, v143
	v_or_b32_e32 v3, v144, v143
	v_bitop3_b32 v1, v8, v0, 3 bitop3:0x6c
	v_bitop3_b32 v0, v142, v0, 4 bitop3:0x36
	v_lshl_add_u32 v153, v2, 7, 0
	v_lshl_add_u32 v169, v3, 7, s79
	v_lshlrev_b32_e32 v170, 4, v1
	v_lshlrev_b32_e32 v171, 4, v0
	s_mov_b64 s[4:5], 0
	s_waitcnt vmcnt(12) lgkmcnt(0)
	s_barrier
	s_branch .LBB0_113
.LBB0_113:
	v_add_u32_e32 v172, v153, v170
	v_add_u32_e32 v173, v153, v171
	v_add_u32_e32 v174, v169, v170
	v_add_u32_e32 v175, v169, v171
	v_add_u32_e32 v254, 0x20000, v172
	v_add_u32_e32 v255, 0x20000, v173
	s_nop 1
	ds_read_b128 v[176:179], v172 offset:0
	ds_read_b128 v[180:183], v172 offset:2048
	ds_read_b128 v[184:187], v172 offset:4096
	ds_read_b128 v[188:191], v172 offset:6144
	ds_read_b128 v[208:211], v174 offset:0
	ds_read_b128 v[212:215], v174 offset:2048
	ds_read_b128 v[216:219], v174 offset:4096
	ds_read_b128 v[220:223], v174 offset:6144
	s_waitcnt lgkmcnt(0)
	v_mfma_f32_16x16x32_bf16 v[120:123], v[208:211], v[176:179], 0
	ds_read_b128 v[224:227], v174 offset:8192
	v_mfma_f32_16x16x32_bf16 v[112:115], v[212:215], v[176:179], 0
	ds_read_b128 v[228:231], v174 offset:10240
	v_mfma_f32_16x16x32_bf16 v[124:127], v[216:219], v[176:179], 0
	ds_read_b128 v[232:235], v174 offset:12288
	v_mfma_f32_16x16x32_bf16 v[116:119], v[220:223], v[176:179], 0
	ds_read_b128 v[236:239], v174 offset:14336
	v_mfma_f32_16x16x32_bf16 v[88:91], v[208:211], v[180:183], 0
	v_mfma_f32_16x16x32_bf16 v[80:83], v[212:215], v[180:183], 0
	v_mfma_f32_16x16x32_bf16 v[92:95], v[216:219], v[180:183], 0
	v_mfma_f32_16x16x32_bf16 v[84:87], v[220:223], v[180:183], 0
	v_mfma_f32_16x16x32_bf16 v[56:59], v[208:211], v[184:187], 0
	v_mfma_f32_16x16x32_bf16 v[48:51], v[212:215], v[184:187], 0
	v_mfma_f32_16x16x32_bf16 v[60:63], v[216:219], v[184:187], 0
	v_mfma_f32_16x16x32_bf16 v[52:55], v[220:223], v[184:187], 0
	v_mfma_f32_16x16x32_bf16 v[24:27], v[208:211], v[188:191], 0
	v_mfma_f32_16x16x32_bf16 v[16:19], v[212:215], v[188:191], 0
	v_mfma_f32_16x16x32_bf16 v[28:31], v[216:219], v[188:191], 0
	v_mfma_f32_16x16x32_bf16 v[20:23], v[220:223], v[188:191], 0
	s_waitcnt lgkmcnt(0)
	v_mfma_f32_16x16x32_bf16 v[104:107], v[224:227], v[176:179], 0
	ds_read_b128 v[192:195], v173 offset:0
	v_mfma_f32_16x16x32_bf16 v[96:99], v[228:231], v[176:179], 0
	ds_read_b128 v[196:199], v173 offset:2048
	v_mfma_f32_16x16x32_bf16 v[108:111], v[232:235], v[176:179], 0
	ds_read_b128 v[200:203], v173 offset:4096
	v_mfma_f32_16x16x32_bf16 v[100:103], v[236:239], v[176:179], 0
	ds_read_b128 v[204:207], v173 offset:6144
	v_mfma_f32_16x16x32_bf16 v[72:75], v[224:227], v[180:183], 0
	ds_read_b128 v[208:211], v175 offset:0
	v_mfma_f32_16x16x32_bf16 v[64:67], v[228:231], v[180:183], 0
	ds_read_b128 v[212:215], v175 offset:2048
	v_mfma_f32_16x16x32_bf16 v[76:79], v[232:235], v[180:183], 0
	ds_read_b128 v[216:219], v175 offset:4096
	v_mfma_f32_16x16x32_bf16 v[68:71], v[236:239], v[180:183], 0
	ds_read_b128 v[220:223], v175 offset:6144
	v_mfma_f32_16x16x32_bf16 v[40:43], v[224:227], v[184:187], 0
	v_mfma_f32_16x16x32_bf16 v[32:35], v[228:231], v[184:187], 0
	v_mfma_f32_16x16x32_bf16 v[44:47], v[232:235], v[184:187], 0
	v_mfma_f32_16x16x32_bf16 v[36:39], v[236:239], v[184:187], 0
	v_mfma_f32_16x16x32_bf16 v[8:11], v[224:227], v[188:191], 0
	v_mfma_f32_16x16x32_bf16 v[0:3], v[228:231], v[188:191], 0
	v_mfma_f32_16x16x32_bf16 v[12:15], v[232:235], v[188:191], 0
	v_mfma_f32_16x16x32_bf16 v[4:7], v[236:239], v[188:191], 0
	s_waitcnt lgkmcnt(0)
	v_mfma_f32_16x16x32_bf16 v[120:123], v[208:211], v[192:195], v[120:123]
	ds_read_b128 v[224:227], v175 offset:8192
	v_mfma_f32_16x16x32_bf16 v[112:115], v[212:215], v[192:195], v[112:115]
	ds_read_b128 v[228:231], v175 offset:10240
	v_mfma_f32_16x16x32_bf16 v[124:127], v[216:219], v[192:195], v[124:127]
	ds_read_b128 v[232:235], v175 offset:12288
	v_mfma_f32_16x16x32_bf16 v[116:119], v[220:223], v[192:195], v[116:119]
	ds_read_b128 v[236:239], v175 offset:14336
	v_mfma_f32_16x16x32_bf16 v[88:91], v[208:211], v[196:199], v[88:91]
	v_mfma_f32_16x16x32_bf16 v[80:83], v[212:215], v[196:199], v[80:83]
	v_mfma_f32_16x16x32_bf16 v[92:95], v[216:219], v[196:199], v[92:95]
	v_mfma_f32_16x16x32_bf16 v[84:87], v[220:223], v[196:199], v[84:87]
	v_mfma_f32_16x16x32_bf16 v[56:59], v[208:211], v[200:203], v[56:59]
	v_mfma_f32_16x16x32_bf16 v[48:51], v[212:215], v[200:203], v[48:51]
	v_mfma_f32_16x16x32_bf16 v[60:63], v[216:219], v[200:203], v[60:63]
	v_mfma_f32_16x16x32_bf16 v[52:55], v[220:223], v[200:203], v[52:55]
	v_mfma_f32_16x16x32_bf16 v[24:27], v[208:211], v[204:207], v[24:27]
	v_mfma_f32_16x16x32_bf16 v[16:19], v[212:215], v[204:207], v[16:19]
	v_mfma_f32_16x16x32_bf16 v[28:31], v[216:219], v[204:207], v[28:31]
	v_mfma_f32_16x16x32_bf16 v[20:23], v[220:223], v[204:207], v[20:23]
	s_waitcnt lgkmcnt(0)
	s_waitcnt vmcnt(4)
	s_barrier
	s_mov_b32 s7, 2

.LBB0_279:
	global_load_dwordx4 v[128:131], v141, s[54:55]
	s_waitcnt vmcnt(0)
	v_add_f32_e32 v124, v124, v128
	v_mul_f32_e64 v128, |v124|, s48
	v_exp_f32_e32 v128, v128
	v_max_f32_e64 v124, -v124, 0
	v_add_f32_e32 v128, 1.0, v128
	v_log_f32_e32 v128, v128
	s_nop 0
	v_mul_f32_e32 v134, 0x3f317217, v128
	v_fma_f32 v134, v128, s49, -v134
	v_fmac_f32_e32 v134, 0x3377d1cf, v128
	v_fmac_f32_e32 v134, 0x3f317217, v128
	v_add_f32_e32 v124, v124, v134
	v_sub_f32_e32 v124, -0.5, v124
	v_mul_f32_e32 v124, 0x3fb8aa3b, v124
	v_exp_f32_e32 v128, v124
	s_nop 0
	v_cmp_ngt_f32_e32 vcc, s12, v128
	s_and_saveexec_b64 s[4:5], vcc
	s_xor_b64 s[4:5], exec, s[4:5]
	v_mul_f32_e32 v124, 0xbfb8aa3b, v128
	v_exp_f32_e32 v124, v124
	s_nop 0
	v_sub_f32_e32 v124, 1.0, v124
	s_andn2_saveexec_b64 s[4:5], s[4:5]
	v_fmamk_f32 v124, v128, 0xbd2aaaab, v160
	v_fma_f32 v124, -v128, v124, 0.5
	v_fma_f32 v124, -v128, v124, 1.0
	v_mul_f32_e32 v124, v128, v124
	s_or_b64 exec, exec, s[4:5]
	v_add_f32_e32 v125, v125, v129
	v_mul_f32_e64 v128, |v125|, s48
	v_exp_f32_e32 v128, v128
	v_max_f32_e64 v125, -v125, 0
	v_add_f32_e32 v128, 1.0, v128
	v_log_f32_e32 v128, v128
	s_nop 0
	v_mul_f32_e32 v129, 0x3f317217, v128
	v_fma_f32 v129, v128, s49, -v129
	v_fmac_f32_e32 v129, 0x3377d1cf, v128
	v_fmac_f32_e32 v129, 0x3f317217, v128
	v_add_f32_e32 v125, v125, v129
	v_sub_f32_e32 v125, -0.5, v125
	v_mul_f32_e32 v125, 0x3fb8aa3b, v125
	v_exp_f32_e32 v128, v125
	s_nop 0
	v_cmp_ngt_f32_e32 vcc, s12, v128
	s_and_saveexec_b64 s[4:5], vcc
	s_xor_b64 s[4:5], exec, s[4:5]
	v_mul_f32_e32 v125, 0xbfb8aa3b, v128
	v_exp_f32_e32 v125, v125
	s_nop 0
	v_sub_f32_e32 v125, 1.0, v125
	s_andn2_saveexec_b64 s[4:5], s[4:5]
	v_fmamk_f32 v125, v128, 0xbd2aaaab, v160
	v_fma_f32 v125, -v128, v125, 0.5
	v_fma_f32 v125, -v128, v125, 1.0
	v_mul_f32_e32 v125, v128, v125
	s_or_b64 exec, exec, s[4:5]
	v_add_f32_e32 v126, v126, v130
	v_mul_f32_e64 v128, |v126|, s48
	v_exp_f32_e32 v128, v128
	v_max_f32_e64 v126, -v126, 0
	v_add_f32_e32 v128, 1.0, v128
	v_log_f32_e32 v128, v128
	s_nop 0
	v_mul_f32_e32 v129, 0x3f317217, v128
	v_fma_f32 v129, v128, s49, -v129
	v_fmac_f32_e32 v129, 0x3377d1cf, v128
	v_fmac_f32_e32 v129, 0x3f317217, v128
	v_add_f32_e32 v126, v126, v129
	v_sub_f32_e32 v126, -0.5, v126
	v_mul_f32_e32 v126, 0x3fb8aa3b, v126
	v_exp_f32_e32 v128, v126
	s_nop 0
	v_cmp_ngt_f32_e32 vcc, s12, v128
	s_and_saveexec_b64 s[4:5], vcc
	s_xor_b64 s[4:5], exec, s[4:5]
	v_mul_f32_e32 v126, 0xbfb8aa3b, v128
	v_exp_f32_e32 v126, v126
	s_nop 0
	v_sub_f32_e32 v126, 1.0, v126
	s_andn2_saveexec_b64 s[4:5], s[4:5]
	v_fmamk_f32 v126, v128, 0xbd2aaaab, v160
	v_fma_f32 v126, -v128, v126, 0.5
	v_fma_f32 v126, -v128, v126, 1.0
	v_mul_f32_e32 v126, v128, v126
	s_or_b64 exec, exec, s[4:5]
	v_add_f32_e32 v127, v127, v131
	v_mul_f32_e64 v128, |v127|, s48
	v_exp_f32_e32 v128, v128
	v_max_f32_e64 v127, -v127, 0
	v_add_f32_e32 v128, 1.0, v128
	v_log_f32_e32 v128, v128
	s_nop 0
	v_mul_f32_e32 v129, 0x3f317217, v128
	v_fma_f32 v129, v128, s49, -v129
	v_fmac_f32_e32 v129, 0x3377d1cf, v128
	v_fmac_f32_e32 v129, 0x3f317217, v128
	v_add_f32_e32 v127, v127, v129
	v_sub_f32_e32 v127, -0.5, v127
	v_mul_f32_e32 v127, 0x3fb8aa3b, v127
	v_exp_f32_e32 v127, v127
	s_nop 0
	v_cmp_ngt_f32_e32 vcc, s12, v127
	s_and_saveexec_b64 s[4:5], vcc
	s_xor_b64 s[4:5], exec, s[4:5]
	v_mul_f32_e32 v127, 0xbfb8aa3b, v127
	v_exp_f32_e32 v127, v127
	s_nop 0
	v_sub_f32_e32 v128, 1.0, v127
	s_andn2_saveexec_b64 s[4:5], s[4:5]
	v_fmamk_f32 v128, v127, 0xbd2aaaab, v160
	v_fma_f32 v128, -v127, v128, 0.5
	v_fma_f32 v128, -v127, v128, 1.0
	v_mul_f32_e32 v128, v127, v128
	s_or_b64 exec, exec, s[4:5]
	v_cvt_pk_f16_f32 v127, v126, v128
	v_cvt_pk_f16_f32 v126, v124, v125
	v_mov_b64_e32 v[124:125], v[132:133]
	v_ashrrev_i32_e32 v139, 31, v138
	v_lshlrev_b64 v[128:129], 11, v[138:139]
	v_lshl_add_u64 v[124:125], v[124:125], 0, v[128:129]
	s_lshl_b32 s52, s61, 10
	v_lshl_add_u64 v[124:125], v[124:125], 0, s[52:53]
	v_lshlrev_b32_e32 v134, 1, v140
	v_lshl_add_u64 v[124:125], v[124:125], 0, v[134:135]
	v_add_co_u32_e32 v124, vcc, 0x15a00000, v124
	s_nop 1
	v_addc_co_u32_e32 v125, vcc, 0, v125, vcc
	global_store_dwordx2 v[124:125], v[126:127], off
	s_mov_b64 s[4:5], -1
	s_and_b64 vcc, exec, s[6:7]
	s_cbranch_vccz .LBB0_266

.LBB0_301:
	global_load_dwordx4 v[124:127], v141, s[54:55] offset:64
	s_waitcnt vmcnt(0)
	v_add_f32_e32 v120, v120, v124
	v_mul_f32_e64 v124, |v120|, s48
	v_exp_f32_e32 v124, v124
	v_max_f32_e64 v120, -v120, 0
	v_add_f32_e32 v124, 1.0, v124
	v_log_f32_e32 v124, v124
	s_nop 0
	v_mul_f32_e32 v128, 0x3f317217, v124
	v_fma_f32 v128, v124, s49, -v128
	v_fmac_f32_e32 v128, 0x3377d1cf, v124
	v_fmac_f32_e32 v128, 0x3f317217, v124
	v_add_f32_e32 v120, v120, v128
	v_sub_f32_e32 v120, -0.5, v120
	v_mul_f32_e32 v120, 0x3fb8aa3b, v120
	v_exp_f32_e32 v124, v120
	s_nop 0
	v_cmp_ngt_f32_e32 vcc, s12, v124
	s_and_saveexec_b64 s[4:5], vcc
	s_xor_b64 s[4:5], exec, s[4:5]
	v_mul_f32_e32 v120, 0xbfb8aa3b, v124
	v_exp_f32_e32 v120, v120
	s_nop 0
	v_sub_f32_e32 v120, 1.0, v120
	s_andn2_saveexec_b64 s[4:5], s[4:5]
	v_fmamk_f32 v120, v124, 0xbd2aaaab, v160
	v_fma_f32 v120, -v124, v120, 0.5
	v_fma_f32 v120, -v124, v120, 1.0
	v_mul_f32_e32 v120, v124, v120
	s_or_b64 exec, exec, s[4:5]
	v_add_f32_e32 v121, v121, v125
	v_mul_f32_e64 v124, |v121|, s48
	v_exp_f32_e32 v124, v124
	v_max_f32_e64 v121, -v121, 0
	v_add_f32_e32 v124, 1.0, v124
	v_log_f32_e32 v124, v124
	s_nop 0
	v_mul_f32_e32 v125, 0x3f317217, v124
	v_fma_f32 v125, v124, s49, -v125
	v_fmac_f32_e32 v125, 0x3377d1cf, v124
	v_fmac_f32_e32 v125, 0x3f317217, v124
	v_add_f32_e32 v121, v121, v125
	v_sub_f32_e32 v121, -0.5, v121
	v_mul_f32_e32 v121, 0x3fb8aa3b, v121
	v_exp_f32_e32 v124, v121
	s_nop 0
	v_cmp_ngt_f32_e32 vcc, s12, v124
	s_and_saveexec_b64 s[4:5], vcc
	s_xor_b64 s[4:5], exec, s[4:5]
	v_mul_f32_e32 v121, 0xbfb8aa3b, v124
	v_exp_f32_e32 v121, v121
	s_nop 0
	v_sub_f32_e32 v121, 1.0, v121
	s_andn2_saveexec_b64 s[4:5], s[4:5]
	v_fmamk_f32 v121, v124, 0xbd2aaaab, v160
	v_fma_f32 v121, -v124, v121, 0.5
	v_fma_f32 v121, -v124, v121, 1.0
	v_mul_f32_e32 v121, v124, v121
	s_or_b64 exec, exec, s[4:5]
	v_add_f32_e32 v122, v122, v126
	v_mul_f32_e64 v124, |v122|, s48
	v_exp_f32_e32 v124, v124
	v_max_f32_e64 v122, -v122, 0
	v_add_f32_e32 v124, 1.0, v124
	v_log_f32_e32 v124, v124
	s_nop 0
	v_mul_f32_e32 v125, 0x3f317217, v124
	v_fma_f32 v125, v124, s49, -v125
	v_fmac_f32_e32 v125, 0x3377d1cf, v124
	v_fmac_f32_e32 v125, 0x3f317217, v124
	v_add_f32_e32 v122, v122, v125
	v_sub_f32_e32 v122, -0.5, v122
	v_mul_f32_e32 v122, 0x3fb8aa3b, v122
	v_exp_f32_e32 v124, v122
	s_nop 0
	v_cmp_ngt_f32_e32 vcc, s12, v124
	s_and_saveexec_b64 s[4:5], vcc
	s_xor_b64 s[4:5], exec, s[4:5]
	v_mul_f32_e32 v122, 0xbfb8aa3b, v124
	v_exp_f32_e32 v122, v122
	s_nop 0
	v_sub_f32_e32 v122, 1.0, v122
	s_andn2_saveexec_b64 s[4:5], s[4:5]
	v_fmamk_f32 v122, v124, 0xbd2aaaab, v160
	v_fma_f32 v122, -v124, v122, 0.5
	v_fma_f32 v122, -v124, v122, 1.0
	v_mul_f32_e32 v122, v124, v122
	s_or_b64 exec, exec, s[4:5]
	v_add_f32_e32 v123, v123, v127
	v_mul_f32_e64 v124, |v123|, s48
	v_exp_f32_e32 v124, v124
	v_max_f32_e64 v123, -v123, 0
	v_add_f32_e32 v124, 1.0, v124
	v_log_f32_e32 v124, v124
	s_nop 0
	v_mul_f32_e32 v125, 0x3f317217, v124
	v_fma_f32 v125, v124, s49, -v125
	v_fmac_f32_e32 v125, 0x3377d1cf, v124
	v_fmac_f32_e32 v125, 0x3f317217, v124
	v_add_f32_e32 v123, v123, v125
	v_sub_f32_e32 v123, -0.5, v123
	v_mul_f32_e32 v123, 0x3fb8aa3b, v123
	v_exp_f32_e32 v123, v123
	s_nop 0
	v_cmp_ngt_f32_e32 vcc, s12, v123
	s_and_saveexec_b64 s[4:5], vcc
	s_xor_b64 s[4:5], exec, s[4:5]
	v_mul_f32_e32 v123, 0xbfb8aa3b, v123
	v_exp_f32_e32 v123, v123
	s_nop 0
	v_sub_f32_e32 v124, 1.0, v123
	s_andn2_saveexec_b64 s[4:5], s[4:5]
	v_fmamk_f32 v124, v123, 0xbd2aaaab, v160
	v_fma_f32 v124, -v123, v124, 0.5
	v_fma_f32 v124, -v123, v124, 1.0
	v_mul_f32_e32 v124, v123, v124
	s_or_b64 exec, exec, s[4:5]
	v_cvt_pk_f16_f32 v123, v122, v124
	v_cvt_pk_f16_f32 v122, v120, v121
	v_mov_b64_e32 v[120:121], v[132:133]
	v_ashrrev_i32_e32 v139, 31, v138
	v_lshlrev_b64 v[124:125], 11, v[138:139]
	v_lshl_add_u64 v[120:121], v[120:121], 0, v[124:125]
	s_lshl_b32 s52, s61, 10
	v_lshl_add_u64 v[120:121], v[120:121], 0, s[52:53]
	v_lshlrev_b32_e32 v134, 1, v140
	v_lshl_add_u64 v[120:121], v[120:121], 0, v[134:135]
	v_add_co_u32_e32 v120, vcc, 0x15a00000, v120
	s_nop 1
	v_addc_co_u32_e32 v121, vcc, 0, v121, vcc
	global_store_dwordx2 v[120:121], v[122:123], off offset:32
	s_mov_b64 s[4:5], -1
	s_and_b64 vcc, exec, s[6:7]
	s_cbranch_vccz .LBB0_268

.LBB0_323:
	global_load_dwordx4 v[120:123], v141, s[54:55] offset:128
	s_waitcnt vmcnt(0)
	v_add_f32_e32 v116, v116, v120
	v_mul_f32_e64 v120, |v116|, s48
	v_exp_f32_e32 v120, v120
	v_max_f32_e64 v116, -v116, 0
	v_add_f32_e32 v120, 1.0, v120
	v_log_f32_e32 v120, v120
	s_nop 0
	v_mul_f32_e32 v124, 0x3f317217, v120
	v_fma_f32 v124, v120, s49, -v124
	v_fmac_f32_e32 v124, 0x3377d1cf, v120
	v_fmac_f32_e32 v124, 0x3f317217, v120
	v_add_f32_e32 v116, v116, v124
	v_sub_f32_e32 v116, -0.5, v116
	v_mul_f32_e32 v116, 0x3fb8aa3b, v116
	v_exp_f32_e32 v120, v116
	s_nop 0
	v_cmp_ngt_f32_e32 vcc, s12, v120
	s_and_saveexec_b64 s[4:5], vcc
	s_xor_b64 s[4:5], exec, s[4:5]
	v_mul_f32_e32 v116, 0xbfb8aa3b, v120
	v_exp_f32_e32 v116, v116
	s_nop 0
	v_sub_f32_e32 v116, 1.0, v116
	s_andn2_saveexec_b64 s[4:5], s[4:5]
	v_fmamk_f32 v116, v120, 0xbd2aaaab, v160
	v_fma_f32 v116, -v120, v116, 0.5
	v_fma_f32 v116, -v120, v116, 1.0
	v_mul_f32_e32 v116, v120, v116
	s_or_b64 exec, exec, s[4:5]
	v_add_f32_e32 v117, v117, v121
	v_mul_f32_e64 v120, |v117|, s48
	v_exp_f32_e32 v120, v120
	v_max_f32_e64 v117, -v117, 0
	v_add_f32_e32 v120, 1.0, v120
	v_log_f32_e32 v120, v120
	s_nop 0
	v_mul_f32_e32 v121, 0x3f317217, v120
	v_fma_f32 v121, v120, s49, -v121
	v_fmac_f32_e32 v121, 0x3377d1cf, v120
	v_fmac_f32_e32 v121, 0x3f317217, v120
	v_add_f32_e32 v117, v117, v121
	v_sub_f32_e32 v117, -0.5, v117
	v_mul_f32_e32 v117, 0x3fb8aa3b, v117
	v_exp_f32_e32 v120, v117
	s_nop 0
	v_cmp_ngt_f32_e32 vcc, s12, v120
	s_and_saveexec_b64 s[4:5], vcc
	s_xor_b64 s[4:5], exec, s[4:5]
	v_mul_f32_e32 v117, 0xbfb8aa3b, v120
	v_exp_f32_e32 v117, v117
	s_nop 0
	v_sub_f32_e32 v117, 1.0, v117
	s_andn2_saveexec_b64 s[4:5], s[4:5]
	v_fmamk_f32 v117, v120, 0xbd2aaaab, v160
	v_fma_f32 v117, -v120, v117, 0.5
	v_fma_f32 v117, -v120, v117, 1.0
	v_mul_f32_e32 v117, v120, v117
	s_or_b64 exec, exec, s[4:5]
	v_add_f32_e32 v118, v118, v122
	v_mul_f32_e64 v120, |v118|, s48
	v_exp_f32_e32 v120, v120
	v_max_f32_e64 v118, -v118, 0
	v_add_f32_e32 v120, 1.0, v120
	v_log_f32_e32 v120, v120
	s_nop 0
	v_mul_f32_e32 v121, 0x3f317217, v120
	v_fma_f32 v121, v120, s49, -v121
	v_fmac_f32_e32 v121, 0x3377d1cf, v120
	v_fmac_f32_e32 v121, 0x3f317217, v120
	v_add_f32_e32 v118, v118, v121
	v_sub_f32_e32 v118, -0.5, v118
	v_mul_f32_e32 v118, 0x3fb8aa3b, v118
	v_exp_f32_e32 v120, v118
	s_nop 0
	v_cmp_ngt_f32_e32 vcc, s12, v120
	s_and_saveexec_b64 s[4:5], vcc
	s_xor_b64 s[4:5], exec, s[4:5]
	v_mul_f32_e32 v118, 0xbfb8aa3b, v120
	v_exp_f32_e32 v118, v118
	s_nop 0
	v_sub_f32_e32 v118, 1.0, v118
	s_andn2_saveexec_b64 s[4:5], s[4:5]
	v_fmamk_f32 v118, v120, 0xbd2aaaab, v160
	v_fma_f32 v118, -v120, v118, 0.5
	v_fma_f32 v118, -v120, v118, 1.0
	v_mul_f32_e32 v118, v120, v118
	s_or_b64 exec, exec, s[4:5]
	v_add_f32_e32 v119, v119, v123
	v_mul_f32_e64 v120, |v119|, s48
	v_exp_f32_e32 v120, v120
	v_max_f32_e64 v119, -v119, 0
	v_add_f32_e32 v120, 1.0, v120
	v_log_f32_e32 v120, v120
	s_nop 0
	v_mul_f32_e32 v121, 0x3f317217, v120
	v_fma_f32 v121, v120, s49, -v121
	v_fmac_f32_e32 v121, 0x3377d1cf, v120
	v_fmac_f32_e32 v121, 0x3f317217, v120
	v_add_f32_e32 v119, v119, v121
	v_sub_f32_e32 v119, -0.5, v119
	v_mul_f32_e32 v119, 0x3fb8aa3b, v119
	v_exp_f32_e32 v119, v119
	s_nop 0
	v_cmp_ngt_f32_e32 vcc, s12, v119
	s_and_saveexec_b64 s[4:5], vcc
	s_xor_b64 s[4:5], exec, s[4:5]
	v_mul_f32_e32 v119, 0xbfb8aa3b, v119
	v_exp_f32_e32 v119, v119
	s_nop 0
	v_sub_f32_e32 v120, 1.0, v119
	s_andn2_saveexec_b64 s[4:5], s[4:5]
	v_fmamk_f32 v120, v119, 0xbd2aaaab, v160
	v_fma_f32 v120, -v119, v120, 0.5
	v_fma_f32 v120, -v119, v120, 1.0
	v_mul_f32_e32 v120, v119, v120
	s_or_b64 exec, exec, s[4:5]
	v_cvt_pk_f16_f32 v119, v118, v120
	v_cvt_pk_f16_f32 v118, v116, v117
	v_mov_b64_e32 v[116:117], v[132:133]
	v_ashrrev_i32_e32 v139, 31, v138
	v_lshlrev_b64 v[120:121], 11, v[138:139]
	v_lshl_add_u64 v[116:117], v[116:117], 0, v[120:121]
	s_lshl_b32 s52, s61, 10
	v_lshl_add_u64 v[116:117], v[116:117], 0, s[52:53]
	v_lshlrev_b32_e32 v134, 1, v140
	v_lshl_add_u64 v[116:117], v[116:117], 0, v[134:135]
	v_add_co_u32_e32 v116, vcc, 0x15a00000, v116
	s_nop 1
	v_addc_co_u32_e32 v117, vcc, 0, v117, vcc
	global_store_dwordx2 v[116:117], v[118:119], off offset:64
	s_mov_b64 s[4:5], -1
	s_and_b64 vcc, exec, s[6:7]
	s_cbranch_vccz .LBB0_270

.LBB0_345:
	global_load_dwordx4 v[116:119], v141, s[54:55] offset:192
	s_waitcnt vmcnt(0)
	v_add_f32_e32 v112, v112, v116
	v_mul_f32_e64 v116, |v112|, s48
	v_exp_f32_e32 v116, v116
	v_max_f32_e64 v112, -v112, 0
	v_add_f32_e32 v116, 1.0, v116
	v_log_f32_e32 v116, v116
	s_nop 0
	v_mul_f32_e32 v120, 0x3f317217, v116
	v_fma_f32 v120, v116, s49, -v120
	v_fmac_f32_e32 v120, 0x3377d1cf, v116
	v_fmac_f32_e32 v120, 0x3f317217, v116
	v_add_f32_e32 v112, v112, v120
	v_sub_f32_e32 v112, -0.5, v112
	v_mul_f32_e32 v112, 0x3fb8aa3b, v112
	v_exp_f32_e32 v116, v112
	s_nop 0
	v_cmp_ngt_f32_e32 vcc, s12, v116
	s_and_saveexec_b64 s[4:5], vcc
	s_xor_b64 s[4:5], exec, s[4:5]
	v_mul_f32_e32 v112, 0xbfb8aa3b, v116
	v_exp_f32_e32 v112, v112
	s_nop 0
	v_sub_f32_e32 v112, 1.0, v112
	s_andn2_saveexec_b64 s[4:5], s[4:5]
	v_fmamk_f32 v112, v116, 0xbd2aaaab, v160
	v_fma_f32 v112, -v116, v112, 0.5
	v_fma_f32 v112, -v116, v112, 1.0
	v_mul_f32_e32 v112, v116, v112
	s_or_b64 exec, exec, s[4:5]
	v_add_f32_e32 v113, v113, v117
	v_mul_f32_e64 v116, |v113|, s48
	v_exp_f32_e32 v116, v116
	v_max_f32_e64 v113, -v113, 0
	v_add_f32_e32 v116, 1.0, v116
	v_log_f32_e32 v116, v116
	s_nop 0
	v_mul_f32_e32 v117, 0x3f317217, v116
	v_fma_f32 v117, v116, s49, -v117
	v_fmac_f32_e32 v117, 0x3377d1cf, v116
	v_fmac_f32_e32 v117, 0x3f317217, v116
	v_add_f32_e32 v113, v113, v117
	v_sub_f32_e32 v113, -0.5, v113
	v_mul_f32_e32 v113, 0x3fb8aa3b, v113
	v_exp_f32_e32 v116, v113
	s_nop 0
	v_cmp_ngt_f32_e32 vcc, s12, v116
	s_and_saveexec_b64 s[4:5], vcc
	s_xor_b64 s[4:5], exec, s[4:5]
	v_mul_f32_e32 v113, 0xbfb8aa3b, v116
	v_exp_f32_e32 v113, v113
	s_nop 0
	v_sub_f32_e32 v113, 1.0, v113
	s_andn2_saveexec_b64 s[4:5], s[4:5]
	v_fmamk_f32 v113, v116, 0xbd2aaaab, v160
	v_fma_f32 v113, -v116, v113, 0.5
	v_fma_f32 v113, -v116, v113, 1.0
	v_mul_f32_e32 v113, v116, v113
	s_or_b64 exec, exec, s[4:5]
	v_add_f32_e32 v114, v114, v118
	v_mul_f32_e64 v116, |v114|, s48
	v_exp_f32_e32 v116, v116
	v_max_f32_e64 v114, -v114, 0
	v_add_f32_e32 v116, 1.0, v116
	v_log_f32_e32 v116, v116
	s_nop 0
	v_mul_f32_e32 v117, 0x3f317217, v116
	v_fma_f32 v117, v116, s49, -v117
	v_fmac_f32_e32 v117, 0x3377d1cf, v116
	v_fmac_f32_e32 v117, 0x3f317217, v116
	v_add_f32_e32 v114, v114, v117
	v_sub_f32_e32 v114, -0.5, v114
	v_mul_f32_e32 v114, 0x3fb8aa3b, v114
	v_exp_f32_e32 v116, v114
	s_nop 0
	v_cmp_ngt_f32_e32 vcc, s12, v116
	s_and_saveexec_b64 s[4:5], vcc
	s_xor_b64 s[4:5], exec, s[4:5]
	v_mul_f32_e32 v114, 0xbfb8aa3b, v116
	v_exp_f32_e32 v114, v114
	s_nop 0
	v_sub_f32_e32 v114, 1.0, v114
	s_andn2_saveexec_b64 s[4:5], s[4:5]
	v_fmamk_f32 v114, v116, 0xbd2aaaab, v160
	v_fma_f32 v114, -v116, v114, 0.5
	v_fma_f32 v114, -v116, v114, 1.0
	v_mul_f32_e32 v114, v116, v114
	s_or_b64 exec, exec, s[4:5]
	v_add_f32_e32 v115, v115, v119
	v_mul_f32_e64 v116, |v115|, s48
	v_exp_f32_e32 v116, v116
	v_max_f32_e64 v115, -v115, 0
	v_add_f32_e32 v116, 1.0, v116
	v_log_f32_e32 v116, v116
	s_nop 0
	v_mul_f32_e32 v117, 0x3f317217, v116
	v_fma_f32 v117, v116, s49, -v117
	v_fmac_f32_e32 v117, 0x3377d1cf, v116
	v_fmac_f32_e32 v117, 0x3f317217, v116
	v_add_f32_e32 v115, v115, v117
	v_sub_f32_e32 v115, -0.5, v115
	v_mul_f32_e32 v115, 0x3fb8aa3b, v115
	v_exp_f32_e32 v115, v115
	s_nop 0
	v_cmp_ngt_f32_e32 vcc, s12, v115
	s_and_saveexec_b64 s[4:5], vcc
	s_xor_b64 s[4:5], exec, s[4:5]
	v_mul_f32_e32 v115, 0xbfb8aa3b, v115
	v_exp_f32_e32 v115, v115
	s_nop 0
	v_sub_f32_e32 v116, 1.0, v115
	s_andn2_saveexec_b64 s[4:5], s[4:5]
	v_fmamk_f32 v116, v115, 0xbd2aaaab, v160
	v_fma_f32 v116, -v115, v116, 0.5
	v_fma_f32 v116, -v115, v116, 1.0
	v_mul_f32_e32 v116, v115, v116
	s_or_b64 exec, exec, s[4:5]
	v_cvt_pk_f16_f32 v115, v114, v116
	v_cvt_pk_f16_f32 v114, v112, v113
	v_mov_b64_e32 v[112:113], v[132:133]
	v_ashrrev_i32_e32 v139, 31, v138
	v_lshlrev_b64 v[116:117], 11, v[138:139]
	v_lshl_add_u64 v[112:113], v[112:113], 0, v[116:117]
	s_lshl_b32 s52, s61, 10
	v_lshl_add_u64 v[112:113], v[112:113], 0, s[52:53]
	v_lshlrev_b32_e32 v134, 1, v140
	v_lshl_add_u64 v[112:113], v[112:113], 0, v[134:135]
	v_add_co_u32_e32 v112, vcc, 0x15a00000, v112
	s_nop 1
	v_addc_co_u32_e32 v113, vcc, 0, v113, vcc
	global_store_dwordx2 v[112:113], v[114:115], off offset:96
	s_mov_b64 s[4:5], -1
	s_and_b64 vcc, exec, s[6:7]
	s_cbranch_vccz .LBB0_272

.LBB0_367:
	global_load_dwordx4 v[112:115], v141, s[54:55] offset:256
	s_waitcnt vmcnt(0)
	v_add_f32_e32 v108, v108, v112
	v_mul_f32_e64 v112, |v108|, s48
	v_exp_f32_e32 v112, v112
	v_max_f32_e64 v108, -v108, 0
	v_add_f32_e32 v112, 1.0, v112
	v_log_f32_e32 v112, v112
	s_nop 0
	v_mul_f32_e32 v116, 0x3f317217, v112
	v_fma_f32 v116, v112, s49, -v116
	v_fmac_f32_e32 v116, 0x3377d1cf, v112
	v_fmac_f32_e32 v116, 0x3f317217, v112
	v_add_f32_e32 v108, v108, v116
	v_sub_f32_e32 v108, -0.5, v108
	v_mul_f32_e32 v108, 0x3fb8aa3b, v108
	v_exp_f32_e32 v112, v108
	s_nop 0
	v_cmp_ngt_f32_e32 vcc, s12, v112
	s_and_saveexec_b64 s[4:5], vcc
	s_xor_b64 s[4:5], exec, s[4:5]
	v_mul_f32_e32 v108, 0xbfb8aa3b, v112
	v_exp_f32_e32 v108, v108
	s_nop 0
	v_sub_f32_e32 v108, 1.0, v108
	s_andn2_saveexec_b64 s[4:5], s[4:5]
	v_fmamk_f32 v108, v112, 0xbd2aaaab, v160
	v_fma_f32 v108, -v112, v108, 0.5
	v_fma_f32 v108, -v112, v108, 1.0
	v_mul_f32_e32 v108, v112, v108
	s_or_b64 exec, exec, s[4:5]
	v_add_f32_e32 v109, v109, v113
	v_mul_f32_e64 v112, |v109|, s48
	v_exp_f32_e32 v112, v112
	v_max_f32_e64 v109, -v109, 0
	v_add_f32_e32 v112, 1.0, v112
	v_log_f32_e32 v112, v112
	s_nop 0
	v_mul_f32_e32 v113, 0x3f317217, v112
	v_fma_f32 v113, v112, s49, -v113
	v_fmac_f32_e32 v113, 0x3377d1cf, v112
	v_fmac_f32_e32 v113, 0x3f317217, v112
	v_add_f32_e32 v109, v109, v113
	v_sub_f32_e32 v109, -0.5, v109
	v_mul_f32_e32 v109, 0x3fb8aa3b, v109
	v_exp_f32_e32 v112, v109
	s_nop 0
	v_cmp_ngt_f32_e32 vcc, s12, v112
	s_and_saveexec_b64 s[4:5], vcc
	s_xor_b64 s[4:5], exec, s[4:5]
	v_mul_f32_e32 v109, 0xbfb8aa3b, v112
	v_exp_f32_e32 v109, v109
	s_nop 0
	v_sub_f32_e32 v109, 1.0, v109
	s_andn2_saveexec_b64 s[4:5], s[4:5]
	v_fmamk_f32 v109, v112, 0xbd2aaaab, v160
	v_fma_f32 v109, -v112, v109, 0.5
	v_fma_f32 v109, -v112, v109, 1.0
	v_mul_f32_e32 v109, v112, v109
	s_or_b64 exec, exec, s[4:5]
	v_add_f32_e32 v110, v110, v114
	v_mul_f32_e64 v112, |v110|, s48
	v_exp_f32_e32 v112, v112
	v_max_f32_e64 v110, -v110, 0
	v_add_f32_e32 v112, 1.0, v112
	v_log_f32_e32 v112, v112
	s_nop 0
	v_mul_f32_e32 v113, 0x3f317217, v112
	v_fma_f32 v113, v112, s49, -v113
	v_fmac_f32_e32 v113, 0x3377d1cf, v112
	v_fmac_f32_e32 v113, 0x3f317217, v112
	v_add_f32_e32 v110, v110, v113
	v_sub_f32_e32 v110, -0.5, v110
	v_mul_f32_e32 v110, 0x3fb8aa3b, v110
	v_exp_f32_e32 v112, v110
	s_nop 0
	v_cmp_ngt_f32_e32 vcc, s12, v112
	s_and_saveexec_b64 s[4:5], vcc
	s_xor_b64 s[4:5], exec, s[4:5]
	v_mul_f32_e32 v110, 0xbfb8aa3b, v112
	v_exp_f32_e32 v110, v110
	s_nop 0
	v_sub_f32_e32 v110, 1.0, v110
	s_andn2_saveexec_b64 s[4:5], s[4:5]
	v_fmamk_f32 v110, v112, 0xbd2aaaab, v160
	v_fma_f32 v110, -v112, v110, 0.5
	v_fma_f32 v110, -v112, v110, 1.0
	v_mul_f32_e32 v110, v112, v110
	s_or_b64 exec, exec, s[4:5]
	v_add_f32_e32 v111, v111, v115
	v_mul_f32_e64 v112, |v111|, s48
	v_exp_f32_e32 v112, v112
	v_max_f32_e64 v111, -v111, 0
	v_add_f32_e32 v112, 1.0, v112
	v_log_f32_e32 v112, v112
	s_nop 0
	v_mul_f32_e32 v113, 0x3f317217, v112
	v_fma_f32 v113, v112, s49, -v113
	v_fmac_f32_e32 v113, 0x3377d1cf, v112
	v_fmac_f32_e32 v113, 0x3f317217, v112
	v_add_f32_e32 v111, v111, v113
	v_sub_f32_e32 v111, -0.5, v111
	v_mul_f32_e32 v111, 0x3fb8aa3b, v111
	v_exp_f32_e32 v111, v111
	s_nop 0
	v_cmp_ngt_f32_e32 vcc, s12, v111
	s_and_saveexec_b64 s[4:5], vcc
	s_xor_b64 s[4:5], exec, s[4:5]
	v_mul_f32_e32 v111, 0xbfb8aa3b, v111
	v_exp_f32_e32 v111, v111
	s_nop 0
	v_sub_f32_e32 v112, 1.0, v111
	s_andn2_saveexec_b64 s[4:5], s[4:5]
	v_fmamk_f32 v112, v111, 0xbd2aaaab, v160
	v_fma_f32 v112, -v111, v112, 0.5
	v_fma_f32 v112, -v111, v112, 1.0
	v_mul_f32_e32 v112, v111, v112
	s_or_b64 exec, exec, s[4:5]
	v_cvt_pk_f16_f32 v111, v110, v112
	v_cvt_pk_f16_f32 v110, v108, v109
	v_mov_b64_e32 v[108:109], v[132:133]
	v_ashrrev_i32_e32 v139, 31, v138
	v_lshlrev_b64 v[112:113], 11, v[138:139]
	v_lshl_add_u64 v[108:109], v[108:109], 0, v[112:113]
	s_lshl_b32 s52, s61, 10
	v_lshl_add_u64 v[108:109], v[108:109], 0, s[52:53]
	v_lshlrev_b32_e32 v134, 1, v140
	v_lshl_add_u64 v[108:109], v[108:109], 0, v[134:135]
	v_add_co_u32_e32 v108, vcc, 0x15a00000, v108
	s_nop 1
	v_addc_co_u32_e32 v109, vcc, 0, v109, vcc
	global_store_dwordx2 v[108:109], v[110:111], off offset:128
	s_mov_b64 s[4:5], -1
	s_and_b64 vcc, exec, s[6:7]
	s_cbranch_vccz .LBB0_274

.LBB0_389:
	global_load_dwordx4 v[108:111], v141, s[54:55] offset:320
	s_waitcnt vmcnt(0)
	v_add_f32_e32 v104, v104, v108
	v_mul_f32_e64 v108, |v104|, s48
	v_exp_f32_e32 v108, v108
	v_max_f32_e64 v104, -v104, 0
	v_add_f32_e32 v108, 1.0, v108
	v_log_f32_e32 v108, v108
	s_nop 0
	v_mul_f32_e32 v112, 0x3f317217, v108
	v_fma_f32 v112, v108, s49, -v112
	v_fmac_f32_e32 v112, 0x3377d1cf, v108
	v_fmac_f32_e32 v112, 0x3f317217, v108
	v_add_f32_e32 v104, v104, v112
	v_sub_f32_e32 v104, -0.5, v104
	v_mul_f32_e32 v104, 0x3fb8aa3b, v104
	v_exp_f32_e32 v108, v104
	s_nop 0
	v_cmp_ngt_f32_e32 vcc, s12, v108
	s_and_saveexec_b64 s[4:5], vcc
	s_xor_b64 s[4:5], exec, s[4:5]
	v_mul_f32_e32 v104, 0xbfb8aa3b, v108
	v_exp_f32_e32 v104, v104
	s_nop 0
	v_sub_f32_e32 v104, 1.0, v104
	s_andn2_saveexec_b64 s[4:5], s[4:5]
	v_fmamk_f32 v104, v108, 0xbd2aaaab, v160
	v_fma_f32 v104, -v108, v104, 0.5
	v_fma_f32 v104, -v108, v104, 1.0
	v_mul_f32_e32 v104, v108, v104
	s_or_b64 exec, exec, s[4:5]
	v_add_f32_e32 v105, v105, v109
	v_mul_f32_e64 v108, |v105|, s48
	v_exp_f32_e32 v108, v108
	v_max_f32_e64 v105, -v105, 0
	v_add_f32_e32 v108, 1.0, v108
	v_log_f32_e32 v108, v108
	s_nop 0
	v_mul_f32_e32 v109, 0x3f317217, v108
	v_fma_f32 v109, v108, s49, -v109
	v_fmac_f32_e32 v109, 0x3377d1cf, v108
	v_fmac_f32_e32 v109, 0x3f317217, v108
	v_add_f32_e32 v105, v105, v109
	v_sub_f32_e32 v105, -0.5, v105
	v_mul_f32_e32 v105, 0x3fb8aa3b, v105
	v_exp_f32_e32 v108, v105
	s_nop 0
	v_cmp_ngt_f32_e32 vcc, s12, v108
	s_and_saveexec_b64 s[4:5], vcc
	s_xor_b64 s[4:5], exec, s[4:5]
	v_mul_f32_e32 v105, 0xbfb8aa3b, v108
	v_exp_f32_e32 v105, v105
	s_nop 0
	v_sub_f32_e32 v105, 1.0, v105
	s_andn2_saveexec_b64 s[4:5], s[4:5]
	v_fmamk_f32 v105, v108, 0xbd2aaaab, v160
	v_fma_f32 v105, -v108, v105, 0.5
	v_fma_f32 v105, -v108, v105, 1.0
	v_mul_f32_e32 v105, v108, v105
	s_or_b64 exec, exec, s[4:5]
	v_add_f32_e32 v106, v106, v110
	v_mul_f32_e64 v108, |v106|, s48
	v_exp_f32_e32 v108, v108
	v_max_f32_e64 v106, -v106, 0
	v_add_f32_e32 v108, 1.0, v108
	v_log_f32_e32 v108, v108
	s_nop 0
	v_mul_f32_e32 v109, 0x3f317217, v108
	v_fma_f32 v109, v108, s49, -v109
	v_fmac_f32_e32 v109, 0x3377d1cf, v108
	v_fmac_f32_e32 v109, 0x3f317217, v108
	v_add_f32_e32 v106, v106, v109
	v_sub_f32_e32 v106, -0.5, v106
	v_mul_f32_e32 v106, 0x3fb8aa3b, v106
	v_exp_f32_e32 v108, v106
	s_nop 0
	v_cmp_ngt_f32_e32 vcc, s12, v108
	s_and_saveexec_b64 s[4:5], vcc
	s_xor_b64 s[4:5], exec, s[4:5]
	v_mul_f32_e32 v106, 0xbfb8aa3b, v108
	v_exp_f32_e32 v106, v106
	s_nop 0
	v_sub_f32_e32 v106, 1.0, v106
	s_andn2_saveexec_b64 s[4:5], s[4:5]
	v_fmamk_f32 v106, v108, 0xbd2aaaab, v160
	v_fma_f32 v106, -v108, v106, 0.5
	v_fma_f32 v106, -v108, v106, 1.0
	v_mul_f32_e32 v106, v108, v106
	s_or_b64 exec, exec, s[4:5]
	v_add_f32_e32 v107, v107, v111
	v_mul_f32_e64 v108, |v107|, s48
	v_exp_f32_e32 v108, v108
	v_max_f32_e64 v107, -v107, 0
	v_add_f32_e32 v108, 1.0, v108
	v_log_f32_e32 v108, v108
	s_nop 0
	v_mul_f32_e32 v109, 0x3f317217, v108
	v_fma_f32 v109, v108, s49, -v109
	v_fmac_f32_e32 v109, 0x3377d1cf, v108
	v_fmac_f32_e32 v109, 0x3f317217, v108
	v_add_f32_e32 v107, v107, v109
	v_sub_f32_e32 v107, -0.5, v107
	v_mul_f32_e32 v107, 0x3fb8aa3b, v107
	v_exp_f32_e32 v107, v107
	s_nop 0
	v_cmp_ngt_f32_e32 vcc, s12, v107
	s_and_saveexec_b64 s[4:5], vcc
	s_xor_b64 s[4:5], exec, s[4:5]
	v_mul_f32_e32 v107, 0xbfb8aa3b, v107
	v_exp_f32_e32 v107, v107
	s_nop 0
	v_sub_f32_e32 v108, 1.0, v107
	s_andn2_saveexec_b64 s[4:5], s[4:5]
	v_fmamk_f32 v108, v107, 0xbd2aaaab, v160
	v_fma_f32 v108, -v107, v108, 0.5
	v_fma_f32 v108, -v107, v108, 1.0
	v_mul_f32_e32 v108, v107, v108
	s_or_b64 exec, exec, s[4:5]
	v_cvt_pk_f16_f32 v107, v106, v108
	v_cvt_pk_f16_f32 v106, v104, v105
	v_mov_b64_e32 v[104:105], v[132:133]
	v_ashrrev_i32_e32 v139, 31, v138
	v_lshlrev_b64 v[108:109], 11, v[138:139]
	v_lshl_add_u64 v[104:105], v[104:105], 0, v[108:109]
	s_lshl_b32 s52, s61, 10
	v_lshl_add_u64 v[104:105], v[104:105], 0, s[52:53]
	v_lshlrev_b32_e32 v134, 1, v140
	v_lshl_add_u64 v[104:105], v[104:105], 0, v[134:135]
	v_add_co_u32_e32 v104, vcc, 0x15a00000, v104
	s_nop 1
	v_addc_co_u32_e32 v105, vcc, 0, v105, vcc
	global_store_dwordx2 v[104:105], v[106:107], off offset:160
	s_mov_b64 s[4:5], -1
	s_and_b64 vcc, exec, s[6:7]
	s_cbranch_vccz .LBB0_276

.LBB0_411:
	global_load_dwordx4 v[104:107], v141, s[54:55] offset:384
	s_waitcnt vmcnt(0)
	v_add_f32_e32 v100, v100, v104
	v_mul_f32_e64 v104, |v100|, s48
	v_exp_f32_e32 v104, v104
	v_max_f32_e64 v100, -v100, 0
	v_add_f32_e32 v104, 1.0, v104
	v_log_f32_e32 v104, v104
	s_nop 0
	v_mul_f32_e32 v108, 0x3f317217, v104
	v_fma_f32 v108, v104, s49, -v108
	v_fmac_f32_e32 v108, 0x3377d1cf, v104
	v_fmac_f32_e32 v108, 0x3f317217, v104
	v_add_f32_e32 v100, v100, v108
	v_sub_f32_e32 v100, -0.5, v100
	v_mul_f32_e32 v100, 0x3fb8aa3b, v100
	v_exp_f32_e32 v104, v100
	s_nop 0
	v_cmp_ngt_f32_e32 vcc, s12, v104
	s_and_saveexec_b64 s[4:5], vcc
	s_xor_b64 s[4:5], exec, s[4:5]
	v_mul_f32_e32 v100, 0xbfb8aa3b, v104
	v_exp_f32_e32 v100, v100
	s_nop 0
	v_sub_f32_e32 v100, 1.0, v100
	s_andn2_saveexec_b64 s[4:5], s[4:5]
	v_fmamk_f32 v100, v104, 0xbd2aaaab, v160
	v_fma_f32 v100, -v104, v100, 0.5
	v_fma_f32 v100, -v104, v100, 1.0
	v_mul_f32_e32 v100, v104, v100
	s_or_b64 exec, exec, s[4:5]
	v_add_f32_e32 v101, v101, v105
	v_mul_f32_e64 v104, |v101|, s48
	v_exp_f32_e32 v104, v104
	v_max_f32_e64 v101, -v101, 0
	v_add_f32_e32 v104, 1.0, v104
	v_log_f32_e32 v104, v104
	s_nop 0
	v_mul_f32_e32 v105, 0x3f317217, v104
	v_fma_f32 v105, v104, s49, -v105
	v_fmac_f32_e32 v105, 0x3377d1cf, v104
	v_fmac_f32_e32 v105, 0x3f317217, v104
	v_add_f32_e32 v101, v101, v105
	v_sub_f32_e32 v101, -0.5, v101
	v_mul_f32_e32 v101, 0x3fb8aa3b, v101
	v_exp_f32_e32 v104, v101
	s_nop 0
	v_cmp_ngt_f32_e32 vcc, s12, v104
	s_and_saveexec_b64 s[4:5], vcc
	s_xor_b64 s[4:5], exec, s[4:5]
	v_mul_f32_e32 v101, 0xbfb8aa3b, v104
	v_exp_f32_e32 v101, v101
	s_nop 0
	v_sub_f32_e32 v101, 1.0, v101
	s_andn2_saveexec_b64 s[4:5], s[4:5]
	v_fmamk_f32 v101, v104, 0xbd2aaaab, v160
	v_fma_f32 v101, -v104, v101, 0.5
	v_fma_f32 v101, -v104, v101, 1.0
	v_mul_f32_e32 v101, v104, v101
	s_or_b64 exec, exec, s[4:5]
	v_add_f32_e32 v102, v102, v106
	v_mul_f32_e64 v104, |v102|, s48
	v_exp_f32_e32 v104, v104
	v_max_f32_e64 v102, -v102, 0
	v_add_f32_e32 v104, 1.0, v104
	v_log_f32_e32 v104, v104
	s_nop 0
	v_mul_f32_e32 v105, 0x3f317217, v104
	v_fma_f32 v105, v104, s49, -v105
	v_fmac_f32_e32 v105, 0x3377d1cf, v104
	v_fmac_f32_e32 v105, 0x3f317217, v104
	v_add_f32_e32 v102, v102, v105
	v_sub_f32_e32 v102, -0.5, v102
	v_mul_f32_e32 v102, 0x3fb8aa3b, v102
	v_exp_f32_e32 v104, v102
	s_nop 0
	v_cmp_ngt_f32_e32 vcc, s12, v104
	s_and_saveexec_b64 s[4:5], vcc
	s_xor_b64 s[4:5], exec, s[4:5]
	v_mul_f32_e32 v102, 0xbfb8aa3b, v104
	v_exp_f32_e32 v102, v102
	s_nop 0
	v_sub_f32_e32 v102, 1.0, v102
	s_andn2_saveexec_b64 s[4:5], s[4:5]
	v_fmamk_f32 v102, v104, 0xbd2aaaab, v160
	v_fma_f32 v102, -v104, v102, 0.5
	v_fma_f32 v102, -v104, v102, 1.0
	v_mul_f32_e32 v102, v104, v102
	s_or_b64 exec, exec, s[4:5]
	v_add_f32_e32 v103, v103, v107
	v_mul_f32_e64 v104, |v103|, s48
	v_exp_f32_e32 v104, v104
	v_max_f32_e64 v103, -v103, 0
	v_add_f32_e32 v104, 1.0, v104
	v_log_f32_e32 v104, v104
	s_nop 0
	v_mul_f32_e32 v105, 0x3f317217, v104
	v_fma_f32 v105, v104, s49, -v105
	v_fmac_f32_e32 v105, 0x3377d1cf, v104
	v_fmac_f32_e32 v105, 0x3f317217, v104
	v_add_f32_e32 v103, v103, v105
	v_sub_f32_e32 v103, -0.5, v103
	v_mul_f32_e32 v103, 0x3fb8aa3b, v103
	v_exp_f32_e32 v103, v103
	s_nop 0
	v_cmp_ngt_f32_e32 vcc, s12, v103
	s_and_saveexec_b64 s[4:5], vcc
	s_xor_b64 s[4:5], exec, s[4:5]
	v_mul_f32_e32 v103, 0xbfb8aa3b, v103
	v_exp_f32_e32 v103, v103
	s_nop 0
	v_sub_f32_e32 v104, 1.0, v103
	s_andn2_saveexec_b64 s[4:5], s[4:5]
	v_fmamk_f32 v104, v103, 0xbd2aaaab, v160
	v_fma_f32 v104, -v103, v104, 0.5
	v_fma_f32 v104, -v103, v104, 1.0
	v_mul_f32_e32 v104, v103, v104
	s_or_b64 exec, exec, s[4:5]
	v_cvt_pk_f16_f32 v103, v102, v104
	v_cvt_pk_f16_f32 v102, v100, v101
	v_mov_b64_e32 v[100:101], v[132:133]
	v_ashrrev_i32_e32 v139, 31, v138
	v_lshlrev_b64 v[104:105], 11, v[138:139]
	v_lshl_add_u64 v[100:101], v[100:101], 0, v[104:105]
	s_lshl_b32 s52, s61, 10
	v_lshl_add_u64 v[100:101], v[100:101], 0, s[52:53]
	v_lshlrev_b32_e32 v134, 1, v140
	v_lshl_add_u64 v[100:101], v[100:101], 0, v[134:135]
	v_add_co_u32_e32 v100, vcc, 0x15a00000, v100
	s_nop 1
	v_addc_co_u32_e32 v101, vcc, 0, v101, vcc
	global_store_dwordx2 v[100:101], v[102:103], off offset:192
	s_mov_b64 s[4:5], -1
	s_and_b64 vcc, exec, s[6:7]
	s_cbranch_vccz .LBB0_278

.LBB0_433:
	global_load_dwordx4 v[100:103], v141, s[54:55] offset:448
	s_waitcnt vmcnt(0)
	v_add_f32_e32 v96, v96, v100
	v_mul_f32_e64 v100, |v96|, s48
	v_exp_f32_e32 v100, v100
	v_max_f32_e64 v96, -v96, 0
	v_add_f32_e32 v100, 1.0, v100
	v_log_f32_e32 v100, v100
	s_nop 0
	v_mul_f32_e32 v104, 0x3f317217, v100
	v_fma_f32 v104, v100, s49, -v104
	v_fmac_f32_e32 v104, 0x3377d1cf, v100
	v_fmac_f32_e32 v104, 0x3f317217, v100
	v_add_f32_e32 v96, v96, v104
	v_sub_f32_e32 v96, -0.5, v96
	v_mul_f32_e32 v96, 0x3fb8aa3b, v96
	v_exp_f32_e32 v100, v96
	s_nop 0
	v_cmp_ngt_f32_e32 vcc, s12, v100
	s_and_saveexec_b64 s[4:5], vcc
	s_xor_b64 s[4:5], exec, s[4:5]
	v_mul_f32_e32 v96, 0xbfb8aa3b, v100
	v_exp_f32_e32 v96, v96
	s_nop 0
	v_sub_f32_e32 v96, 1.0, v96
	s_andn2_saveexec_b64 s[4:5], s[4:5]
	v_fmamk_f32 v96, v100, 0xbd2aaaab, v160
	v_fma_f32 v96, -v100, v96, 0.5
	v_fma_f32 v96, -v100, v96, 1.0
	v_mul_f32_e32 v96, v100, v96
	s_or_b64 exec, exec, s[4:5]
	v_add_f32_e32 v97, v97, v101
	v_mul_f32_e64 v100, |v97|, s48
	v_exp_f32_e32 v100, v100
	v_max_f32_e64 v97, -v97, 0
	v_add_f32_e32 v100, 1.0, v100
	v_log_f32_e32 v100, v100
	s_nop 0
	v_mul_f32_e32 v101, 0x3f317217, v100
	v_fma_f32 v101, v100, s49, -v101
	v_fmac_f32_e32 v101, 0x3377d1cf, v100
	v_fmac_f32_e32 v101, 0x3f317217, v100
	v_add_f32_e32 v97, v97, v101
	v_sub_f32_e32 v97, -0.5, v97
	v_mul_f32_e32 v97, 0x3fb8aa3b, v97
	v_exp_f32_e32 v100, v97
	s_nop 0
	v_cmp_ngt_f32_e32 vcc, s12, v100
	s_and_saveexec_b64 s[4:5], vcc
	s_xor_b64 s[4:5], exec, s[4:5]
	v_mul_f32_e32 v97, 0xbfb8aa3b, v100
	v_exp_f32_e32 v97, v97
	s_nop 0
	v_sub_f32_e32 v97, 1.0, v97
	s_andn2_saveexec_b64 s[4:5], s[4:5]
	v_fmamk_f32 v97, v100, 0xbd2aaaab, v160
	v_fma_f32 v97, -v100, v97, 0.5
	v_fma_f32 v97, -v100, v97, 1.0
	v_mul_f32_e32 v97, v100, v97
	s_or_b64 exec, exec, s[4:5]
	v_add_f32_e32 v98, v98, v102
	v_mul_f32_e64 v100, |v98|, s48
	v_exp_f32_e32 v100, v100
	v_max_f32_e64 v98, -v98, 0
	v_add_f32_e32 v100, 1.0, v100
	v_log_f32_e32 v100, v100
	s_nop 0
	v_mul_f32_e32 v101, 0x3f317217, v100
	v_fma_f32 v101, v100, s49, -v101
	v_fmac_f32_e32 v101, 0x3377d1cf, v100
	v_fmac_f32_e32 v101, 0x3f317217, v100
	v_add_f32_e32 v98, v98, v101
	v_sub_f32_e32 v98, -0.5, v98
	v_mul_f32_e32 v98, 0x3fb8aa3b, v98
	v_exp_f32_e32 v100, v98
	s_nop 0
	v_cmp_ngt_f32_e32 vcc, s12, v100
	s_and_saveexec_b64 s[4:5], vcc
	s_xor_b64 s[4:5], exec, s[4:5]
	v_mul_f32_e32 v98, 0xbfb8aa3b, v100
	v_exp_f32_e32 v98, v98
	s_nop 0
	v_sub_f32_e32 v98, 1.0, v98
	s_andn2_saveexec_b64 s[4:5], s[4:5]
	v_fmamk_f32 v98, v100, 0xbd2aaaab, v160
	v_fma_f32 v98, -v100, v98, 0.5
	v_fma_f32 v98, -v100, v98, 1.0
	v_mul_f32_e32 v98, v100, v98
	s_or_b64 exec, exec, s[4:5]
	v_add_f32_e32 v99, v99, v103
	v_mul_f32_e64 v100, |v99|, s48
	v_exp_f32_e32 v100, v100
	v_max_f32_e64 v99, -v99, 0
	v_add_f32_e32 v100, 1.0, v100
	v_log_f32_e32 v100, v100
	s_nop 0
	v_mul_f32_e32 v101, 0x3f317217, v100
	v_fma_f32 v101, v100, s49, -v101
	v_fmac_f32_e32 v101, 0x3377d1cf, v100
	v_fmac_f32_e32 v101, 0x3f317217, v100
	v_add_f32_e32 v99, v99, v101
	v_sub_f32_e32 v99, -0.5, v99
	v_mul_f32_e32 v99, 0x3fb8aa3b, v99
	v_exp_f32_e32 v99, v99
	s_nop 0
	v_cmp_ngt_f32_e32 vcc, s12, v99
	s_and_saveexec_b64 s[4:5], vcc
	s_xor_b64 s[4:5], exec, s[4:5]
	v_mul_f32_e32 v99, 0xbfb8aa3b, v99
	v_exp_f32_e32 v99, v99
	s_nop 0
	v_sub_f32_e32 v100, 1.0, v99
	s_andn2_saveexec_b64 s[4:5], s[4:5]
	v_fmamk_f32 v100, v99, 0xbd2aaaab, v160
	v_fma_f32 v100, -v99, v100, 0.5
	v_fma_f32 v100, -v99, v100, 1.0
	v_mul_f32_e32 v100, v99, v100
	s_or_b64 exec, exec, s[4:5]
	v_cvt_pk_f16_f32 v99, v98, v100
	v_cvt_pk_f16_f32 v98, v96, v97
	v_mov_b64_e32 v[96:97], v[132:133]
	v_ashrrev_i32_e32 v139, 31, v138
	v_lshlrev_b64 v[100:101], 11, v[138:139]
	v_lshl_add_u64 v[96:97], v[96:97], 0, v[100:101]
	s_lshl_b32 s52, s61, 10
	v_lshl_add_u64 v[96:97], v[96:97], 0, s[52:53]
	v_lshlrev_b32_e32 v134, 1, v140
	v_lshl_add_u64 v[96:97], v[96:97], 0, v[134:135]
	v_add_co_u32_e32 v96, vcc, 0x15a00000, v96
	s_nop 1
	v_addc_co_u32_e32 v97, vcc, 0, v97, vcc
	global_store_dwordx2 v[96:97], v[98:99], off offset:224

.LBB0_503:
	global_load_dwordx4 v[96:99], v141, s[54:55]
	s_waitcnt vmcnt(0)
	v_add_f32_e32 v92, v92, v96
	v_mul_f32_e64 v96, |v92|, s48
	v_exp_f32_e32 v96, v96
	v_max_f32_e64 v92, -v92, 0
	v_add_f32_e32 v96, 1.0, v96
	v_log_f32_e32 v96, v96
	s_nop 0
	v_mul_f32_e32 v101, 0x3f317217, v96
	v_fma_f32 v101, v96, s49, -v101
	v_fmac_f32_e32 v101, 0x3377d1cf, v96
	v_fmac_f32_e32 v101, 0x3f317217, v96
	v_add_f32_e32 v92, v92, v101
	v_sub_f32_e32 v92, -0.5, v92
	v_mul_f32_e32 v92, 0x3fb8aa3b, v92
	v_exp_f32_e32 v96, v92
	s_nop 0
	v_cmp_ngt_f32_e32 vcc, s12, v96
	s_and_saveexec_b64 s[6:7], vcc
	s_xor_b64 s[6:7], exec, s[6:7]
	v_mul_f32_e32 v92, 0xbfb8aa3b, v96
	v_exp_f32_e32 v92, v92
	s_nop 0
	v_sub_f32_e32 v92, 1.0, v92
	s_andn2_saveexec_b64 s[6:7], s[6:7]
	v_fmamk_f32 v92, v96, 0xbd2aaaab, v160
	v_fma_f32 v92, -v96, v92, 0.5
	v_fma_f32 v92, -v96, v92, 1.0
	v_mul_f32_e32 v92, v96, v92
	s_or_b64 exec, exec, s[6:7]
	v_add_f32_e32 v93, v93, v97
	v_mul_f32_e64 v96, |v93|, s48
	v_exp_f32_e32 v96, v96
	v_max_f32_e64 v93, -v93, 0
	v_add_f32_e32 v96, 1.0, v96
	v_log_f32_e32 v96, v96
	s_nop 0
	v_mul_f32_e32 v97, 0x3f317217, v96
	v_fma_f32 v97, v96, s49, -v97
	v_fmac_f32_e32 v97, 0x3377d1cf, v96
	v_fmac_f32_e32 v97, 0x3f317217, v96
	v_add_f32_e32 v93, v93, v97
	v_sub_f32_e32 v93, -0.5, v93
	v_mul_f32_e32 v93, 0x3fb8aa3b, v93
	v_exp_f32_e32 v96, v93
	s_nop 0
	v_cmp_ngt_f32_e32 vcc, s12, v96
	s_and_saveexec_b64 s[6:7], vcc
	s_xor_b64 s[6:7], exec, s[6:7]
	v_mul_f32_e32 v93, 0xbfb8aa3b, v96
	v_exp_f32_e32 v93, v93
	s_nop 0
	v_sub_f32_e32 v93, 1.0, v93
	s_andn2_saveexec_b64 s[6:7], s[6:7]
	v_fmamk_f32 v93, v96, 0xbd2aaaab, v160
	v_fma_f32 v93, -v96, v93, 0.5
	v_fma_f32 v93, -v96, v93, 1.0
	v_mul_f32_e32 v93, v96, v93
	s_or_b64 exec, exec, s[6:7]
	v_add_f32_e32 v94, v94, v98
	v_mul_f32_e64 v96, |v94|, s48
	v_exp_f32_e32 v96, v96
	v_max_f32_e64 v94, -v94, 0
	v_add_f32_e32 v96, 1.0, v96
	v_log_f32_e32 v96, v96
	s_nop 0
	v_mul_f32_e32 v97, 0x3f317217, v96
	v_fma_f32 v97, v96, s49, -v97
	v_fmac_f32_e32 v97, 0x3377d1cf, v96
	v_fmac_f32_e32 v97, 0x3f317217, v96
	v_add_f32_e32 v94, v94, v97
	v_sub_f32_e32 v94, -0.5, v94
	v_mul_f32_e32 v94, 0x3fb8aa3b, v94
	v_exp_f32_e32 v96, v94
	s_nop 0
	v_cmp_ngt_f32_e32 vcc, s12, v96
	s_and_saveexec_b64 s[6:7], vcc
	s_xor_b64 s[6:7], exec, s[6:7]
	v_mul_f32_e32 v94, 0xbfb8aa3b, v96
	v_exp_f32_e32 v94, v94
	s_nop 0
	v_sub_f32_e32 v94, 1.0, v94
	s_andn2_saveexec_b64 s[6:7], s[6:7]
	v_fmamk_f32 v94, v96, 0xbd2aaaab, v160
	v_fma_f32 v94, -v96, v94, 0.5
	v_fma_f32 v94, -v96, v94, 1.0
	v_mul_f32_e32 v94, v96, v94
	s_or_b64 exec, exec, s[6:7]
	v_add_f32_e32 v95, v95, v99
	v_mul_f32_e64 v96, |v95|, s48
	v_exp_f32_e32 v96, v96
	v_max_f32_e64 v95, -v95, 0
	v_add_f32_e32 v96, 1.0, v96
	v_log_f32_e32 v96, v96
	s_nop 0
	v_mul_f32_e32 v97, 0x3f317217, v96
	v_fma_f32 v97, v96, s49, -v97
	v_fmac_f32_e32 v97, 0x3377d1cf, v96
	v_fmac_f32_e32 v97, 0x3f317217, v96
	v_add_f32_e32 v95, v95, v97
	v_sub_f32_e32 v95, -0.5, v95
	v_mul_f32_e32 v95, 0x3fb8aa3b, v95
	v_exp_f32_e32 v95, v95
	s_nop 0
	v_cmp_ngt_f32_e32 vcc, s12, v95
	s_and_saveexec_b64 s[6:7], vcc
	s_xor_b64 s[6:7], exec, s[6:7]
	v_mul_f32_e32 v95, 0xbfb8aa3b, v95
	v_exp_f32_e32 v95, v95
	s_nop 0
	v_sub_f32_e32 v96, 1.0, v95
	s_andn2_saveexec_b64 s[6:7], s[6:7]
	v_fmamk_f32 v96, v95, 0xbd2aaaab, v160
	v_fma_f32 v96, -v95, v96, 0.5
	v_fma_f32 v96, -v95, v96, 1.0
	v_mul_f32_e32 v96, v95, v96
	s_or_b64 exec, exec, s[6:7]
	v_cvt_pk_f16_f32 v95, v94, v96
	v_cvt_pk_f16_f32 v94, v92, v93
	v_mov_b64_e32 v[92:93], v[132:133]
	v_ashrrev_i32_e32 v101, 31, v100
	v_lshlrev_b64 v[96:97], 11, v[100:101]
	v_lshl_add_u64 v[92:93], v[92:93], 0, v[96:97]
	s_lshl_b32 s52, s61, 10
	v_lshl_add_u64 v[92:93], v[92:93], 0, s[52:53]
	v_lshlrev_b32_e32 v134, 1, v140
	v_lshl_add_u64 v[92:93], v[92:93], 0, v[134:135]
	v_add_co_u32_e32 v92, vcc, 0x15a00000, v92
	s_nop 1
	v_addc_co_u32_e32 v93, vcc, 0, v93, vcc
	global_store_dwordx2 v[92:93], v[94:95], off
	s_and_b64 vcc, exec, s[4:5]
	s_mov_b64 s[6:7], -1
	s_cbranch_vccnz .LBB0_453

.LBB0_525:
	global_load_dwordx4 v[92:95], v141, s[54:55] offset:64
	s_waitcnt vmcnt(0)
	v_add_f32_e32 v88, v88, v92
	v_mul_f32_e64 v92, |v88|, s48
	v_exp_f32_e32 v92, v92
	v_max_f32_e64 v88, -v88, 0
	v_add_f32_e32 v92, 1.0, v92
	v_log_f32_e32 v92, v92
	s_nop 0
	v_mul_f32_e32 v96, 0x3f317217, v92
	v_fma_f32 v96, v92, s49, -v96
	v_fmac_f32_e32 v96, 0x3377d1cf, v92
	v_fmac_f32_e32 v96, 0x3f317217, v92
	v_add_f32_e32 v88, v88, v96
	v_sub_f32_e32 v88, -0.5, v88
	v_mul_f32_e32 v88, 0x3fb8aa3b, v88
	v_exp_f32_e32 v92, v88
	s_nop 0
	v_cmp_ngt_f32_e32 vcc, s12, v92
	s_and_saveexec_b64 s[6:7], vcc
	s_xor_b64 s[6:7], exec, s[6:7]
	v_mul_f32_e32 v88, 0xbfb8aa3b, v92
	v_exp_f32_e32 v88, v88
	s_nop 0
	v_sub_f32_e32 v88, 1.0, v88
	s_andn2_saveexec_b64 s[6:7], s[6:7]
	v_fmamk_f32 v88, v92, 0xbd2aaaab, v160
	v_fma_f32 v88, -v92, v88, 0.5
	v_fma_f32 v88, -v92, v88, 1.0
	v_mul_f32_e32 v88, v92, v88
	s_or_b64 exec, exec, s[6:7]
	v_add_f32_e32 v89, v89, v93
	v_mul_f32_e64 v92, |v89|, s48
	v_exp_f32_e32 v92, v92
	v_max_f32_e64 v89, -v89, 0
	v_add_f32_e32 v92, 1.0, v92
	v_log_f32_e32 v92, v92
	s_nop 0
	v_mul_f32_e32 v93, 0x3f317217, v92
	v_fma_f32 v93, v92, s49, -v93
	v_fmac_f32_e32 v93, 0x3377d1cf, v92
	v_fmac_f32_e32 v93, 0x3f317217, v92
	v_add_f32_e32 v89, v89, v93
	v_sub_f32_e32 v89, -0.5, v89
	v_mul_f32_e32 v89, 0x3fb8aa3b, v89
	v_exp_f32_e32 v92, v89
	s_nop 0
	v_cmp_ngt_f32_e32 vcc, s12, v92
	s_and_saveexec_b64 s[6:7], vcc
	s_xor_b64 s[6:7], exec, s[6:7]
	v_mul_f32_e32 v89, 0xbfb8aa3b, v92
	v_exp_f32_e32 v89, v89
	s_nop 0
	v_sub_f32_e32 v89, 1.0, v89
	s_andn2_saveexec_b64 s[6:7], s[6:7]
	v_fmamk_f32 v89, v92, 0xbd2aaaab, v160
	v_fma_f32 v89, -v92, v89, 0.5
	v_fma_f32 v89, -v92, v89, 1.0
	v_mul_f32_e32 v89, v92, v89
	s_or_b64 exec, exec, s[6:7]
	v_add_f32_e32 v90, v90, v94
	v_mul_f32_e64 v92, |v90|, s48
	v_exp_f32_e32 v92, v92
	v_max_f32_e64 v90, -v90, 0
	v_add_f32_e32 v92, 1.0, v92
	v_log_f32_e32 v92, v92
	s_nop 0
	v_mul_f32_e32 v93, 0x3f317217, v92
	v_fma_f32 v93, v92, s49, -v93
	v_fmac_f32_e32 v93, 0x3377d1cf, v92
	v_fmac_f32_e32 v93, 0x3f317217, v92
	v_add_f32_e32 v90, v90, v93
	v_sub_f32_e32 v90, -0.5, v90
	v_mul_f32_e32 v90, 0x3fb8aa3b, v90
	v_exp_f32_e32 v92, v90
	s_nop 0
	v_cmp_ngt_f32_e32 vcc, s12, v92
	s_and_saveexec_b64 s[6:7], vcc
	s_xor_b64 s[6:7], exec, s[6:7]
	v_mul_f32_e32 v90, 0xbfb8aa3b, v92
	v_exp_f32_e32 v90, v90
	s_nop 0
	v_sub_f32_e32 v90, 1.0, v90
	s_andn2_saveexec_b64 s[6:7], s[6:7]
	v_fmamk_f32 v90, v92, 0xbd2aaaab, v160
	v_fma_f32 v90, -v92, v90, 0.5
	v_fma_f32 v90, -v92, v90, 1.0
	v_mul_f32_e32 v90, v92, v90
	s_or_b64 exec, exec, s[6:7]
	v_add_f32_e32 v91, v91, v95
	v_mul_f32_e64 v92, |v91|, s48
	v_exp_f32_e32 v92, v92
	v_max_f32_e64 v91, -v91, 0
	v_add_f32_e32 v92, 1.0, v92
	v_log_f32_e32 v92, v92
	s_nop 0
	v_mul_f32_e32 v93, 0x3f317217, v92
	v_fma_f32 v93, v92, s49, -v93
	v_fmac_f32_e32 v93, 0x3377d1cf, v92
	v_fmac_f32_e32 v93, 0x3f317217, v92
	v_add_f32_e32 v91, v91, v93
	v_sub_f32_e32 v91, -0.5, v91
	v_mul_f32_e32 v91, 0x3fb8aa3b, v91
	v_exp_f32_e32 v91, v91
	s_nop 0
	v_cmp_ngt_f32_e32 vcc, s12, v91
	s_and_saveexec_b64 s[6:7], vcc
	s_xor_b64 s[6:7], exec, s[6:7]
	v_mul_f32_e32 v91, 0xbfb8aa3b, v91
	v_exp_f32_e32 v91, v91
	s_nop 0
	v_sub_f32_e32 v92, 1.0, v91
	s_andn2_saveexec_b64 s[6:7], s[6:7]
	v_fmamk_f32 v92, v91, 0xbd2aaaab, v160
	v_fma_f32 v92, -v91, v92, 0.5
	v_fma_f32 v92, -v91, v92, 1.0
	v_mul_f32_e32 v92, v91, v92
	s_or_b64 exec, exec, s[6:7]
	v_cvt_pk_f16_f32 v91, v90, v92
	v_cvt_pk_f16_f32 v90, v88, v89
	v_mov_b64_e32 v[88:89], v[132:133]
	v_ashrrev_i32_e32 v101, 31, v100
	v_lshlrev_b64 v[92:93], 11, v[100:101]
	v_lshl_add_u64 v[88:89], v[88:89], 0, v[92:93]
	s_lshl_b32 s52, s61, 10
	v_lshl_add_u64 v[88:89], v[88:89], 0, s[52:53]
	v_lshlrev_b32_e32 v134, 1, v140
	v_lshl_add_u64 v[88:89], v[88:89], 0, v[134:135]
	v_add_co_u32_e32 v88, vcc, 0x15a00000, v88
	s_nop 1
	v_addc_co_u32_e32 v89, vcc, 0, v89, vcc
	global_store_dwordx2 v[88:89], v[90:91], off offset:32
	s_and_b64 vcc, exec, s[4:5]
	s_mov_b64 s[6:7], -1
	s_cbranch_vccnz .LBB0_455

.LBB0_547:
	global_load_dwordx4 v[88:91], v141, s[54:55] offset:128
	s_waitcnt vmcnt(0)
	v_add_f32_e32 v84, v84, v88
	v_mul_f32_e64 v88, |v84|, s48
	v_exp_f32_e32 v88, v88
	v_max_f32_e64 v84, -v84, 0
	v_add_f32_e32 v88, 1.0, v88
	v_log_f32_e32 v88, v88
	s_nop 0
	v_mul_f32_e32 v92, 0x3f317217, v88
	v_fma_f32 v92, v88, s49, -v92
	v_fmac_f32_e32 v92, 0x3377d1cf, v88
	v_fmac_f32_e32 v92, 0x3f317217, v88
	v_add_f32_e32 v84, v84, v92
	v_sub_f32_e32 v84, -0.5, v84
	v_mul_f32_e32 v84, 0x3fb8aa3b, v84
	v_exp_f32_e32 v88, v84
	s_nop 0
	v_cmp_ngt_f32_e32 vcc, s12, v88
	s_and_saveexec_b64 s[6:7], vcc
	s_xor_b64 s[6:7], exec, s[6:7]
	v_mul_f32_e32 v84, 0xbfb8aa3b, v88
	v_exp_f32_e32 v84, v84
	s_nop 0
	v_sub_f32_e32 v84, 1.0, v84
	s_andn2_saveexec_b64 s[6:7], s[6:7]
	v_fmamk_f32 v84, v88, 0xbd2aaaab, v160
	v_fma_f32 v84, -v88, v84, 0.5
	v_fma_f32 v84, -v88, v84, 1.0
	v_mul_f32_e32 v84, v88, v84
	s_or_b64 exec, exec, s[6:7]
	v_add_f32_e32 v85, v85, v89
	v_mul_f32_e64 v88, |v85|, s48
	v_exp_f32_e32 v88, v88
	v_max_f32_e64 v85, -v85, 0
	v_add_f32_e32 v88, 1.0, v88
	v_log_f32_e32 v88, v88
	s_nop 0
	v_mul_f32_e32 v89, 0x3f317217, v88
	v_fma_f32 v89, v88, s49, -v89
	v_fmac_f32_e32 v89, 0x3377d1cf, v88
	v_fmac_f32_e32 v89, 0x3f317217, v88
	v_add_f32_e32 v85, v85, v89
	v_sub_f32_e32 v85, -0.5, v85
	v_mul_f32_e32 v85, 0x3fb8aa3b, v85
	v_exp_f32_e32 v88, v85
	s_nop 0
	v_cmp_ngt_f32_e32 vcc, s12, v88
	s_and_saveexec_b64 s[6:7], vcc
	s_xor_b64 s[6:7], exec, s[6:7]
	v_mul_f32_e32 v85, 0xbfb8aa3b, v88
	v_exp_f32_e32 v85, v85
	s_nop 0
	v_sub_f32_e32 v85, 1.0, v85
	s_andn2_saveexec_b64 s[6:7], s[6:7]
	v_fmamk_f32 v85, v88, 0xbd2aaaab, v160
	v_fma_f32 v85, -v88, v85, 0.5
	v_fma_f32 v85, -v88, v85, 1.0
	v_mul_f32_e32 v85, v88, v85
	s_or_b64 exec, exec, s[6:7]
	v_add_f32_e32 v86, v86, v90
	v_mul_f32_e64 v88, |v86|, s48
	v_exp_f32_e32 v88, v88
	v_max_f32_e64 v86, -v86, 0
	v_add_f32_e32 v88, 1.0, v88
	v_log_f32_e32 v88, v88
	s_nop 0
	v_mul_f32_e32 v89, 0x3f317217, v88
	v_fma_f32 v89, v88, s49, -v89
	v_fmac_f32_e32 v89, 0x3377d1cf, v88
	v_fmac_f32_e32 v89, 0x3f317217, v88
	v_add_f32_e32 v86, v86, v89
	v_sub_f32_e32 v86, -0.5, v86
	v_mul_f32_e32 v86, 0x3fb8aa3b, v86
	v_exp_f32_e32 v88, v86
	s_nop 0
	v_cmp_ngt_f32_e32 vcc, s12, v88
	s_and_saveexec_b64 s[6:7], vcc
	s_xor_b64 s[6:7], exec, s[6:7]
	v_mul_f32_e32 v86, 0xbfb8aa3b, v88
	v_exp_f32_e32 v86, v86
	s_nop 0
	v_sub_f32_e32 v86, 1.0, v86
	s_andn2_saveexec_b64 s[6:7], s[6:7]
	v_fmamk_f32 v86, v88, 0xbd2aaaab, v160
	v_fma_f32 v86, -v88, v86, 0.5
	v_fma_f32 v86, -v88, v86, 1.0
	v_mul_f32_e32 v86, v88, v86
	s_or_b64 exec, exec, s[6:7]
	v_add_f32_e32 v87, v87, v91
	v_mul_f32_e64 v88, |v87|, s48
	v_exp_f32_e32 v88, v88
	v_max_f32_e64 v87, -v87, 0
	v_add_f32_e32 v88, 1.0, v88
	v_log_f32_e32 v88, v88
	s_nop 0
	v_mul_f32_e32 v89, 0x3f317217, v88
	v_fma_f32 v89, v88, s49, -v89
	v_fmac_f32_e32 v89, 0x3377d1cf, v88
	v_fmac_f32_e32 v89, 0x3f317217, v88
	v_add_f32_e32 v87, v87, v89
	v_sub_f32_e32 v87, -0.5, v87
	v_mul_f32_e32 v87, 0x3fb8aa3b, v87
	v_exp_f32_e32 v87, v87
	s_nop 0
	v_cmp_ngt_f32_e32 vcc, s12, v87
	s_and_saveexec_b64 s[6:7], vcc
	s_xor_b64 s[6:7], exec, s[6:7]
	v_mul_f32_e32 v87, 0xbfb8aa3b, v87
	v_exp_f32_e32 v87, v87
	s_nop 0
	v_sub_f32_e32 v88, 1.0, v87
	s_andn2_saveexec_b64 s[6:7], s[6:7]
	v_fmamk_f32 v88, v87, 0xbd2aaaab, v160
	v_fma_f32 v88, -v87, v88, 0.5
	v_fma_f32 v88, -v87, v88, 1.0
	v_mul_f32_e32 v88, v87, v88
	s_or_b64 exec, exec, s[6:7]
	v_cvt_pk_f16_f32 v87, v86, v88
	v_cvt_pk_f16_f32 v86, v84, v85
	v_mov_b64_e32 v[84:85], v[132:133]
	v_ashrrev_i32_e32 v101, 31, v100
	v_lshlrev_b64 v[88:89], 11, v[100:101]
	v_lshl_add_u64 v[84:85], v[84:85], 0, v[88:89]
	s_lshl_b32 s52, s61, 10
	v_lshl_add_u64 v[84:85], v[84:85], 0, s[52:53]
	v_lshlrev_b32_e32 v134, 1, v140
	v_lshl_add_u64 v[84:85], v[84:85], 0, v[134:135]
	v_add_co_u32_e32 v84, vcc, 0x15a00000, v84
	s_nop 1
	v_addc_co_u32_e32 v85, vcc, 0, v85, vcc
	global_store_dwordx2 v[84:85], v[86:87], off offset:64
	s_and_b64 vcc, exec, s[4:5]
	s_mov_b64 s[6:7], -1
	s_cbranch_vccnz .LBB0_457

.LBB0_569:
	global_load_dwordx4 v[84:87], v141, s[54:55] offset:192
	s_waitcnt vmcnt(0)
	v_add_f32_e32 v80, v80, v84
	v_mul_f32_e64 v84, |v80|, s48
	v_exp_f32_e32 v84, v84
	v_max_f32_e64 v80, -v80, 0
	v_add_f32_e32 v84, 1.0, v84
	v_log_f32_e32 v84, v84
	s_nop 0
	v_mul_f32_e32 v88, 0x3f317217, v84
	v_fma_f32 v88, v84, s49, -v88
	v_fmac_f32_e32 v88, 0x3377d1cf, v84
	v_fmac_f32_e32 v88, 0x3f317217, v84
	v_add_f32_e32 v80, v80, v88
	v_sub_f32_e32 v80, -0.5, v80
	v_mul_f32_e32 v80, 0x3fb8aa3b, v80
	v_exp_f32_e32 v84, v80
	s_nop 0
	v_cmp_ngt_f32_e32 vcc, s12, v84
	s_and_saveexec_b64 s[6:7], vcc
	s_xor_b64 s[6:7], exec, s[6:7]
	v_mul_f32_e32 v80, 0xbfb8aa3b, v84
	v_exp_f32_e32 v80, v80
	s_nop 0
	v_sub_f32_e32 v80, 1.0, v80
	s_andn2_saveexec_b64 s[6:7], s[6:7]
	v_fmamk_f32 v80, v84, 0xbd2aaaab, v160
	v_fma_f32 v80, -v84, v80, 0.5
	v_fma_f32 v80, -v84, v80, 1.0
	v_mul_f32_e32 v80, v84, v80
	s_or_b64 exec, exec, s[6:7]
	v_add_f32_e32 v81, v81, v85
	v_mul_f32_e64 v84, |v81|, s48
	v_exp_f32_e32 v84, v84
	v_max_f32_e64 v81, -v81, 0
	v_add_f32_e32 v84, 1.0, v84
	v_log_f32_e32 v84, v84
	s_nop 0
	v_mul_f32_e32 v85, 0x3f317217, v84
	v_fma_f32 v85, v84, s49, -v85
	v_fmac_f32_e32 v85, 0x3377d1cf, v84
	v_fmac_f32_e32 v85, 0x3f317217, v84
	v_add_f32_e32 v81, v81, v85
	v_sub_f32_e32 v81, -0.5, v81
	v_mul_f32_e32 v81, 0x3fb8aa3b, v81
	v_exp_f32_e32 v84, v81
	s_nop 0
	v_cmp_ngt_f32_e32 vcc, s12, v84
	s_and_saveexec_b64 s[6:7], vcc
	s_xor_b64 s[6:7], exec, s[6:7]
	v_mul_f32_e32 v81, 0xbfb8aa3b, v84
	v_exp_f32_e32 v81, v81
	s_nop 0
	v_sub_f32_e32 v81, 1.0, v81
	s_andn2_saveexec_b64 s[6:7], s[6:7]
	v_fmamk_f32 v81, v84, 0xbd2aaaab, v160
	v_fma_f32 v81, -v84, v81, 0.5
	v_fma_f32 v81, -v84, v81, 1.0
	v_mul_f32_e32 v81, v84, v81
	s_or_b64 exec, exec, s[6:7]
	v_add_f32_e32 v82, v82, v86
	v_mul_f32_e64 v84, |v82|, s48
	v_exp_f32_e32 v84, v84
	v_max_f32_e64 v82, -v82, 0
	v_add_f32_e32 v84, 1.0, v84
	v_log_f32_e32 v84, v84
	s_nop 0
	v_mul_f32_e32 v85, 0x3f317217, v84
	v_fma_f32 v85, v84, s49, -v85
	v_fmac_f32_e32 v85, 0x3377d1cf, v84
	v_fmac_f32_e32 v85, 0x3f317217, v84
	v_add_f32_e32 v82, v82, v85
	v_sub_f32_e32 v82, -0.5, v82
	v_mul_f32_e32 v82, 0x3fb8aa3b, v82
	v_exp_f32_e32 v84, v82
	s_nop 0
	v_cmp_ngt_f32_e32 vcc, s12, v84
	s_and_saveexec_b64 s[6:7], vcc
	s_xor_b64 s[6:7], exec, s[6:7]
	v_mul_f32_e32 v82, 0xbfb8aa3b, v84
	v_exp_f32_e32 v82, v82
	s_nop 0
	v_sub_f32_e32 v82, 1.0, v82
	s_andn2_saveexec_b64 s[6:7], s[6:7]
	v_fmamk_f32 v82, v84, 0xbd2aaaab, v160
	v_fma_f32 v82, -v84, v82, 0.5
	v_fma_f32 v82, -v84, v82, 1.0
	v_mul_f32_e32 v82, v84, v82
	s_or_b64 exec, exec, s[6:7]
	v_add_f32_e32 v83, v83, v87
	v_mul_f32_e64 v84, |v83|, s48
	v_exp_f32_e32 v84, v84
	v_max_f32_e64 v83, -v83, 0
	v_add_f32_e32 v84, 1.0, v84
	v_log_f32_e32 v84, v84
	s_nop 0
	v_mul_f32_e32 v85, 0x3f317217, v84
	v_fma_f32 v85, v84, s49, -v85
	v_fmac_f32_e32 v85, 0x3377d1cf, v84
	v_fmac_f32_e32 v85, 0x3f317217, v84
	v_add_f32_e32 v83, v83, v85
	v_sub_f32_e32 v83, -0.5, v83
	v_mul_f32_e32 v83, 0x3fb8aa3b, v83
	v_exp_f32_e32 v83, v83
	s_nop 0
	v_cmp_ngt_f32_e32 vcc, s12, v83
	s_and_saveexec_b64 s[6:7], vcc
	s_xor_b64 s[6:7], exec, s[6:7]
	v_mul_f32_e32 v83, 0xbfb8aa3b, v83
	v_exp_f32_e32 v83, v83
	s_nop 0
	v_sub_f32_e32 v84, 1.0, v83
	s_andn2_saveexec_b64 s[6:7], s[6:7]
	v_fmamk_f32 v84, v83, 0xbd2aaaab, v160
	v_fma_f32 v84, -v83, v84, 0.5
	v_fma_f32 v84, -v83, v84, 1.0
	v_mul_f32_e32 v84, v83, v84
	s_or_b64 exec, exec, s[6:7]
	v_cvt_pk_f16_f32 v83, v82, v84
	v_cvt_pk_f16_f32 v82, v80, v81
	v_mov_b64_e32 v[80:81], v[132:133]
	v_ashrrev_i32_e32 v101, 31, v100
	v_lshlrev_b64 v[84:85], 11, v[100:101]
	v_lshl_add_u64 v[80:81], v[80:81], 0, v[84:85]
	s_lshl_b32 s52, s61, 10
	v_lshl_add_u64 v[80:81], v[80:81], 0, s[52:53]
	v_lshlrev_b32_e32 v134, 1, v140
	v_lshl_add_u64 v[80:81], v[80:81], 0, v[134:135]
	v_add_co_u32_e32 v80, vcc, 0x15a00000, v80
	s_nop 1
	v_addc_co_u32_e32 v81, vcc, 0, v81, vcc
	global_store_dwordx2 v[80:81], v[82:83], off offset:96
	s_and_b64 vcc, exec, s[4:5]
	s_mov_b64 s[6:7], -1
	s_cbranch_vccnz .LBB0_459

.LBB0_591:
	global_load_dwordx4 v[80:83], v141, s[54:55] offset:256
	s_waitcnt vmcnt(0)
	v_add_f32_e32 v76, v76, v80
	v_mul_f32_e64 v80, |v76|, s48
	v_exp_f32_e32 v80, v80
	v_max_f32_e64 v76, -v76, 0
	v_add_f32_e32 v80, 1.0, v80
	v_log_f32_e32 v80, v80
	s_nop 0
	v_mul_f32_e32 v84, 0x3f317217, v80
	v_fma_f32 v84, v80, s49, -v84
	v_fmac_f32_e32 v84, 0x3377d1cf, v80
	v_fmac_f32_e32 v84, 0x3f317217, v80
	v_add_f32_e32 v76, v76, v84
	v_sub_f32_e32 v76, -0.5, v76
	v_mul_f32_e32 v76, 0x3fb8aa3b, v76
	v_exp_f32_e32 v80, v76
	s_nop 0
	v_cmp_ngt_f32_e32 vcc, s12, v80
	s_and_saveexec_b64 s[6:7], vcc
	s_xor_b64 s[6:7], exec, s[6:7]
	v_mul_f32_e32 v76, 0xbfb8aa3b, v80
	v_exp_f32_e32 v76, v76
	s_nop 0
	v_sub_f32_e32 v76, 1.0, v76
	s_andn2_saveexec_b64 s[6:7], s[6:7]
	v_fmamk_f32 v76, v80, 0xbd2aaaab, v160
	v_fma_f32 v76, -v80, v76, 0.5
	v_fma_f32 v76, -v80, v76, 1.0
	v_mul_f32_e32 v76, v80, v76
	s_or_b64 exec, exec, s[6:7]
	v_add_f32_e32 v77, v77, v81
	v_mul_f32_e64 v80, |v77|, s48
	v_exp_f32_e32 v80, v80
	v_max_f32_e64 v77, -v77, 0
	v_add_f32_e32 v80, 1.0, v80
	v_log_f32_e32 v80, v80
	s_nop 0
	v_mul_f32_e32 v81, 0x3f317217, v80
	v_fma_f32 v81, v80, s49, -v81
	v_fmac_f32_e32 v81, 0x3377d1cf, v80
	v_fmac_f32_e32 v81, 0x3f317217, v80
	v_add_f32_e32 v77, v77, v81
	v_sub_f32_e32 v77, -0.5, v77
	v_mul_f32_e32 v77, 0x3fb8aa3b, v77
	v_exp_f32_e32 v80, v77
	s_nop 0
	v_cmp_ngt_f32_e32 vcc, s12, v80
	s_and_saveexec_b64 s[6:7], vcc
	s_xor_b64 s[6:7], exec, s[6:7]
	v_mul_f32_e32 v77, 0xbfb8aa3b, v80
	v_exp_f32_e32 v77, v77
	s_nop 0
	v_sub_f32_e32 v77, 1.0, v77
	s_andn2_saveexec_b64 s[6:7], s[6:7]
	v_fmamk_f32 v77, v80, 0xbd2aaaab, v160
	v_fma_f32 v77, -v80, v77, 0.5
	v_fma_f32 v77, -v80, v77, 1.0
	v_mul_f32_e32 v77, v80, v77
	s_or_b64 exec, exec, s[6:7]
	v_add_f32_e32 v78, v78, v82
	v_mul_f32_e64 v80, |v78|, s48
	v_exp_f32_e32 v80, v80
	v_max_f32_e64 v78, -v78, 0
	v_add_f32_e32 v80, 1.0, v80
	v_log_f32_e32 v80, v80
	s_nop 0
	v_mul_f32_e32 v81, 0x3f317217, v80
	v_fma_f32 v81, v80, s49, -v81
	v_fmac_f32_e32 v81, 0x3377d1cf, v80
	v_fmac_f32_e32 v81, 0x3f317217, v80
	v_add_f32_e32 v78, v78, v81
	v_sub_f32_e32 v78, -0.5, v78
	v_mul_f32_e32 v78, 0x3fb8aa3b, v78
	v_exp_f32_e32 v80, v78
	s_nop 0
	v_cmp_ngt_f32_e32 vcc, s12, v80
	s_and_saveexec_b64 s[6:7], vcc
	s_xor_b64 s[6:7], exec, s[6:7]
	v_mul_f32_e32 v78, 0xbfb8aa3b, v80
	v_exp_f32_e32 v78, v78
	s_nop 0
	v_sub_f32_e32 v78, 1.0, v78
	s_andn2_saveexec_b64 s[6:7], s[6:7]
	v_fmamk_f32 v78, v80, 0xbd2aaaab, v160
	v_fma_f32 v78, -v80, v78, 0.5
	v_fma_f32 v78, -v80, v78, 1.0
	v_mul_f32_e32 v78, v80, v78
	s_or_b64 exec, exec, s[6:7]
	v_add_f32_e32 v79, v79, v83
	v_mul_f32_e64 v80, |v79|, s48
	v_exp_f32_e32 v80, v80
	v_max_f32_e64 v79, -v79, 0
	v_add_f32_e32 v80, 1.0, v80
	v_log_f32_e32 v80, v80
	s_nop 0
	v_mul_f32_e32 v81, 0x3f317217, v80
	v_fma_f32 v81, v80, s49, -v81
	v_fmac_f32_e32 v81, 0x3377d1cf, v80
	v_fmac_f32_e32 v81, 0x3f317217, v80
	v_add_f32_e32 v79, v79, v81
	v_sub_f32_e32 v79, -0.5, v79
	v_mul_f32_e32 v79, 0x3fb8aa3b, v79
	v_exp_f32_e32 v79, v79
	s_nop 0
	v_cmp_ngt_f32_e32 vcc, s12, v79
	s_and_saveexec_b64 s[6:7], vcc
	s_xor_b64 s[6:7], exec, s[6:7]
	v_mul_f32_e32 v79, 0xbfb8aa3b, v79
	v_exp_f32_e32 v79, v79
	s_nop 0
	v_sub_f32_e32 v80, 1.0, v79
	s_andn2_saveexec_b64 s[6:7], s[6:7]
	v_fmamk_f32 v80, v79, 0xbd2aaaab, v160
	v_fma_f32 v80, -v79, v80, 0.5
	v_fma_f32 v80, -v79, v80, 1.0
	v_mul_f32_e32 v80, v79, v80
	s_or_b64 exec, exec, s[6:7]
	v_cvt_pk_f16_f32 v79, v78, v80
	v_cvt_pk_f16_f32 v78, v76, v77
	v_mov_b64_e32 v[76:77], v[132:133]
	v_ashrrev_i32_e32 v101, 31, v100
	v_lshlrev_b64 v[80:81], 11, v[100:101]
	v_lshl_add_u64 v[76:77], v[76:77], 0, v[80:81]
	s_lshl_b32 s52, s61, 10
	v_lshl_add_u64 v[76:77], v[76:77], 0, s[52:53]
	v_lshlrev_b32_e32 v134, 1, v140
	v_lshl_add_u64 v[76:77], v[76:77], 0, v[134:135]
	v_add_co_u32_e32 v76, vcc, 0x15a00000, v76
	s_nop 1
	v_addc_co_u32_e32 v77, vcc, 0, v77, vcc
	global_store_dwordx2 v[76:77], v[78:79], off offset:128
	s_and_b64 vcc, exec, s[4:5]
	s_mov_b64 s[6:7], -1
	s_cbranch_vccnz .LBB0_461

.LBB0_613:
	global_load_dwordx4 v[76:79], v141, s[54:55] offset:320
	s_waitcnt vmcnt(0)
	v_add_f32_e32 v72, v72, v76
	v_mul_f32_e64 v76, |v72|, s48
	v_exp_f32_e32 v76, v76
	v_max_f32_e64 v72, -v72, 0
	v_add_f32_e32 v76, 1.0, v76
	v_log_f32_e32 v76, v76
	s_nop 0
	v_mul_f32_e32 v80, 0x3f317217, v76
	v_fma_f32 v80, v76, s49, -v80
	v_fmac_f32_e32 v80, 0x3377d1cf, v76
	v_fmac_f32_e32 v80, 0x3f317217, v76
	v_add_f32_e32 v72, v72, v80
	v_sub_f32_e32 v72, -0.5, v72
	v_mul_f32_e32 v72, 0x3fb8aa3b, v72
	v_exp_f32_e32 v76, v72
	s_nop 0
	v_cmp_ngt_f32_e32 vcc, s12, v76
	s_and_saveexec_b64 s[6:7], vcc
	s_xor_b64 s[6:7], exec, s[6:7]
	v_mul_f32_e32 v72, 0xbfb8aa3b, v76
	v_exp_f32_e32 v72, v72
	s_nop 0
	v_sub_f32_e32 v72, 1.0, v72
	s_andn2_saveexec_b64 s[6:7], s[6:7]
	v_fmamk_f32 v72, v76, 0xbd2aaaab, v160
	v_fma_f32 v72, -v76, v72, 0.5
	v_fma_f32 v72, -v76, v72, 1.0
	v_mul_f32_e32 v72, v76, v72
	s_or_b64 exec, exec, s[6:7]
	v_add_f32_e32 v73, v73, v77
	v_mul_f32_e64 v76, |v73|, s48
	v_exp_f32_e32 v76, v76
	v_max_f32_e64 v73, -v73, 0
	v_add_f32_e32 v76, 1.0, v76
	v_log_f32_e32 v76, v76
	s_nop 0
	v_mul_f32_e32 v77, 0x3f317217, v76
	v_fma_f32 v77, v76, s49, -v77
	v_fmac_f32_e32 v77, 0x3377d1cf, v76
	v_fmac_f32_e32 v77, 0x3f317217, v76
	v_add_f32_e32 v73, v73, v77
	v_sub_f32_e32 v73, -0.5, v73
	v_mul_f32_e32 v73, 0x3fb8aa3b, v73
	v_exp_f32_e32 v76, v73
	s_nop 0
	v_cmp_ngt_f32_e32 vcc, s12, v76
	s_and_saveexec_b64 s[6:7], vcc
	s_xor_b64 s[6:7], exec, s[6:7]
	v_mul_f32_e32 v73, 0xbfb8aa3b, v76
	v_exp_f32_e32 v73, v73
	s_nop 0
	v_sub_f32_e32 v73, 1.0, v73
	s_andn2_saveexec_b64 s[6:7], s[6:7]
	v_fmamk_f32 v73, v76, 0xbd2aaaab, v160
	v_fma_f32 v73, -v76, v73, 0.5
	v_fma_f32 v73, -v76, v73, 1.0
	v_mul_f32_e32 v73, v76, v73
	s_or_b64 exec, exec, s[6:7]
	v_add_f32_e32 v74, v74, v78
	v_mul_f32_e64 v76, |v74|, s48
	v_exp_f32_e32 v76, v76
	v_max_f32_e64 v74, -v74, 0
	v_add_f32_e32 v76, 1.0, v76
	v_log_f32_e32 v76, v76
	s_nop 0
	v_mul_f32_e32 v77, 0x3f317217, v76
	v_fma_f32 v77, v76, s49, -v77
	v_fmac_f32_e32 v77, 0x3377d1cf, v76
	v_fmac_f32_e32 v77, 0x3f317217, v76
	v_add_f32_e32 v74, v74, v77
	v_sub_f32_e32 v74, -0.5, v74
	v_mul_f32_e32 v74, 0x3fb8aa3b, v74
	v_exp_f32_e32 v76, v74
	s_nop 0
	v_cmp_ngt_f32_e32 vcc, s12, v76
	s_and_saveexec_b64 s[6:7], vcc
	s_xor_b64 s[6:7], exec, s[6:7]
	v_mul_f32_e32 v74, 0xbfb8aa3b, v76
	v_exp_f32_e32 v74, v74
	s_nop 0
	v_sub_f32_e32 v74, 1.0, v74
	s_andn2_saveexec_b64 s[6:7], s[6:7]
	v_fmamk_f32 v74, v76, 0xbd2aaaab, v160
	v_fma_f32 v74, -v76, v74, 0.5
	v_fma_f32 v74, -v76, v74, 1.0
	v_mul_f32_e32 v74, v76, v74
	s_or_b64 exec, exec, s[6:7]
	v_add_f32_e32 v75, v75, v79
	v_mul_f32_e64 v76, |v75|, s48
	v_exp_f32_e32 v76, v76
	v_max_f32_e64 v75, -v75, 0
	v_add_f32_e32 v76, 1.0, v76
	v_log_f32_e32 v76, v76
	s_nop 0
	v_mul_f32_e32 v77, 0x3f317217, v76
	v_fma_f32 v77, v76, s49, -v77
	v_fmac_f32_e32 v77, 0x3377d1cf, v76
	v_fmac_f32_e32 v77, 0x3f317217, v76
	v_add_f32_e32 v75, v75, v77
	v_sub_f32_e32 v75, -0.5, v75
	v_mul_f32_e32 v75, 0x3fb8aa3b, v75
	v_exp_f32_e32 v75, v75
	s_nop 0
	v_cmp_ngt_f32_e32 vcc, s12, v75
	s_and_saveexec_b64 s[6:7], vcc
	s_xor_b64 s[6:7], exec, s[6:7]
	v_mul_f32_e32 v75, 0xbfb8aa3b, v75
	v_exp_f32_e32 v75, v75
	s_nop 0
	v_sub_f32_e32 v76, 1.0, v75
	s_andn2_saveexec_b64 s[6:7], s[6:7]
	v_fmamk_f32 v76, v75, 0xbd2aaaab, v160
	v_fma_f32 v76, -v75, v76, 0.5
	v_fma_f32 v76, -v75, v76, 1.0
	v_mul_f32_e32 v76, v75, v76
	s_or_b64 exec, exec, s[6:7]
	v_cvt_pk_f16_f32 v75, v74, v76
	v_cvt_pk_f16_f32 v74, v72, v73
	v_mov_b64_e32 v[72:73], v[132:133]
	v_ashrrev_i32_e32 v101, 31, v100
	v_lshlrev_b64 v[76:77], 11, v[100:101]
	v_lshl_add_u64 v[72:73], v[72:73], 0, v[76:77]
	s_lshl_b32 s52, s61, 10
	v_lshl_add_u64 v[72:73], v[72:73], 0, s[52:53]
	v_lshlrev_b32_e32 v134, 1, v140
	v_lshl_add_u64 v[72:73], v[72:73], 0, v[134:135]
	v_add_co_u32_e32 v72, vcc, 0x15a00000, v72
	s_nop 1
	v_addc_co_u32_e32 v73, vcc, 0, v73, vcc
	global_store_dwordx2 v[72:73], v[74:75], off offset:160
	s_and_b64 vcc, exec, s[4:5]
	s_mov_b64 s[6:7], -1
	s_cbranch_vccnz .LBB0_463

.LBB0_635:
	global_load_dwordx4 v[72:75], v141, s[54:55] offset:384
	s_waitcnt vmcnt(0)
	v_add_f32_e32 v68, v68, v72
	v_mul_f32_e64 v72, |v68|, s48
	v_exp_f32_e32 v72, v72
	v_max_f32_e64 v68, -v68, 0
	v_add_f32_e32 v72, 1.0, v72
	v_log_f32_e32 v72, v72
	s_nop 0
	v_mul_f32_e32 v76, 0x3f317217, v72
	v_fma_f32 v76, v72, s49, -v76
	v_fmac_f32_e32 v76, 0x3377d1cf, v72
	v_fmac_f32_e32 v76, 0x3f317217, v72
	v_add_f32_e32 v68, v68, v76
	v_sub_f32_e32 v68, -0.5, v68
	v_mul_f32_e32 v68, 0x3fb8aa3b, v68
	v_exp_f32_e32 v72, v68
	s_nop 0
	v_cmp_ngt_f32_e32 vcc, s12, v72
	s_and_saveexec_b64 s[6:7], vcc
	s_xor_b64 s[6:7], exec, s[6:7]
	v_mul_f32_e32 v68, 0xbfb8aa3b, v72
	v_exp_f32_e32 v68, v68
	s_nop 0
	v_sub_f32_e32 v68, 1.0, v68
	s_andn2_saveexec_b64 s[6:7], s[6:7]
	v_fmamk_f32 v68, v72, 0xbd2aaaab, v160
	v_fma_f32 v68, -v72, v68, 0.5
	v_fma_f32 v68, -v72, v68, 1.0
	v_mul_f32_e32 v68, v72, v68
	s_or_b64 exec, exec, s[6:7]
	v_add_f32_e32 v69, v69, v73
	v_mul_f32_e64 v72, |v69|, s48
	v_exp_f32_e32 v72, v72
	v_max_f32_e64 v69, -v69, 0
	v_add_f32_e32 v72, 1.0, v72
	v_log_f32_e32 v72, v72
	s_nop 0
	v_mul_f32_e32 v73, 0x3f317217, v72
	v_fma_f32 v73, v72, s49, -v73
	v_fmac_f32_e32 v73, 0x3377d1cf, v72
	v_fmac_f32_e32 v73, 0x3f317217, v72
	v_add_f32_e32 v69, v69, v73
	v_sub_f32_e32 v69, -0.5, v69
	v_mul_f32_e32 v69, 0x3fb8aa3b, v69
	v_exp_f32_e32 v72, v69
	s_nop 0
	v_cmp_ngt_f32_e32 vcc, s12, v72
	s_and_saveexec_b64 s[6:7], vcc
	s_xor_b64 s[6:7], exec, s[6:7]
	v_mul_f32_e32 v69, 0xbfb8aa3b, v72
	v_exp_f32_e32 v69, v69
	s_nop 0
	v_sub_f32_e32 v69, 1.0, v69
	s_andn2_saveexec_b64 s[6:7], s[6:7]
	v_fmamk_f32 v69, v72, 0xbd2aaaab, v160
	v_fma_f32 v69, -v72, v69, 0.5
	v_fma_f32 v69, -v72, v69, 1.0
	v_mul_f32_e32 v69, v72, v69
	s_or_b64 exec, exec, s[6:7]
	v_add_f32_e32 v70, v70, v74
	v_mul_f32_e64 v72, |v70|, s48
	v_exp_f32_e32 v72, v72
	v_max_f32_e64 v70, -v70, 0
	v_add_f32_e32 v72, 1.0, v72
	v_log_f32_e32 v72, v72
	s_nop 0
	v_mul_f32_e32 v73, 0x3f317217, v72
	v_fma_f32 v73, v72, s49, -v73
	v_fmac_f32_e32 v73, 0x3377d1cf, v72
	v_fmac_f32_e32 v73, 0x3f317217, v72
	v_add_f32_e32 v70, v70, v73
	v_sub_f32_e32 v70, -0.5, v70
	v_mul_f32_e32 v70, 0x3fb8aa3b, v70
	v_exp_f32_e32 v72, v70
	s_nop 0
	v_cmp_ngt_f32_e32 vcc, s12, v72
	s_and_saveexec_b64 s[6:7], vcc
	s_xor_b64 s[6:7], exec, s[6:7]
	v_mul_f32_e32 v70, 0xbfb8aa3b, v72
	v_exp_f32_e32 v70, v70
	s_nop 0
	v_sub_f32_e32 v70, 1.0, v70
	s_andn2_saveexec_b64 s[6:7], s[6:7]
	v_fmamk_f32 v70, v72, 0xbd2aaaab, v160
	v_fma_f32 v70, -v72, v70, 0.5
	v_fma_f32 v70, -v72, v70, 1.0
	v_mul_f32_e32 v70, v72, v70
	s_or_b64 exec, exec, s[6:7]
	v_add_f32_e32 v71, v71, v75
	v_mul_f32_e64 v72, |v71|, s48
	v_exp_f32_e32 v72, v72
	v_max_f32_e64 v71, -v71, 0
	v_add_f32_e32 v72, 1.0, v72
	v_log_f32_e32 v72, v72
	s_nop 0
	v_mul_f32_e32 v73, 0x3f317217, v72
	v_fma_f32 v73, v72, s49, -v73
	v_fmac_f32_e32 v73, 0x3377d1cf, v72
	v_fmac_f32_e32 v73, 0x3f317217, v72
	v_add_f32_e32 v71, v71, v73
	v_sub_f32_e32 v71, -0.5, v71
	v_mul_f32_e32 v71, 0x3fb8aa3b, v71
	v_exp_f32_e32 v71, v71
	s_nop 0
	v_cmp_ngt_f32_e32 vcc, s12, v71
	s_and_saveexec_b64 s[6:7], vcc
	s_xor_b64 s[6:7], exec, s[6:7]
	v_mul_f32_e32 v71, 0xbfb8aa3b, v71
	v_exp_f32_e32 v71, v71
	s_nop 0
	v_sub_f32_e32 v72, 1.0, v71
	s_andn2_saveexec_b64 s[6:7], s[6:7]
	v_fmamk_f32 v72, v71, 0xbd2aaaab, v160
	v_fma_f32 v72, -v71, v72, 0.5
	v_fma_f32 v72, -v71, v72, 1.0
	v_mul_f32_e32 v72, v71, v72
	s_or_b64 exec, exec, s[6:7]
	v_cvt_pk_f16_f32 v71, v70, v72
	v_cvt_pk_f16_f32 v70, v68, v69
	v_mov_b64_e32 v[68:69], v[132:133]
	v_ashrrev_i32_e32 v101, 31, v100
	v_lshlrev_b64 v[72:73], 11, v[100:101]
	v_lshl_add_u64 v[68:69], v[68:69], 0, v[72:73]
	s_lshl_b32 s52, s61, 10
	v_lshl_add_u64 v[68:69], v[68:69], 0, s[52:53]
	v_lshlrev_b32_e32 v134, 1, v140
	v_lshl_add_u64 v[68:69], v[68:69], 0, v[134:135]
	v_add_co_u32_e32 v68, vcc, 0x15a00000, v68
	s_nop 1
	v_addc_co_u32_e32 v69, vcc, 0, v69, vcc
	global_store_dwordx2 v[68:69], v[70:71], off offset:192
	s_and_b64 vcc, exec, s[4:5]
	s_mov_b64 s[6:7], -1
	s_cbranch_vccnz .LBB0_465

.LBB0_657:
	global_load_dwordx4 v[68:71], v141, s[54:55] offset:448
	s_waitcnt vmcnt(0)
	v_add_f32_e32 v64, v64, v68
	v_mul_f32_e64 v68, |v64|, s48
	v_exp_f32_e32 v68, v68
	v_max_f32_e64 v64, -v64, 0
	v_add_f32_e32 v68, 1.0, v68
	v_log_f32_e32 v68, v68
	s_nop 0
	v_mul_f32_e32 v72, 0x3f317217, v68
	v_fma_f32 v72, v68, s49, -v72
	v_fmac_f32_e32 v72, 0x3377d1cf, v68
	v_fmac_f32_e32 v72, 0x3f317217, v68
	v_add_f32_e32 v64, v64, v72
	v_sub_f32_e32 v64, -0.5, v64
	v_mul_f32_e32 v64, 0x3fb8aa3b, v64
	v_exp_f32_e32 v68, v64
	s_nop 0
	v_cmp_ngt_f32_e32 vcc, s12, v68
	s_and_saveexec_b64 s[6:7], vcc
	s_xor_b64 s[6:7], exec, s[6:7]
	v_mul_f32_e32 v64, 0xbfb8aa3b, v68
	v_exp_f32_e32 v64, v64
	s_nop 0
	v_sub_f32_e32 v64, 1.0, v64
	s_andn2_saveexec_b64 s[6:7], s[6:7]
	v_fmamk_f32 v64, v68, 0xbd2aaaab, v160
	v_fma_f32 v64, -v68, v64, 0.5
	v_fma_f32 v64, -v68, v64, 1.0
	v_mul_f32_e32 v64, v68, v64
	s_or_b64 exec, exec, s[6:7]
	v_add_f32_e32 v65, v65, v69
	v_mul_f32_e64 v68, |v65|, s48
	v_exp_f32_e32 v68, v68
	v_max_f32_e64 v65, -v65, 0
	v_add_f32_e32 v68, 1.0, v68
	v_log_f32_e32 v68, v68
	s_nop 0
	v_mul_f32_e32 v69, 0x3f317217, v68
	v_fma_f32 v69, v68, s49, -v69
	v_fmac_f32_e32 v69, 0x3377d1cf, v68
	v_fmac_f32_e32 v69, 0x3f317217, v68
	v_add_f32_e32 v65, v65, v69
	v_sub_f32_e32 v65, -0.5, v65
	v_mul_f32_e32 v65, 0x3fb8aa3b, v65
	v_exp_f32_e32 v68, v65
	s_nop 0
	v_cmp_ngt_f32_e32 vcc, s12, v68
	s_and_saveexec_b64 s[6:7], vcc
	s_xor_b64 s[6:7], exec, s[6:7]
	v_mul_f32_e32 v65, 0xbfb8aa3b, v68
	v_exp_f32_e32 v65, v65
	s_nop 0
	v_sub_f32_e32 v65, 1.0, v65
	s_andn2_saveexec_b64 s[6:7], s[6:7]
	v_fmamk_f32 v65, v68, 0xbd2aaaab, v160
	v_fma_f32 v65, -v68, v65, 0.5
	v_fma_f32 v65, -v68, v65, 1.0
	v_mul_f32_e32 v65, v68, v65
	s_or_b64 exec, exec, s[6:7]
	v_add_f32_e32 v66, v66, v70
	v_mul_f32_e64 v68, |v66|, s48
	v_exp_f32_e32 v68, v68
	v_max_f32_e64 v66, -v66, 0
	v_add_f32_e32 v68, 1.0, v68
	v_log_f32_e32 v68, v68
	s_nop 0
	v_mul_f32_e32 v69, 0x3f317217, v68
	v_fma_f32 v69, v68, s49, -v69
	v_fmac_f32_e32 v69, 0x3377d1cf, v68
	v_fmac_f32_e32 v69, 0x3f317217, v68
	v_add_f32_e32 v66, v66, v69
	v_sub_f32_e32 v66, -0.5, v66
	v_mul_f32_e32 v66, 0x3fb8aa3b, v66
	v_exp_f32_e32 v68, v66
	s_nop 0
	v_cmp_ngt_f32_e32 vcc, s12, v68
	s_and_saveexec_b64 s[6:7], vcc
	s_xor_b64 s[6:7], exec, s[6:7]
	v_mul_f32_e32 v66, 0xbfb8aa3b, v68
	v_exp_f32_e32 v66, v66
	s_nop 0
	v_sub_f32_e32 v66, 1.0, v66
	s_andn2_saveexec_b64 s[6:7], s[6:7]
	v_fmamk_f32 v66, v68, 0xbd2aaaab, v160
	v_fma_f32 v66, -v68, v66, 0.5
	v_fma_f32 v66, -v68, v66, 1.0
	v_mul_f32_e32 v66, v68, v66
	s_or_b64 exec, exec, s[6:7]
	v_add_f32_e32 v67, v67, v71
	v_mul_f32_e64 v68, |v67|, s48
	v_exp_f32_e32 v68, v68
	v_max_f32_e64 v67, -v67, 0
	v_add_f32_e32 v68, 1.0, v68
	v_log_f32_e32 v68, v68
	s_nop 0
	v_mul_f32_e32 v69, 0x3f317217, v68
	v_fma_f32 v69, v68, s49, -v69
	v_fmac_f32_e32 v69, 0x3377d1cf, v68
	v_fmac_f32_e32 v69, 0x3f317217, v68
	v_add_f32_e32 v67, v67, v69
	v_sub_f32_e32 v67, -0.5, v67
	v_mul_f32_e32 v67, 0x3fb8aa3b, v67
	v_exp_f32_e32 v67, v67
	s_nop 0
	v_cmp_ngt_f32_e32 vcc, s12, v67
	s_and_saveexec_b64 s[6:7], vcc
	s_xor_b64 s[6:7], exec, s[6:7]
	v_mul_f32_e32 v67, 0xbfb8aa3b, v67
	v_exp_f32_e32 v67, v67
	s_nop 0
	v_sub_f32_e32 v68, 1.0, v67
	s_andn2_saveexec_b64 s[6:7], s[6:7]
	v_fmamk_f32 v68, v67, 0xbd2aaaab, v160
	v_fma_f32 v68, -v67, v68, 0.5
	v_fma_f32 v68, -v67, v68, 1.0
	v_mul_f32_e32 v68, v67, v68
	s_or_b64 exec, exec, s[6:7]
	v_cvt_pk_f16_f32 v67, v66, v68
	v_cvt_pk_f16_f32 v66, v64, v65
	v_mov_b64_e32 v[64:65], v[132:133]
	v_ashrrev_i32_e32 v101, 31, v100
	v_lshlrev_b64 v[68:69], 11, v[100:101]
	v_lshl_add_u64 v[64:65], v[64:65], 0, v[68:69]
	s_lshl_b32 s52, s61, 10
	v_lshl_add_u64 v[64:65], v[64:65], 0, s[52:53]
	v_lshlrev_b32_e32 v134, 1, v140
	v_lshl_add_u64 v[64:65], v[64:65], 0, v[134:135]
	v_add_co_u32_e32 v64, vcc, 0x15a00000, v64
	s_nop 1
	v_addc_co_u32_e32 v65, vcc, 0, v65, vcc
	global_store_dwordx2 v[64:65], v[66:67], off offset:224
	v_or_b32_e32 v68, 32, v138
	s_and_b64 vcc, exec, s[4:5]
	s_mov_b64 s[6:7], -1
	s_cbranch_vccnz .LBB0_467

.LBB0_679:
	global_load_dwordx4 v[64:67], v141, s[54:55]
	s_waitcnt vmcnt(0)
	v_add_f32_e32 v60, v60, v64
	v_mul_f32_e64 v64, |v60|, s48
	v_exp_f32_e32 v64, v64
	v_max_f32_e64 v60, -v60, 0
	v_add_f32_e32 v64, 1.0, v64
	v_log_f32_e32 v64, v64
	s_nop 0
	v_mul_f32_e32 v69, 0x3f317217, v64
	v_fma_f32 v69, v64, s49, -v69
	v_fmac_f32_e32 v69, 0x3377d1cf, v64
	v_fmac_f32_e32 v69, 0x3f317217, v64
	v_add_f32_e32 v60, v60, v69
	v_sub_f32_e32 v60, -0.5, v60
	v_mul_f32_e32 v60, 0x3fb8aa3b, v60
	v_exp_f32_e32 v64, v60
	s_nop 0
	v_cmp_ngt_f32_e32 vcc, s12, v64
	s_and_saveexec_b64 s[6:7], vcc
	s_xor_b64 s[6:7], exec, s[6:7]
	v_mul_f32_e32 v60, 0xbfb8aa3b, v64
	v_exp_f32_e32 v60, v60
	s_nop 0
	v_sub_f32_e32 v60, 1.0, v60
	s_andn2_saveexec_b64 s[6:7], s[6:7]
	v_fmamk_f32 v60, v64, 0xbd2aaaab, v160
	v_fma_f32 v60, -v64, v60, 0.5
	v_fma_f32 v60, -v64, v60, 1.0
	v_mul_f32_e32 v60, v64, v60
	s_or_b64 exec, exec, s[6:7]
	v_add_f32_e32 v61, v61, v65
	v_mul_f32_e64 v64, |v61|, s48
	v_exp_f32_e32 v64, v64
	v_max_f32_e64 v61, -v61, 0
	v_add_f32_e32 v64, 1.0, v64
	v_log_f32_e32 v64, v64
	s_nop 0
	v_mul_f32_e32 v65, 0x3f317217, v64
	v_fma_f32 v65, v64, s49, -v65
	v_fmac_f32_e32 v65, 0x3377d1cf, v64
	v_fmac_f32_e32 v65, 0x3f317217, v64
	v_add_f32_e32 v61, v61, v65
	v_sub_f32_e32 v61, -0.5, v61
	v_mul_f32_e32 v61, 0x3fb8aa3b, v61
	v_exp_f32_e32 v64, v61
	s_nop 0
	v_cmp_ngt_f32_e32 vcc, s12, v64
	s_and_saveexec_b64 s[6:7], vcc
	s_xor_b64 s[6:7], exec, s[6:7]
	v_mul_f32_e32 v61, 0xbfb8aa3b, v64
	v_exp_f32_e32 v61, v61
	s_nop 0
	v_sub_f32_e32 v61, 1.0, v61
	s_andn2_saveexec_b64 s[6:7], s[6:7]
	v_fmamk_f32 v61, v64, 0xbd2aaaab, v160
	v_fma_f32 v61, -v64, v61, 0.5
	v_fma_f32 v61, -v64, v61, 1.0
	v_mul_f32_e32 v61, v64, v61
	s_or_b64 exec, exec, s[6:7]
	v_add_f32_e32 v62, v62, v66
	v_mul_f32_e64 v64, |v62|, s48
	v_exp_f32_e32 v64, v64
	v_max_f32_e64 v62, -v62, 0
	v_add_f32_e32 v64, 1.0, v64
	v_log_f32_e32 v64, v64
	s_nop 0
	v_mul_f32_e32 v65, 0x3f317217, v64
	v_fma_f32 v65, v64, s49, -v65
	v_fmac_f32_e32 v65, 0x3377d1cf, v64
	v_fmac_f32_e32 v65, 0x3f317217, v64
	v_add_f32_e32 v62, v62, v65
	v_sub_f32_e32 v62, -0.5, v62
	v_mul_f32_e32 v62, 0x3fb8aa3b, v62
	v_exp_f32_e32 v64, v62
	s_nop 0
	v_cmp_ngt_f32_e32 vcc, s12, v64
	s_and_saveexec_b64 s[6:7], vcc
	s_xor_b64 s[6:7], exec, s[6:7]
	v_mul_f32_e32 v62, 0xbfb8aa3b, v64
	v_exp_f32_e32 v62, v62
	s_nop 0
	v_sub_f32_e32 v62, 1.0, v62
	s_andn2_saveexec_b64 s[6:7], s[6:7]
	v_fmamk_f32 v62, v64, 0xbd2aaaab, v160
	v_fma_f32 v62, -v64, v62, 0.5
	v_fma_f32 v62, -v64, v62, 1.0
	v_mul_f32_e32 v62, v64, v62
	s_or_b64 exec, exec, s[6:7]
	v_add_f32_e32 v63, v63, v67
	v_mul_f32_e64 v64, |v63|, s48
	v_exp_f32_e32 v64, v64
	v_max_f32_e64 v63, -v63, 0
	v_add_f32_e32 v64, 1.0, v64
	v_log_f32_e32 v64, v64
	s_nop 0
	v_mul_f32_e32 v65, 0x3f317217, v64
	v_fma_f32 v65, v64, s49, -v65
	v_fmac_f32_e32 v65, 0x3377d1cf, v64
	v_fmac_f32_e32 v65, 0x3f317217, v64
	v_add_f32_e32 v63, v63, v65
	v_sub_f32_e32 v63, -0.5, v63
	v_mul_f32_e32 v63, 0x3fb8aa3b, v63
	v_exp_f32_e32 v63, v63
	s_nop 0
	v_cmp_ngt_f32_e32 vcc, s12, v63
	s_and_saveexec_b64 s[6:7], vcc
	s_xor_b64 s[6:7], exec, s[6:7]
	v_mul_f32_e32 v63, 0xbfb8aa3b, v63
	v_exp_f32_e32 v63, v63
	s_nop 0
	v_sub_f32_e32 v64, 1.0, v63
	s_andn2_saveexec_b64 s[6:7], s[6:7]
	v_fmamk_f32 v64, v63, 0xbd2aaaab, v160
	v_fma_f32 v64, -v63, v64, 0.5
	v_fma_f32 v64, -v63, v64, 1.0
	v_mul_f32_e32 v64, v63, v64
	s_or_b64 exec, exec, s[6:7]
	v_cvt_pk_f16_f32 v63, v62, v64
	v_cvt_pk_f16_f32 v62, v60, v61
	v_mov_b64_e32 v[60:61], v[132:133]
	v_ashrrev_i32_e32 v69, 31, v68
	v_lshlrev_b64 v[64:65], 11, v[68:69]
	v_lshl_add_u64 v[60:61], v[60:61], 0, v[64:65]
	s_lshl_b32 s52, s61, 10
	v_lshl_add_u64 v[60:61], v[60:61], 0, s[52:53]
	v_lshlrev_b32_e32 v134, 1, v140
	v_lshl_add_u64 v[60:61], v[60:61], 0, v[134:135]
	v_add_co_u32_e32 v60, vcc, 0x15a00000, v60
	s_nop 1
	v_addc_co_u32_e32 v61, vcc, 0, v61, vcc
	global_store_dwordx2 v[60:61], v[62:63], off
	s_and_b64 vcc, exec, s[4:5]
	s_mov_b64 s[6:7], -1
	s_cbranch_vccnz .LBB0_469

.LBB0_701:
	global_load_dwordx4 v[60:63], v141, s[54:55] offset:64
	s_waitcnt vmcnt(0)
	v_add_f32_e32 v56, v56, v60
	v_mul_f32_e64 v60, |v56|, s48
	v_exp_f32_e32 v60, v60
	v_max_f32_e64 v56, -v56, 0
	v_add_f32_e32 v60, 1.0, v60
	v_log_f32_e32 v60, v60
	s_nop 0
	v_mul_f32_e32 v64, 0x3f317217, v60
	v_fma_f32 v64, v60, s49, -v64
	v_fmac_f32_e32 v64, 0x3377d1cf, v60
	v_fmac_f32_e32 v64, 0x3f317217, v60
	v_add_f32_e32 v56, v56, v64
	v_sub_f32_e32 v56, -0.5, v56
	v_mul_f32_e32 v56, 0x3fb8aa3b, v56
	v_exp_f32_e32 v60, v56
	s_nop 0
	v_cmp_ngt_f32_e32 vcc, s12, v60
	s_and_saveexec_b64 s[6:7], vcc
	s_xor_b64 s[6:7], exec, s[6:7]
	v_mul_f32_e32 v56, 0xbfb8aa3b, v60
	v_exp_f32_e32 v56, v56
	s_nop 0
	v_sub_f32_e32 v56, 1.0, v56
	s_andn2_saveexec_b64 s[6:7], s[6:7]
	v_fmamk_f32 v56, v60, 0xbd2aaaab, v160
	v_fma_f32 v56, -v60, v56, 0.5
	v_fma_f32 v56, -v60, v56, 1.0
	v_mul_f32_e32 v56, v60, v56
	s_or_b64 exec, exec, s[6:7]
	v_add_f32_e32 v57, v57, v61
	v_mul_f32_e64 v60, |v57|, s48
	v_exp_f32_e32 v60, v60
	v_max_f32_e64 v57, -v57, 0
	v_add_f32_e32 v60, 1.0, v60
	v_log_f32_e32 v60, v60
	s_nop 0
	v_mul_f32_e32 v61, 0x3f317217, v60
	v_fma_f32 v61, v60, s49, -v61
	v_fmac_f32_e32 v61, 0x3377d1cf, v60
	v_fmac_f32_e32 v61, 0x3f317217, v60
	v_add_f32_e32 v57, v57, v61
	v_sub_f32_e32 v57, -0.5, v57
	v_mul_f32_e32 v57, 0x3fb8aa3b, v57
	v_exp_f32_e32 v60, v57
	s_nop 0
	v_cmp_ngt_f32_e32 vcc, s12, v60
	s_and_saveexec_b64 s[6:7], vcc
	s_xor_b64 s[6:7], exec, s[6:7]
	v_mul_f32_e32 v57, 0xbfb8aa3b, v60
	v_exp_f32_e32 v57, v57
	s_nop 0
	v_sub_f32_e32 v57, 1.0, v57
	s_andn2_saveexec_b64 s[6:7], s[6:7]
	v_fmamk_f32 v57, v60, 0xbd2aaaab, v160
	v_fma_f32 v57, -v60, v57, 0.5
	v_fma_f32 v57, -v60, v57, 1.0
	v_mul_f32_e32 v57, v60, v57
	s_or_b64 exec, exec, s[6:7]
	v_add_f32_e32 v58, v58, v62
	v_mul_f32_e64 v60, |v58|, s48
	v_exp_f32_e32 v60, v60
	v_max_f32_e64 v58, -v58, 0
	v_add_f32_e32 v60, 1.0, v60
	v_log_f32_e32 v60, v60
	s_nop 0
	v_mul_f32_e32 v61, 0x3f317217, v60
	v_fma_f32 v61, v60, s49, -v61
	v_fmac_f32_e32 v61, 0x3377d1cf, v60
	v_fmac_f32_e32 v61, 0x3f317217, v60
	v_add_f32_e32 v58, v58, v61
	v_sub_f32_e32 v58, -0.5, v58
	v_mul_f32_e32 v58, 0x3fb8aa3b, v58
	v_exp_f32_e32 v60, v58
	s_nop 0
	v_cmp_ngt_f32_e32 vcc, s12, v60
	s_and_saveexec_b64 s[6:7], vcc
	s_xor_b64 s[6:7], exec, s[6:7]
	v_mul_f32_e32 v58, 0xbfb8aa3b, v60
	v_exp_f32_e32 v58, v58
	s_nop 0
	v_sub_f32_e32 v58, 1.0, v58
	s_andn2_saveexec_b64 s[6:7], s[6:7]
	v_fmamk_f32 v58, v60, 0xbd2aaaab, v160
	v_fma_f32 v58, -v60, v58, 0.5
	v_fma_f32 v58, -v60, v58, 1.0
	v_mul_f32_e32 v58, v60, v58
	s_or_b64 exec, exec, s[6:7]
	v_add_f32_e32 v59, v59, v63
	v_mul_f32_e64 v60, |v59|, s48
	v_exp_f32_e32 v60, v60
	v_max_f32_e64 v59, -v59, 0
	v_add_f32_e32 v60, 1.0, v60
	v_log_f32_e32 v60, v60
	s_nop 0
	v_mul_f32_e32 v61, 0x3f317217, v60
	v_fma_f32 v61, v60, s49, -v61
	v_fmac_f32_e32 v61, 0x3377d1cf, v60
	v_fmac_f32_e32 v61, 0x3f317217, v60
	v_add_f32_e32 v59, v59, v61
	v_sub_f32_e32 v59, -0.5, v59
	v_mul_f32_e32 v59, 0x3fb8aa3b, v59
	v_exp_f32_e32 v59, v59
	s_nop 0
	v_cmp_ngt_f32_e32 vcc, s12, v59
	s_and_saveexec_b64 s[6:7], vcc
	s_xor_b64 s[6:7], exec, s[6:7]
	v_mul_f32_e32 v59, 0xbfb8aa3b, v59
	v_exp_f32_e32 v59, v59
	s_nop 0
	v_sub_f32_e32 v60, 1.0, v59
	s_andn2_saveexec_b64 s[6:7], s[6:7]
	v_fmamk_f32 v60, v59, 0xbd2aaaab, v160
	v_fma_f32 v60, -v59, v60, 0.5
	v_fma_f32 v60, -v59, v60, 1.0
	v_mul_f32_e32 v60, v59, v60
	s_or_b64 exec, exec, s[6:7]
	v_cvt_pk_f16_f32 v59, v58, v60
	v_cvt_pk_f16_f32 v58, v56, v57
	v_mov_b64_e32 v[56:57], v[132:133]
	v_ashrrev_i32_e32 v69, 31, v68
	v_lshlrev_b64 v[60:61], 11, v[68:69]
	v_lshl_add_u64 v[56:57], v[56:57], 0, v[60:61]
	s_lshl_b32 s52, s61, 10
	v_lshl_add_u64 v[56:57], v[56:57], 0, s[52:53]
	v_lshlrev_b32_e32 v134, 1, v140
	v_lshl_add_u64 v[56:57], v[56:57], 0, v[134:135]
	v_add_co_u32_e32 v56, vcc, 0x15a00000, v56
	s_nop 1
	v_addc_co_u32_e32 v57, vcc, 0, v57, vcc
	global_store_dwordx2 v[56:57], v[58:59], off offset:32
	s_and_b64 vcc, exec, s[4:5]
	s_mov_b64 s[6:7], -1
	s_cbranch_vccnz .LBB0_471

.LBB0_723:
	global_load_dwordx4 v[56:59], v141, s[54:55] offset:128
	s_waitcnt vmcnt(0)
	v_add_f32_e32 v52, v52, v56
	v_mul_f32_e64 v56, |v52|, s48
	v_exp_f32_e32 v56, v56
	v_max_f32_e64 v52, -v52, 0
	v_add_f32_e32 v56, 1.0, v56
	v_log_f32_e32 v56, v56
	s_nop 0
	v_mul_f32_e32 v60, 0x3f317217, v56
	v_fma_f32 v60, v56, s49, -v60
	v_fmac_f32_e32 v60, 0x3377d1cf, v56
	v_fmac_f32_e32 v60, 0x3f317217, v56
	v_add_f32_e32 v52, v52, v60
	v_sub_f32_e32 v52, -0.5, v52
	v_mul_f32_e32 v52, 0x3fb8aa3b, v52
	v_exp_f32_e32 v56, v52
	s_nop 0
	v_cmp_ngt_f32_e32 vcc, s12, v56
	s_and_saveexec_b64 s[6:7], vcc
	s_xor_b64 s[6:7], exec, s[6:7]
	v_mul_f32_e32 v52, 0xbfb8aa3b, v56
	v_exp_f32_e32 v52, v52
	s_nop 0
	v_sub_f32_e32 v52, 1.0, v52
	s_andn2_saveexec_b64 s[6:7], s[6:7]
	v_fmamk_f32 v52, v56, 0xbd2aaaab, v160
	v_fma_f32 v52, -v56, v52, 0.5
	v_fma_f32 v52, -v56, v52, 1.0
	v_mul_f32_e32 v52, v56, v52
	s_or_b64 exec, exec, s[6:7]
	v_add_f32_e32 v53, v53, v57
	v_mul_f32_e64 v56, |v53|, s48
	v_exp_f32_e32 v56, v56
	v_max_f32_e64 v53, -v53, 0
	v_add_f32_e32 v56, 1.0, v56
	v_log_f32_e32 v56, v56
	s_nop 0
	v_mul_f32_e32 v57, 0x3f317217, v56
	v_fma_f32 v57, v56, s49, -v57
	v_fmac_f32_e32 v57, 0x3377d1cf, v56
	v_fmac_f32_e32 v57, 0x3f317217, v56
	v_add_f32_e32 v53, v53, v57
	v_sub_f32_e32 v53, -0.5, v53
	v_mul_f32_e32 v53, 0x3fb8aa3b, v53
	v_exp_f32_e32 v56, v53
	s_nop 0
	v_cmp_ngt_f32_e32 vcc, s12, v56
	s_and_saveexec_b64 s[6:7], vcc
	s_xor_b64 s[6:7], exec, s[6:7]
	v_mul_f32_e32 v53, 0xbfb8aa3b, v56
	v_exp_f32_e32 v53, v53
	s_nop 0
	v_sub_f32_e32 v53, 1.0, v53
	s_andn2_saveexec_b64 s[6:7], s[6:7]
	v_fmamk_f32 v53, v56, 0xbd2aaaab, v160
	v_fma_f32 v53, -v56, v53, 0.5
	v_fma_f32 v53, -v56, v53, 1.0
	v_mul_f32_e32 v53, v56, v53
	s_or_b64 exec, exec, s[6:7]
	v_add_f32_e32 v54, v54, v58
	v_mul_f32_e64 v56, |v54|, s48
	v_exp_f32_e32 v56, v56
	v_max_f32_e64 v54, -v54, 0
	v_add_f32_e32 v56, 1.0, v56
	v_log_f32_e32 v56, v56
	s_nop 0
	v_mul_f32_e32 v57, 0x3f317217, v56
	v_fma_f32 v57, v56, s49, -v57
	v_fmac_f32_e32 v57, 0x3377d1cf, v56
	v_fmac_f32_e32 v57, 0x3f317217, v56
	v_add_f32_e32 v54, v54, v57
	v_sub_f32_e32 v54, -0.5, v54
	v_mul_f32_e32 v54, 0x3fb8aa3b, v54
	v_exp_f32_e32 v56, v54
	s_nop 0
	v_cmp_ngt_f32_e32 vcc, s12, v56
	s_and_saveexec_b64 s[6:7], vcc
	s_xor_b64 s[6:7], exec, s[6:7]
	v_mul_f32_e32 v54, 0xbfb8aa3b, v56
	v_exp_f32_e32 v54, v54
	s_nop 0
	v_sub_f32_e32 v54, 1.0, v54
	s_andn2_saveexec_b64 s[6:7], s[6:7]
	v_fmamk_f32 v54, v56, 0xbd2aaaab, v160
	v_fma_f32 v54, -v56, v54, 0.5
	v_fma_f32 v54, -v56, v54, 1.0
	v_mul_f32_e32 v54, v56, v54
	s_or_b64 exec, exec, s[6:7]
	v_add_f32_e32 v55, v55, v59
	v_mul_f32_e64 v56, |v55|, s48
	v_exp_f32_e32 v56, v56
	v_max_f32_e64 v55, -v55, 0
	v_add_f32_e32 v56, 1.0, v56
	v_log_f32_e32 v56, v56
	s_nop 0
	v_mul_f32_e32 v57, 0x3f317217, v56
	v_fma_f32 v57, v56, s49, -v57
	v_fmac_f32_e32 v57, 0x3377d1cf, v56
	v_fmac_f32_e32 v57, 0x3f317217, v56
	v_add_f32_e32 v55, v55, v57
	v_sub_f32_e32 v55, -0.5, v55
	v_mul_f32_e32 v55, 0x3fb8aa3b, v55
	v_exp_f32_e32 v55, v55
	s_nop 0
	v_cmp_ngt_f32_e32 vcc, s12, v55
	s_and_saveexec_b64 s[6:7], vcc
	s_xor_b64 s[6:7], exec, s[6:7]
	v_mul_f32_e32 v55, 0xbfb8aa3b, v55
	v_exp_f32_e32 v55, v55
	s_nop 0
	v_sub_f32_e32 v56, 1.0, v55
	s_andn2_saveexec_b64 s[6:7], s[6:7]
	v_fmamk_f32 v56, v55, 0xbd2aaaab, v160
	v_fma_f32 v56, -v55, v56, 0.5
	v_fma_f32 v56, -v55, v56, 1.0
	v_mul_f32_e32 v56, v55, v56
	s_or_b64 exec, exec, s[6:7]
	v_cvt_pk_f16_f32 v55, v54, v56
	v_cvt_pk_f16_f32 v54, v52, v53
	v_mov_b64_e32 v[52:53], v[132:133]
	v_ashrrev_i32_e32 v69, 31, v68
	v_lshlrev_b64 v[56:57], 11, v[68:69]
	v_lshl_add_u64 v[52:53], v[52:53], 0, v[56:57]
	s_lshl_b32 s52, s61, 10
	v_lshl_add_u64 v[52:53], v[52:53], 0, s[52:53]
	v_lshlrev_b32_e32 v134, 1, v140
	v_lshl_add_u64 v[52:53], v[52:53], 0, v[134:135]
	v_add_co_u32_e32 v52, vcc, 0x15a00000, v52
	s_nop 1
	v_addc_co_u32_e32 v53, vcc, 0, v53, vcc
	global_store_dwordx2 v[52:53], v[54:55], off offset:64
	s_and_b64 vcc, exec, s[4:5]
	s_mov_b64 s[6:7], -1
	s_cbranch_vccnz .LBB0_473

.LBB0_745:
	global_load_dwordx4 v[52:55], v141, s[54:55] offset:192
	s_waitcnt vmcnt(0)
	v_add_f32_e32 v48, v48, v52
	v_mul_f32_e64 v52, |v48|, s48
	v_exp_f32_e32 v52, v52
	v_max_f32_e64 v48, -v48, 0
	v_add_f32_e32 v52, 1.0, v52
	v_log_f32_e32 v52, v52
	s_nop 0
	v_mul_f32_e32 v56, 0x3f317217, v52
	v_fma_f32 v56, v52, s49, -v56
	v_fmac_f32_e32 v56, 0x3377d1cf, v52
	v_fmac_f32_e32 v56, 0x3f317217, v52
	v_add_f32_e32 v48, v48, v56
	v_sub_f32_e32 v48, -0.5, v48
	v_mul_f32_e32 v48, 0x3fb8aa3b, v48
	v_exp_f32_e32 v52, v48
	s_nop 0
	v_cmp_ngt_f32_e32 vcc, s12, v52
	s_and_saveexec_b64 s[6:7], vcc
	s_xor_b64 s[6:7], exec, s[6:7]
	v_mul_f32_e32 v48, 0xbfb8aa3b, v52
	v_exp_f32_e32 v48, v48
	s_nop 0
	v_sub_f32_e32 v48, 1.0, v48
	s_andn2_saveexec_b64 s[6:7], s[6:7]
	v_fmamk_f32 v48, v52, 0xbd2aaaab, v160
	v_fma_f32 v48, -v52, v48, 0.5
	v_fma_f32 v48, -v52, v48, 1.0
	v_mul_f32_e32 v48, v52, v48
	s_or_b64 exec, exec, s[6:7]
	v_add_f32_e32 v49, v49, v53
	v_mul_f32_e64 v52, |v49|, s48
	v_exp_f32_e32 v52, v52
	v_max_f32_e64 v49, -v49, 0
	v_add_f32_e32 v52, 1.0, v52
	v_log_f32_e32 v52, v52
	s_nop 0
	v_mul_f32_e32 v53, 0x3f317217, v52
	v_fma_f32 v53, v52, s49, -v53
	v_fmac_f32_e32 v53, 0x3377d1cf, v52
	v_fmac_f32_e32 v53, 0x3f317217, v52
	v_add_f32_e32 v49, v49, v53
	v_sub_f32_e32 v49, -0.5, v49
	v_mul_f32_e32 v49, 0x3fb8aa3b, v49
	v_exp_f32_e32 v52, v49
	s_nop 0
	v_cmp_ngt_f32_e32 vcc, s12, v52
	s_and_saveexec_b64 s[6:7], vcc
	s_xor_b64 s[6:7], exec, s[6:7]
	v_mul_f32_e32 v49, 0xbfb8aa3b, v52
	v_exp_f32_e32 v49, v49
	s_nop 0
	v_sub_f32_e32 v49, 1.0, v49
	s_andn2_saveexec_b64 s[6:7], s[6:7]
	v_fmamk_f32 v49, v52, 0xbd2aaaab, v160
	v_fma_f32 v49, -v52, v49, 0.5
	v_fma_f32 v49, -v52, v49, 1.0
	v_mul_f32_e32 v49, v52, v49
	s_or_b64 exec, exec, s[6:7]
	v_add_f32_e32 v50, v50, v54
	v_mul_f32_e64 v52, |v50|, s48
	v_exp_f32_e32 v52, v52
	v_max_f32_e64 v50, -v50, 0
	v_add_f32_e32 v52, 1.0, v52
	v_log_f32_e32 v52, v52
	s_nop 0
	v_mul_f32_e32 v53, 0x3f317217, v52
	v_fma_f32 v53, v52, s49, -v53
	v_fmac_f32_e32 v53, 0x3377d1cf, v52
	v_fmac_f32_e32 v53, 0x3f317217, v52
	v_add_f32_e32 v50, v50, v53
	v_sub_f32_e32 v50, -0.5, v50
	v_mul_f32_e32 v50, 0x3fb8aa3b, v50
	v_exp_f32_e32 v52, v50
	s_nop 0
	v_cmp_ngt_f32_e32 vcc, s12, v52
	s_and_saveexec_b64 s[6:7], vcc
	s_xor_b64 s[6:7], exec, s[6:7]
	v_mul_f32_e32 v50, 0xbfb8aa3b, v52
	v_exp_f32_e32 v50, v50
	s_nop 0
	v_sub_f32_e32 v50, 1.0, v50
	s_andn2_saveexec_b64 s[6:7], s[6:7]
	v_fmamk_f32 v50, v52, 0xbd2aaaab, v160
	v_fma_f32 v50, -v52, v50, 0.5
	v_fma_f32 v50, -v52, v50, 1.0
	v_mul_f32_e32 v50, v52, v50
	s_or_b64 exec, exec, s[6:7]
	v_add_f32_e32 v51, v51, v55
	v_mul_f32_e64 v52, |v51|, s48
	v_exp_f32_e32 v52, v52
	v_max_f32_e64 v51, -v51, 0
	v_add_f32_e32 v52, 1.0, v52
	v_log_f32_e32 v52, v52
	s_nop 0
	v_mul_f32_e32 v53, 0x3f317217, v52
	v_fma_f32 v53, v52, s49, -v53
	v_fmac_f32_e32 v53, 0x3377d1cf, v52
	v_fmac_f32_e32 v53, 0x3f317217, v52
	v_add_f32_e32 v51, v51, v53
	v_sub_f32_e32 v51, -0.5, v51
	v_mul_f32_e32 v51, 0x3fb8aa3b, v51
	v_exp_f32_e32 v51, v51
	s_nop 0
	v_cmp_ngt_f32_e32 vcc, s12, v51
	s_and_saveexec_b64 s[6:7], vcc
	s_xor_b64 s[6:7], exec, s[6:7]
	v_mul_f32_e32 v51, 0xbfb8aa3b, v51
	v_exp_f32_e32 v51, v51
	s_nop 0
	v_sub_f32_e32 v52, 1.0, v51
	s_andn2_saveexec_b64 s[6:7], s[6:7]
	v_fmamk_f32 v52, v51, 0xbd2aaaab, v160
	v_fma_f32 v52, -v51, v52, 0.5
	v_fma_f32 v52, -v51, v52, 1.0
	v_mul_f32_e32 v52, v51, v52
	s_or_b64 exec, exec, s[6:7]
	v_cvt_pk_f16_f32 v51, v50, v52
	v_cvt_pk_f16_f32 v50, v48, v49
	v_mov_b64_e32 v[48:49], v[132:133]
	v_ashrrev_i32_e32 v69, 31, v68
	v_lshlrev_b64 v[52:53], 11, v[68:69]
	v_lshl_add_u64 v[48:49], v[48:49], 0, v[52:53]
	s_lshl_b32 s52, s61, 10
	v_lshl_add_u64 v[48:49], v[48:49], 0, s[52:53]
	v_lshlrev_b32_e32 v134, 1, v140
	v_lshl_add_u64 v[48:49], v[48:49], 0, v[134:135]
	v_add_co_u32_e32 v48, vcc, 0x15a00000, v48
	s_nop 1
	v_addc_co_u32_e32 v49, vcc, 0, v49, vcc
	global_store_dwordx2 v[48:49], v[50:51], off offset:96
	s_and_b64 vcc, exec, s[4:5]
	s_mov_b64 s[6:7], -1
	s_cbranch_vccnz .LBB0_475

.LBB0_767:
	global_load_dwordx4 v[48:51], v141, s[54:55] offset:256
	s_waitcnt vmcnt(0)
	v_add_f32_e32 v44, v44, v48
	v_mul_f32_e64 v48, |v44|, s48
	v_exp_f32_e32 v48, v48
	v_max_f32_e64 v44, -v44, 0
	v_add_f32_e32 v48, 1.0, v48
	v_log_f32_e32 v48, v48
	s_nop 0
	v_mul_f32_e32 v52, 0x3f317217, v48
	v_fma_f32 v52, v48, s49, -v52
	v_fmac_f32_e32 v52, 0x3377d1cf, v48
	v_fmac_f32_e32 v52, 0x3f317217, v48
	v_add_f32_e32 v44, v44, v52
	v_sub_f32_e32 v44, -0.5, v44
	v_mul_f32_e32 v44, 0x3fb8aa3b, v44
	v_exp_f32_e32 v48, v44
	s_nop 0
	v_cmp_ngt_f32_e32 vcc, s12, v48
	s_and_saveexec_b64 s[6:7], vcc
	s_xor_b64 s[6:7], exec, s[6:7]
	v_mul_f32_e32 v44, 0xbfb8aa3b, v48
	v_exp_f32_e32 v44, v44
	s_nop 0
	v_sub_f32_e32 v44, 1.0, v44
	s_andn2_saveexec_b64 s[6:7], s[6:7]
	v_fmamk_f32 v44, v48, 0xbd2aaaab, v160
	v_fma_f32 v44, -v48, v44, 0.5
	v_fma_f32 v44, -v48, v44, 1.0
	v_mul_f32_e32 v44, v48, v44
	s_or_b64 exec, exec, s[6:7]
	v_add_f32_e32 v45, v45, v49
	v_mul_f32_e64 v48, |v45|, s48
	v_exp_f32_e32 v48, v48
	v_max_f32_e64 v45, -v45, 0
	v_add_f32_e32 v48, 1.0, v48
	v_log_f32_e32 v48, v48
	s_nop 0
	v_mul_f32_e32 v49, 0x3f317217, v48
	v_fma_f32 v49, v48, s49, -v49
	v_fmac_f32_e32 v49, 0x3377d1cf, v48
	v_fmac_f32_e32 v49, 0x3f317217, v48
	v_add_f32_e32 v45, v45, v49
	v_sub_f32_e32 v45, -0.5, v45
	v_mul_f32_e32 v45, 0x3fb8aa3b, v45
	v_exp_f32_e32 v48, v45
	s_nop 0
	v_cmp_ngt_f32_e32 vcc, s12, v48
	s_and_saveexec_b64 s[6:7], vcc
	s_xor_b64 s[6:7], exec, s[6:7]
	v_mul_f32_e32 v45, 0xbfb8aa3b, v48
	v_exp_f32_e32 v45, v45
	s_nop 0
	v_sub_f32_e32 v45, 1.0, v45
	s_andn2_saveexec_b64 s[6:7], s[6:7]
	v_fmamk_f32 v45, v48, 0xbd2aaaab, v160
	v_fma_f32 v45, -v48, v45, 0.5
	v_fma_f32 v45, -v48, v45, 1.0
	v_mul_f32_e32 v45, v48, v45
	s_or_b64 exec, exec, s[6:7]
	v_add_f32_e32 v46, v46, v50
	v_mul_f32_e64 v48, |v46|, s48
	v_exp_f32_e32 v48, v48
	v_max_f32_e64 v46, -v46, 0
	v_add_f32_e32 v48, 1.0, v48
	v_log_f32_e32 v48, v48
	s_nop 0
	v_mul_f32_e32 v49, 0x3f317217, v48
	v_fma_f32 v49, v48, s49, -v49
	v_fmac_f32_e32 v49, 0x3377d1cf, v48
	v_fmac_f32_e32 v49, 0x3f317217, v48
	v_add_f32_e32 v46, v46, v49
	v_sub_f32_e32 v46, -0.5, v46
	v_mul_f32_e32 v46, 0x3fb8aa3b, v46
	v_exp_f32_e32 v48, v46
	s_nop 0
	v_cmp_ngt_f32_e32 vcc, s12, v48
	s_and_saveexec_b64 s[6:7], vcc
	s_xor_b64 s[6:7], exec, s[6:7]
	v_mul_f32_e32 v46, 0xbfb8aa3b, v48
	v_exp_f32_e32 v46, v46
	s_nop 0
	v_sub_f32_e32 v46, 1.0, v46
	s_andn2_saveexec_b64 s[6:7], s[6:7]
	v_fmamk_f32 v46, v48, 0xbd2aaaab, v160
	v_fma_f32 v46, -v48, v46, 0.5
	v_fma_f32 v46, -v48, v46, 1.0
	v_mul_f32_e32 v46, v48, v46
	s_or_b64 exec, exec, s[6:7]
	v_add_f32_e32 v47, v47, v51
	v_mul_f32_e64 v48, |v47|, s48
	v_exp_f32_e32 v48, v48
	v_max_f32_e64 v47, -v47, 0
	v_add_f32_e32 v48, 1.0, v48
	v_log_f32_e32 v48, v48
	s_nop 0
	v_mul_f32_e32 v49, 0x3f317217, v48
	v_fma_f32 v49, v48, s49, -v49
	v_fmac_f32_e32 v49, 0x3377d1cf, v48
	v_fmac_f32_e32 v49, 0x3f317217, v48
	v_add_f32_e32 v47, v47, v49
	v_sub_f32_e32 v47, -0.5, v47
	v_mul_f32_e32 v47, 0x3fb8aa3b, v47
	v_exp_f32_e32 v47, v47
	s_nop 0
	v_cmp_ngt_f32_e32 vcc, s12, v47
	s_and_saveexec_b64 s[6:7], vcc
	s_xor_b64 s[6:7], exec, s[6:7]
	v_mul_f32_e32 v47, 0xbfb8aa3b, v47
	v_exp_f32_e32 v47, v47
	s_nop 0
	v_sub_f32_e32 v48, 1.0, v47
	s_andn2_saveexec_b64 s[6:7], s[6:7]
	v_fmamk_f32 v48, v47, 0xbd2aaaab, v160
	v_fma_f32 v48, -v47, v48, 0.5
	v_fma_f32 v48, -v47, v48, 1.0
	v_mul_f32_e32 v48, v47, v48
	s_or_b64 exec, exec, s[6:7]
	v_cvt_pk_f16_f32 v47, v46, v48
	v_cvt_pk_f16_f32 v46, v44, v45
	v_mov_b64_e32 v[44:45], v[132:133]
	v_ashrrev_i32_e32 v69, 31, v68
	v_lshlrev_b64 v[48:49], 11, v[68:69]
	v_lshl_add_u64 v[44:45], v[44:45], 0, v[48:49]
	s_lshl_b32 s52, s61, 10
	v_lshl_add_u64 v[44:45], v[44:45], 0, s[52:53]
	v_lshlrev_b32_e32 v134, 1, v140
	v_lshl_add_u64 v[44:45], v[44:45], 0, v[134:135]
	v_add_co_u32_e32 v44, vcc, 0x15a00000, v44
	s_nop 1
	v_addc_co_u32_e32 v45, vcc, 0, v45, vcc
	global_store_dwordx2 v[44:45], v[46:47], off offset:128
	s_and_b64 vcc, exec, s[4:5]
	s_mov_b64 s[6:7], -1
	s_cbranch_vccnz .LBB0_477

.LBB0_789:
	global_load_dwordx4 v[44:47], v141, s[54:55] offset:320
	s_waitcnt vmcnt(0)
	v_add_f32_e32 v40, v40, v44
	v_mul_f32_e64 v44, |v40|, s48
	v_exp_f32_e32 v44, v44
	v_max_f32_e64 v40, -v40, 0
	v_add_f32_e32 v44, 1.0, v44
	v_log_f32_e32 v44, v44
	s_nop 0
	v_mul_f32_e32 v48, 0x3f317217, v44
	v_fma_f32 v48, v44, s49, -v48
	v_fmac_f32_e32 v48, 0x3377d1cf, v44
	v_fmac_f32_e32 v48, 0x3f317217, v44
	v_add_f32_e32 v40, v40, v48
	v_sub_f32_e32 v40, -0.5, v40
	v_mul_f32_e32 v40, 0x3fb8aa3b, v40
	v_exp_f32_e32 v44, v40
	s_nop 0
	v_cmp_ngt_f32_e32 vcc, s12, v44
	s_and_saveexec_b64 s[6:7], vcc
	s_xor_b64 s[6:7], exec, s[6:7]
	v_mul_f32_e32 v40, 0xbfb8aa3b, v44
	v_exp_f32_e32 v40, v40
	s_nop 0
	v_sub_f32_e32 v40, 1.0, v40
	s_andn2_saveexec_b64 s[6:7], s[6:7]
	v_fmamk_f32 v40, v44, 0xbd2aaaab, v160
	v_fma_f32 v40, -v44, v40, 0.5
	v_fma_f32 v40, -v44, v40, 1.0
	v_mul_f32_e32 v40, v44, v40
	s_or_b64 exec, exec, s[6:7]
	v_add_f32_e32 v41, v41, v45
	v_mul_f32_e64 v44, |v41|, s48
	v_exp_f32_e32 v44, v44
	v_max_f32_e64 v41, -v41, 0
	v_add_f32_e32 v44, 1.0, v44
	v_log_f32_e32 v44, v44
	s_nop 0
	v_mul_f32_e32 v45, 0x3f317217, v44
	v_fma_f32 v45, v44, s49, -v45
	v_fmac_f32_e32 v45, 0x3377d1cf, v44
	v_fmac_f32_e32 v45, 0x3f317217, v44
	v_add_f32_e32 v41, v41, v45
	v_sub_f32_e32 v41, -0.5, v41
	v_mul_f32_e32 v41, 0x3fb8aa3b, v41
	v_exp_f32_e32 v44, v41
	s_nop 0
	v_cmp_ngt_f32_e32 vcc, s12, v44
	s_and_saveexec_b64 s[6:7], vcc
	s_xor_b64 s[6:7], exec, s[6:7]
	v_mul_f32_e32 v41, 0xbfb8aa3b, v44
	v_exp_f32_e32 v41, v41
	s_nop 0
	v_sub_f32_e32 v41, 1.0, v41
	s_andn2_saveexec_b64 s[6:7], s[6:7]
	v_fmamk_f32 v41, v44, 0xbd2aaaab, v160
	v_fma_f32 v41, -v44, v41, 0.5
	v_fma_f32 v41, -v44, v41, 1.0
	v_mul_f32_e32 v41, v44, v41
	s_or_b64 exec, exec, s[6:7]
	v_add_f32_e32 v42, v42, v46
	v_mul_f32_e64 v44, |v42|, s48
	v_exp_f32_e32 v44, v44
	v_max_f32_e64 v42, -v42, 0
	v_add_f32_e32 v44, 1.0, v44
	v_log_f32_e32 v44, v44
	s_nop 0
	v_mul_f32_e32 v45, 0x3f317217, v44
	v_fma_f32 v45, v44, s49, -v45
	v_fmac_f32_e32 v45, 0x3377d1cf, v44
	v_fmac_f32_e32 v45, 0x3f317217, v44
	v_add_f32_e32 v42, v42, v45
	v_sub_f32_e32 v42, -0.5, v42
	v_mul_f32_e32 v42, 0x3fb8aa3b, v42
	v_exp_f32_e32 v44, v42
	s_nop 0
	v_cmp_ngt_f32_e32 vcc, s12, v44
	s_and_saveexec_b64 s[6:7], vcc
	s_xor_b64 s[6:7], exec, s[6:7]
	v_mul_f32_e32 v42, 0xbfb8aa3b, v44
	v_exp_f32_e32 v42, v42
	s_nop 0
	v_sub_f32_e32 v42, 1.0, v42
	s_andn2_saveexec_b64 s[6:7], s[6:7]
	v_fmamk_f32 v42, v44, 0xbd2aaaab, v160
	v_fma_f32 v42, -v44, v42, 0.5
	v_fma_f32 v42, -v44, v42, 1.0
	v_mul_f32_e32 v42, v44, v42
	s_or_b64 exec, exec, s[6:7]
	v_add_f32_e32 v43, v43, v47
	v_mul_f32_e64 v44, |v43|, s48
	v_exp_f32_e32 v44, v44
	v_max_f32_e64 v43, -v43, 0
	v_add_f32_e32 v44, 1.0, v44
	v_log_f32_e32 v44, v44
	s_nop 0
	v_mul_f32_e32 v45, 0x3f317217, v44
	v_fma_f32 v45, v44, s49, -v45
	v_fmac_f32_e32 v45, 0x3377d1cf, v44
	v_fmac_f32_e32 v45, 0x3f317217, v44
	v_add_f32_e32 v43, v43, v45
	v_sub_f32_e32 v43, -0.5, v43
	v_mul_f32_e32 v43, 0x3fb8aa3b, v43
	v_exp_f32_e32 v43, v43
	s_nop 0
	v_cmp_ngt_f32_e32 vcc, s12, v43
	s_and_saveexec_b64 s[6:7], vcc
	s_xor_b64 s[6:7], exec, s[6:7]
	v_mul_f32_e32 v43, 0xbfb8aa3b, v43
	v_exp_f32_e32 v43, v43
	s_nop 0
	v_sub_f32_e32 v44, 1.0, v43
	s_andn2_saveexec_b64 s[6:7], s[6:7]
	v_fmamk_f32 v44, v43, 0xbd2aaaab, v160
	v_fma_f32 v44, -v43, v44, 0.5
	v_fma_f32 v44, -v43, v44, 1.0
	v_mul_f32_e32 v44, v43, v44
	s_or_b64 exec, exec, s[6:7]
	v_cvt_pk_f16_f32 v43, v42, v44
	v_cvt_pk_f16_f32 v42, v40, v41
	v_mov_b64_e32 v[40:41], v[132:133]
	v_ashrrev_i32_e32 v69, 31, v68
	v_lshlrev_b64 v[44:45], 11, v[68:69]
	v_lshl_add_u64 v[40:41], v[40:41], 0, v[44:45]
	s_lshl_b32 s52, s61, 10
	v_lshl_add_u64 v[40:41], v[40:41], 0, s[52:53]
	v_lshlrev_b32_e32 v134, 1, v140
	v_lshl_add_u64 v[40:41], v[40:41], 0, v[134:135]
	v_add_co_u32_e32 v40, vcc, 0x15a00000, v40
	s_nop 1
	v_addc_co_u32_e32 v41, vcc, 0, v41, vcc
	global_store_dwordx2 v[40:41], v[42:43], off offset:160
	s_and_b64 vcc, exec, s[4:5]
	s_mov_b64 s[6:7], -1
	s_cbranch_vccnz .LBB0_479

.LBB0_811:
	global_load_dwordx4 v[40:43], v141, s[54:55] offset:384
	s_waitcnt vmcnt(0)
	v_add_f32_e32 v36, v36, v40
	v_mul_f32_e64 v40, |v36|, s48
	v_exp_f32_e32 v40, v40
	v_max_f32_e64 v36, -v36, 0
	v_add_f32_e32 v40, 1.0, v40
	v_log_f32_e32 v40, v40
	s_nop 0
	v_mul_f32_e32 v44, 0x3f317217, v40
	v_fma_f32 v44, v40, s49, -v44
	v_fmac_f32_e32 v44, 0x3377d1cf, v40
	v_fmac_f32_e32 v44, 0x3f317217, v40
	v_add_f32_e32 v36, v36, v44
	v_sub_f32_e32 v36, -0.5, v36
	v_mul_f32_e32 v36, 0x3fb8aa3b, v36
	v_exp_f32_e32 v40, v36
	s_nop 0
	v_cmp_ngt_f32_e32 vcc, s12, v40
	s_and_saveexec_b64 s[6:7], vcc
	s_xor_b64 s[6:7], exec, s[6:7]
	v_mul_f32_e32 v36, 0xbfb8aa3b, v40
	v_exp_f32_e32 v36, v36
	s_nop 0
	v_sub_f32_e32 v36, 1.0, v36
	s_andn2_saveexec_b64 s[6:7], s[6:7]
	v_fmamk_f32 v36, v40, 0xbd2aaaab, v160
	v_fma_f32 v36, -v40, v36, 0.5
	v_fma_f32 v36, -v40, v36, 1.0
	v_mul_f32_e32 v36, v40, v36
	s_or_b64 exec, exec, s[6:7]
	v_add_f32_e32 v37, v37, v41
	v_mul_f32_e64 v40, |v37|, s48
	v_exp_f32_e32 v40, v40
	v_max_f32_e64 v37, -v37, 0
	v_add_f32_e32 v40, 1.0, v40
	v_log_f32_e32 v40, v40
	s_nop 0
	v_mul_f32_e32 v41, 0x3f317217, v40
	v_fma_f32 v41, v40, s49, -v41
	v_fmac_f32_e32 v41, 0x3377d1cf, v40
	v_fmac_f32_e32 v41, 0x3f317217, v40
	v_add_f32_e32 v37, v37, v41
	v_sub_f32_e32 v37, -0.5, v37
	v_mul_f32_e32 v37, 0x3fb8aa3b, v37
	v_exp_f32_e32 v40, v37
	s_nop 0
	v_cmp_ngt_f32_e32 vcc, s12, v40
	s_and_saveexec_b64 s[6:7], vcc
	s_xor_b64 s[6:7], exec, s[6:7]
	v_mul_f32_e32 v37, 0xbfb8aa3b, v40
	v_exp_f32_e32 v37, v37
	s_nop 0
	v_sub_f32_e32 v37, 1.0, v37
	s_andn2_saveexec_b64 s[6:7], s[6:7]
	v_fmamk_f32 v37, v40, 0xbd2aaaab, v160
	v_fma_f32 v37, -v40, v37, 0.5
	v_fma_f32 v37, -v40, v37, 1.0
	v_mul_f32_e32 v37, v40, v37
	s_or_b64 exec, exec, s[6:7]
	v_add_f32_e32 v38, v38, v42
	v_mul_f32_e64 v40, |v38|, s48
	v_exp_f32_e32 v40, v40
	v_max_f32_e64 v38, -v38, 0
	v_add_f32_e32 v40, 1.0, v40
	v_log_f32_e32 v40, v40
	s_nop 0
	v_mul_f32_e32 v41, 0x3f317217, v40
	v_fma_f32 v41, v40, s49, -v41
	v_fmac_f32_e32 v41, 0x3377d1cf, v40
	v_fmac_f32_e32 v41, 0x3f317217, v40
	v_add_f32_e32 v38, v38, v41
	v_sub_f32_e32 v38, -0.5, v38
	v_mul_f32_e32 v38, 0x3fb8aa3b, v38
	v_exp_f32_e32 v40, v38
	s_nop 0
	v_cmp_ngt_f32_e32 vcc, s12, v40
	s_and_saveexec_b64 s[6:7], vcc
	s_xor_b64 s[6:7], exec, s[6:7]
	v_mul_f32_e32 v38, 0xbfb8aa3b, v40
	v_exp_f32_e32 v38, v38
	s_nop 0
	v_sub_f32_e32 v38, 1.0, v38
	s_andn2_saveexec_b64 s[6:7], s[6:7]
	v_fmamk_f32 v38, v40, 0xbd2aaaab, v160
	v_fma_f32 v38, -v40, v38, 0.5
	v_fma_f32 v38, -v40, v38, 1.0
	v_mul_f32_e32 v38, v40, v38
	s_or_b64 exec, exec, s[6:7]
	v_add_f32_e32 v39, v39, v43
	v_mul_f32_e64 v40, |v39|, s48
	v_exp_f32_e32 v40, v40
	v_max_f32_e64 v39, -v39, 0
	v_add_f32_e32 v40, 1.0, v40
	v_log_f32_e32 v40, v40
	s_nop 0
	v_mul_f32_e32 v41, 0x3f317217, v40
	v_fma_f32 v41, v40, s49, -v41
	v_fmac_f32_e32 v41, 0x3377d1cf, v40
	v_fmac_f32_e32 v41, 0x3f317217, v40
	v_add_f32_e32 v39, v39, v41
	v_sub_f32_e32 v39, -0.5, v39
	v_mul_f32_e32 v39, 0x3fb8aa3b, v39
	v_exp_f32_e32 v39, v39
	s_nop 0
	v_cmp_ngt_f32_e32 vcc, s12, v39
	s_and_saveexec_b64 s[6:7], vcc
	s_xor_b64 s[6:7], exec, s[6:7]
	v_mul_f32_e32 v39, 0xbfb8aa3b, v39
	v_exp_f32_e32 v39, v39
	s_nop 0
	v_sub_f32_e32 v40, 1.0, v39
	s_andn2_saveexec_b64 s[6:7], s[6:7]
	v_fmamk_f32 v40, v39, 0xbd2aaaab, v160
	v_fma_f32 v40, -v39, v40, 0.5
	v_fma_f32 v40, -v39, v40, 1.0
	v_mul_f32_e32 v40, v39, v40
	s_or_b64 exec, exec, s[6:7]
	v_cvt_pk_f16_f32 v39, v38, v40
	v_cvt_pk_f16_f32 v38, v36, v37
	v_mov_b64_e32 v[36:37], v[132:133]
	v_ashrrev_i32_e32 v69, 31, v68
	v_lshlrev_b64 v[40:41], 11, v[68:69]
	v_lshl_add_u64 v[36:37], v[36:37], 0, v[40:41]
	s_lshl_b32 s52, s61, 10
	v_lshl_add_u64 v[36:37], v[36:37], 0, s[52:53]
	v_lshlrev_b32_e32 v134, 1, v140
	v_lshl_add_u64 v[36:37], v[36:37], 0, v[134:135]
	v_add_co_u32_e32 v36, vcc, 0x15a00000, v36
	s_nop 1
	v_addc_co_u32_e32 v37, vcc, 0, v37, vcc
	global_store_dwordx2 v[36:37], v[38:39], off offset:192
	s_and_b64 vcc, exec, s[4:5]
	s_mov_b64 s[6:7], -1
	s_cbranch_vccnz .LBB0_481

.LBB0_833:
	global_load_dwordx4 v[36:39], v141, s[54:55] offset:448
	s_waitcnt vmcnt(0)
	v_add_f32_e32 v32, v32, v36
	v_mul_f32_e64 v36, |v32|, s48
	v_exp_f32_e32 v36, v36
	v_max_f32_e64 v32, -v32, 0
	v_add_f32_e32 v36, 1.0, v36
	v_log_f32_e32 v36, v36
	s_nop 0
	v_mul_f32_e32 v40, 0x3f317217, v36
	v_fma_f32 v40, v36, s49, -v40
	v_fmac_f32_e32 v40, 0x3377d1cf, v36
	v_fmac_f32_e32 v40, 0x3f317217, v36
	v_add_f32_e32 v32, v32, v40
	v_sub_f32_e32 v32, -0.5, v32
	v_mul_f32_e32 v32, 0x3fb8aa3b, v32
	v_exp_f32_e32 v36, v32
	s_nop 0
	v_cmp_ngt_f32_e32 vcc, s12, v36
	s_and_saveexec_b64 s[6:7], vcc
	s_xor_b64 s[6:7], exec, s[6:7]
	v_mul_f32_e32 v32, 0xbfb8aa3b, v36
	v_exp_f32_e32 v32, v32
	s_nop 0
	v_sub_f32_e32 v32, 1.0, v32
	s_andn2_saveexec_b64 s[6:7], s[6:7]
	v_fmamk_f32 v32, v36, 0xbd2aaaab, v160
	v_fma_f32 v32, -v36, v32, 0.5
	v_fma_f32 v32, -v36, v32, 1.0
	v_mul_f32_e32 v32, v36, v32
	s_or_b64 exec, exec, s[6:7]
	v_add_f32_e32 v33, v33, v37
	v_mul_f32_e64 v36, |v33|, s48
	v_exp_f32_e32 v36, v36
	v_max_f32_e64 v33, -v33, 0
	v_add_f32_e32 v36, 1.0, v36
	v_log_f32_e32 v36, v36
	s_nop 0
	v_mul_f32_e32 v37, 0x3f317217, v36
	v_fma_f32 v37, v36, s49, -v37
	v_fmac_f32_e32 v37, 0x3377d1cf, v36
	v_fmac_f32_e32 v37, 0x3f317217, v36
	v_add_f32_e32 v33, v33, v37
	v_sub_f32_e32 v33, -0.5, v33
	v_mul_f32_e32 v33, 0x3fb8aa3b, v33
	v_exp_f32_e32 v36, v33
	s_nop 0
	v_cmp_ngt_f32_e32 vcc, s12, v36
	s_and_saveexec_b64 s[6:7], vcc
	s_xor_b64 s[6:7], exec, s[6:7]
	v_mul_f32_e32 v33, 0xbfb8aa3b, v36
	v_exp_f32_e32 v33, v33
	s_nop 0
	v_sub_f32_e32 v33, 1.0, v33
	s_andn2_saveexec_b64 s[6:7], s[6:7]
	v_fmamk_f32 v33, v36, 0xbd2aaaab, v160
	v_fma_f32 v33, -v36, v33, 0.5
	v_fma_f32 v33, -v36, v33, 1.0
	v_mul_f32_e32 v33, v36, v33
	s_or_b64 exec, exec, s[6:7]
	v_add_f32_e32 v34, v34, v38
	v_mul_f32_e64 v36, |v34|, s48
	v_exp_f32_e32 v36, v36
	v_max_f32_e64 v34, -v34, 0
	v_add_f32_e32 v36, 1.0, v36
	v_log_f32_e32 v36, v36
	s_nop 0
	v_mul_f32_e32 v37, 0x3f317217, v36
	v_fma_f32 v37, v36, s49, -v37
	v_fmac_f32_e32 v37, 0x3377d1cf, v36
	v_fmac_f32_e32 v37, 0x3f317217, v36
	v_add_f32_e32 v34, v34, v37
	v_sub_f32_e32 v34, -0.5, v34
	v_mul_f32_e32 v34, 0x3fb8aa3b, v34
	v_exp_f32_e32 v36, v34
	s_nop 0
	v_cmp_ngt_f32_e32 vcc, s12, v36
	s_and_saveexec_b64 s[6:7], vcc
	s_xor_b64 s[6:7], exec, s[6:7]
	v_mul_f32_e32 v34, 0xbfb8aa3b, v36
	v_exp_f32_e32 v34, v34
	s_nop 0
	v_sub_f32_e32 v34, 1.0, v34
	s_andn2_saveexec_b64 s[6:7], s[6:7]
	v_fmamk_f32 v34, v36, 0xbd2aaaab, v160
	v_fma_f32 v34, -v36, v34, 0.5
	v_fma_f32 v34, -v36, v34, 1.0
	v_mul_f32_e32 v34, v36, v34
	s_or_b64 exec, exec, s[6:7]
	v_add_f32_e32 v35, v35, v39
	v_mul_f32_e64 v36, |v35|, s48
	v_exp_f32_e32 v36, v36
	v_max_f32_e64 v35, -v35, 0
	v_add_f32_e32 v36, 1.0, v36
	v_log_f32_e32 v36, v36
	s_nop 0
	v_mul_f32_e32 v37, 0x3f317217, v36
	v_fma_f32 v37, v36, s49, -v37
	v_fmac_f32_e32 v37, 0x3377d1cf, v36
	v_fmac_f32_e32 v37, 0x3f317217, v36
	v_add_f32_e32 v35, v35, v37
	v_sub_f32_e32 v35, -0.5, v35
	v_mul_f32_e32 v35, 0x3fb8aa3b, v35
	v_exp_f32_e32 v35, v35
	s_nop 0
	v_cmp_ngt_f32_e32 vcc, s12, v35
	s_and_saveexec_b64 s[6:7], vcc
	s_xor_b64 s[6:7], exec, s[6:7]
	v_mul_f32_e32 v35, 0xbfb8aa3b, v35
	v_exp_f32_e32 v35, v35
	s_nop 0
	v_sub_f32_e32 v36, 1.0, v35
	s_andn2_saveexec_b64 s[6:7], s[6:7]
	v_fmamk_f32 v36, v35, 0xbd2aaaab, v160
	v_fma_f32 v36, -v35, v36, 0.5
	v_fma_f32 v36, -v35, v36, 1.0
	v_mul_f32_e32 v36, v35, v36
	s_or_b64 exec, exec, s[6:7]
	v_cvt_pk_f16_f32 v35, v34, v36
	v_cvt_pk_f16_f32 v34, v32, v33
	v_mov_b64_e32 v[32:33], v[132:133]
	v_ashrrev_i32_e32 v69, 31, v68
	v_lshlrev_b64 v[36:37], 11, v[68:69]
	v_lshl_add_u64 v[32:33], v[32:33], 0, v[36:37]
	s_lshl_b32 s52, s61, 10
	v_lshl_add_u64 v[32:33], v[32:33], 0, s[52:53]
	v_lshlrev_b32_e32 v134, 1, v140
	v_lshl_add_u64 v[32:33], v[32:33], 0, v[134:135]
	v_add_co_u32_e32 v32, vcc, 0x15a00000, v32
	s_nop 1
	v_addc_co_u32_e32 v33, vcc, 0, v33, vcc
	global_store_dwordx2 v[32:33], v[34:35], off offset:224
	v_or_b32_e32 v36, 48, v138
	s_and_b64 vcc, exec, s[4:5]
	s_mov_b64 s[6:7], -1
	s_cbranch_vccnz .LBB0_483

.LBB0_855:
	global_load_dwordx4 v[32:35], v141, s[54:55]
	s_waitcnt vmcnt(0)
	v_add_f32_e32 v28, v28, v32
	v_mul_f32_e64 v32, |v28|, s48
	v_exp_f32_e32 v32, v32
	v_max_f32_e64 v28, -v28, 0
	v_add_f32_e32 v32, 1.0, v32
	v_log_f32_e32 v32, v32
	s_nop 0
	v_mul_f32_e32 v37, 0x3f317217, v32
	v_fma_f32 v37, v32, s49, -v37
	v_fmac_f32_e32 v37, 0x3377d1cf, v32
	v_fmac_f32_e32 v37, 0x3f317217, v32
	v_add_f32_e32 v28, v28, v37
	v_sub_f32_e32 v28, -0.5, v28
	v_mul_f32_e32 v28, 0x3fb8aa3b, v28
	v_exp_f32_e32 v32, v28
	s_nop 0
	v_cmp_ngt_f32_e32 vcc, s12, v32
	s_and_saveexec_b64 s[6:7], vcc
	s_xor_b64 s[6:7], exec, s[6:7]
	v_mul_f32_e32 v28, 0xbfb8aa3b, v32
	v_exp_f32_e32 v28, v28
	s_nop 0
	v_sub_f32_e32 v28, 1.0, v28
	s_andn2_saveexec_b64 s[6:7], s[6:7]
	v_fmamk_f32 v28, v32, 0xbd2aaaab, v160
	v_fma_f32 v28, -v32, v28, 0.5
	v_fma_f32 v28, -v32, v28, 1.0
	v_mul_f32_e32 v28, v32, v28
	s_or_b64 exec, exec, s[6:7]
	v_add_f32_e32 v29, v29, v33
	v_mul_f32_e64 v32, |v29|, s48
	v_exp_f32_e32 v32, v32
	v_max_f32_e64 v29, -v29, 0
	v_add_f32_e32 v32, 1.0, v32
	v_log_f32_e32 v32, v32
	s_nop 0
	v_mul_f32_e32 v33, 0x3f317217, v32
	v_fma_f32 v33, v32, s49, -v33
	v_fmac_f32_e32 v33, 0x3377d1cf, v32
	v_fmac_f32_e32 v33, 0x3f317217, v32
	v_add_f32_e32 v29, v29, v33
	v_sub_f32_e32 v29, -0.5, v29
	v_mul_f32_e32 v29, 0x3fb8aa3b, v29
	v_exp_f32_e32 v32, v29
	s_nop 0
	v_cmp_ngt_f32_e32 vcc, s12, v32
	s_and_saveexec_b64 s[6:7], vcc
	s_xor_b64 s[6:7], exec, s[6:7]
	v_mul_f32_e32 v29, 0xbfb8aa3b, v32
	v_exp_f32_e32 v29, v29
	s_nop 0
	v_sub_f32_e32 v29, 1.0, v29
	s_andn2_saveexec_b64 s[6:7], s[6:7]
	v_fmamk_f32 v29, v32, 0xbd2aaaab, v160
	v_fma_f32 v29, -v32, v29, 0.5
	v_fma_f32 v29, -v32, v29, 1.0
	v_mul_f32_e32 v29, v32, v29
	s_or_b64 exec, exec, s[6:7]
	v_add_f32_e32 v30, v30, v34
	v_mul_f32_e64 v32, |v30|, s48
	v_exp_f32_e32 v32, v32
	v_max_f32_e64 v30, -v30, 0
	v_add_f32_e32 v32, 1.0, v32
	v_log_f32_e32 v32, v32
	s_nop 0
	v_mul_f32_e32 v33, 0x3f317217, v32
	v_fma_f32 v33, v32, s49, -v33
	v_fmac_f32_e32 v33, 0x3377d1cf, v32
	v_fmac_f32_e32 v33, 0x3f317217, v32
	v_add_f32_e32 v30, v30, v33
	v_sub_f32_e32 v30, -0.5, v30
	v_mul_f32_e32 v30, 0x3fb8aa3b, v30
	v_exp_f32_e32 v32, v30
	s_nop 0
	v_cmp_ngt_f32_e32 vcc, s12, v32
	s_and_saveexec_b64 s[6:7], vcc
	s_xor_b64 s[6:7], exec, s[6:7]
	v_mul_f32_e32 v30, 0xbfb8aa3b, v32
	v_exp_f32_e32 v30, v30
	s_nop 0
	v_sub_f32_e32 v30, 1.0, v30
	s_andn2_saveexec_b64 s[6:7], s[6:7]
	v_fmamk_f32 v30, v32, 0xbd2aaaab, v160
	v_fma_f32 v30, -v32, v30, 0.5
	v_fma_f32 v30, -v32, v30, 1.0
	v_mul_f32_e32 v30, v32, v30
	s_or_b64 exec, exec, s[6:7]
	v_add_f32_e32 v31, v31, v35
	v_mul_f32_e64 v32, |v31|, s48
	v_exp_f32_e32 v32, v32
	v_max_f32_e64 v31, -v31, 0
	v_add_f32_e32 v32, 1.0, v32
	v_log_f32_e32 v32, v32
	s_nop 0
	v_mul_f32_e32 v33, 0x3f317217, v32
	v_fma_f32 v33, v32, s49, -v33
	v_fmac_f32_e32 v33, 0x3377d1cf, v32
	v_fmac_f32_e32 v33, 0x3f317217, v32
	v_add_f32_e32 v31, v31, v33
	v_sub_f32_e32 v31, -0.5, v31
	v_mul_f32_e32 v31, 0x3fb8aa3b, v31
	v_exp_f32_e32 v31, v31
	s_nop 0
	v_cmp_ngt_f32_e32 vcc, s12, v31
	s_and_saveexec_b64 s[6:7], vcc
	s_xor_b64 s[6:7], exec, s[6:7]
	v_mul_f32_e32 v31, 0xbfb8aa3b, v31
	v_exp_f32_e32 v31, v31
	s_nop 0
	v_sub_f32_e32 v32, 1.0, v31
	s_andn2_saveexec_b64 s[6:7], s[6:7]
	v_fmamk_f32 v32, v31, 0xbd2aaaab, v160
	v_fma_f32 v32, -v31, v32, 0.5
	v_fma_f32 v32, -v31, v32, 1.0
	v_mul_f32_e32 v32, v31, v32
	s_or_b64 exec, exec, s[6:7]
	v_cvt_pk_f16_f32 v31, v30, v32
	v_cvt_pk_f16_f32 v30, v28, v29
	v_mov_b64_e32 v[28:29], v[132:133]
	v_ashrrev_i32_e32 v37, 31, v36
	v_lshlrev_b64 v[32:33], 11, v[36:37]
	v_lshl_add_u64 v[28:29], v[28:29], 0, v[32:33]
	s_lshl_b32 s52, s61, 10
	v_lshl_add_u64 v[28:29], v[28:29], 0, s[52:53]
	v_lshlrev_b32_e32 v134, 1, v140
	v_lshl_add_u64 v[28:29], v[28:29], 0, v[134:135]
	v_add_co_u32_e32 v28, vcc, 0x15a00000, v28
	s_nop 1
	v_addc_co_u32_e32 v29, vcc, 0, v29, vcc
	global_store_dwordx2 v[28:29], v[30:31], off
	s_and_b64 vcc, exec, s[4:5]
	s_mov_b64 s[6:7], -1
	s_cbranch_vccnz .LBB0_485

.LBB0_877:
	global_load_dwordx4 v[28:31], v141, s[54:55] offset:64
	s_waitcnt vmcnt(0)
	v_add_f32_e32 v24, v24, v28
	v_mul_f32_e64 v28, |v24|, s48
	v_exp_f32_e32 v28, v28
	v_max_f32_e64 v24, -v24, 0
	v_add_f32_e32 v28, 1.0, v28
	v_log_f32_e32 v28, v28
	s_nop 0
	v_mul_f32_e32 v32, 0x3f317217, v28
	v_fma_f32 v32, v28, s49, -v32
	v_fmac_f32_e32 v32, 0x3377d1cf, v28
	v_fmac_f32_e32 v32, 0x3f317217, v28
	v_add_f32_e32 v24, v24, v32
	v_sub_f32_e32 v24, -0.5, v24
	v_mul_f32_e32 v24, 0x3fb8aa3b, v24
	v_exp_f32_e32 v28, v24
	s_nop 0
	v_cmp_ngt_f32_e32 vcc, s12, v28
	s_and_saveexec_b64 s[6:7], vcc
	s_xor_b64 s[6:7], exec, s[6:7]
	v_mul_f32_e32 v24, 0xbfb8aa3b, v28
	v_exp_f32_e32 v24, v24
	s_nop 0
	v_sub_f32_e32 v24, 1.0, v24
	s_andn2_saveexec_b64 s[6:7], s[6:7]
	v_fmamk_f32 v24, v28, 0xbd2aaaab, v160
	v_fma_f32 v24, -v28, v24, 0.5
	v_fma_f32 v24, -v28, v24, 1.0
	v_mul_f32_e32 v24, v28, v24
	s_or_b64 exec, exec, s[6:7]
	v_add_f32_e32 v25, v25, v29
	v_mul_f32_e64 v28, |v25|, s48
	v_exp_f32_e32 v28, v28
	v_max_f32_e64 v25, -v25, 0
	v_add_f32_e32 v28, 1.0, v28
	v_log_f32_e32 v28, v28
	s_nop 0
	v_mul_f32_e32 v29, 0x3f317217, v28
	v_fma_f32 v29, v28, s49, -v29
	v_fmac_f32_e32 v29, 0x3377d1cf, v28
	v_fmac_f32_e32 v29, 0x3f317217, v28
	v_add_f32_e32 v25, v25, v29
	v_sub_f32_e32 v25, -0.5, v25
	v_mul_f32_e32 v25, 0x3fb8aa3b, v25
	v_exp_f32_e32 v28, v25
	s_nop 0
	v_cmp_ngt_f32_e32 vcc, s12, v28
	s_and_saveexec_b64 s[6:7], vcc
	s_xor_b64 s[6:7], exec, s[6:7]
	v_mul_f32_e32 v25, 0xbfb8aa3b, v28
	v_exp_f32_e32 v25, v25
	s_nop 0
	v_sub_f32_e32 v25, 1.0, v25
	s_andn2_saveexec_b64 s[6:7], s[6:7]
	v_fmamk_f32 v25, v28, 0xbd2aaaab, v160
	v_fma_f32 v25, -v28, v25, 0.5
	v_fma_f32 v25, -v28, v25, 1.0
	v_mul_f32_e32 v25, v28, v25
	s_or_b64 exec, exec, s[6:7]
	v_add_f32_e32 v26, v26, v30
	v_mul_f32_e64 v28, |v26|, s48
	v_exp_f32_e32 v28, v28
	v_max_f32_e64 v26, -v26, 0
	v_add_f32_e32 v28, 1.0, v28
	v_log_f32_e32 v28, v28
	s_nop 0
	v_mul_f32_e32 v29, 0x3f317217, v28
	v_fma_f32 v29, v28, s49, -v29
	v_fmac_f32_e32 v29, 0x3377d1cf, v28
	v_fmac_f32_e32 v29, 0x3f317217, v28
	v_add_f32_e32 v26, v26, v29
	v_sub_f32_e32 v26, -0.5, v26
	v_mul_f32_e32 v26, 0x3fb8aa3b, v26
	v_exp_f32_e32 v28, v26
	s_nop 0
	v_cmp_ngt_f32_e32 vcc, s12, v28
	s_and_saveexec_b64 s[6:7], vcc
	s_xor_b64 s[6:7], exec, s[6:7]
	v_mul_f32_e32 v26, 0xbfb8aa3b, v28
	v_exp_f32_e32 v26, v26
	s_nop 0
	v_sub_f32_e32 v26, 1.0, v26
	s_andn2_saveexec_b64 s[6:7], s[6:7]
	v_fmamk_f32 v26, v28, 0xbd2aaaab, v160
	v_fma_f32 v26, -v28, v26, 0.5
	v_fma_f32 v26, -v28, v26, 1.0
	v_mul_f32_e32 v26, v28, v26
	s_or_b64 exec, exec, s[6:7]
	v_add_f32_e32 v27, v27, v31
	v_mul_f32_e64 v28, |v27|, s48
	v_exp_f32_e32 v28, v28
	v_max_f32_e64 v27, -v27, 0
	v_add_f32_e32 v28, 1.0, v28
	v_log_f32_e32 v28, v28
	s_nop 0
	v_mul_f32_e32 v29, 0x3f317217, v28
	v_fma_f32 v29, v28, s49, -v29
	v_fmac_f32_e32 v29, 0x3377d1cf, v28
	v_fmac_f32_e32 v29, 0x3f317217, v28
	v_add_f32_e32 v27, v27, v29
	v_sub_f32_e32 v27, -0.5, v27
	v_mul_f32_e32 v27, 0x3fb8aa3b, v27
	v_exp_f32_e32 v27, v27
	s_nop 0
	v_cmp_ngt_f32_e32 vcc, s12, v27
	s_and_saveexec_b64 s[6:7], vcc
	s_xor_b64 s[6:7], exec, s[6:7]
	v_mul_f32_e32 v27, 0xbfb8aa3b, v27
	v_exp_f32_e32 v27, v27
	s_nop 0
	v_sub_f32_e32 v28, 1.0, v27
	s_andn2_saveexec_b64 s[6:7], s[6:7]
	v_fmamk_f32 v28, v27, 0xbd2aaaab, v160
	v_fma_f32 v28, -v27, v28, 0.5
	v_fma_f32 v28, -v27, v28, 1.0
	v_mul_f32_e32 v28, v27, v28
	s_or_b64 exec, exec, s[6:7]
	v_cvt_pk_f16_f32 v27, v26, v28
	v_cvt_pk_f16_f32 v26, v24, v25
	v_mov_b64_e32 v[24:25], v[132:133]
	v_ashrrev_i32_e32 v37, 31, v36
	v_lshlrev_b64 v[28:29], 11, v[36:37]
	v_lshl_add_u64 v[24:25], v[24:25], 0, v[28:29]
	s_lshl_b32 s52, s61, 10
	v_lshl_add_u64 v[24:25], v[24:25], 0, s[52:53]
	v_lshlrev_b32_e32 v134, 1, v140
	v_lshl_add_u64 v[24:25], v[24:25], 0, v[134:135]
	v_add_co_u32_e32 v24, vcc, 0x15a00000, v24
	s_nop 1
	v_addc_co_u32_e32 v25, vcc, 0, v25, vcc
	global_store_dwordx2 v[24:25], v[26:27], off offset:32
	s_and_b64 vcc, exec, s[4:5]
	s_mov_b64 s[6:7], -1
	s_cbranch_vccnz .LBB0_487

.LBB0_899:
	global_load_dwordx4 v[24:27], v141, s[54:55] offset:128
	s_waitcnt vmcnt(0)
	v_add_f32_e32 v20, v20, v24
	v_mul_f32_e64 v24, |v20|, s48
	v_exp_f32_e32 v24, v24
	v_max_f32_e64 v20, -v20, 0
	v_add_f32_e32 v24, 1.0, v24
	v_log_f32_e32 v24, v24
	s_nop 0
	v_mul_f32_e32 v28, 0x3f317217, v24
	v_fma_f32 v28, v24, s49, -v28
	v_fmac_f32_e32 v28, 0x3377d1cf, v24
	v_fmac_f32_e32 v28, 0x3f317217, v24
	v_add_f32_e32 v20, v20, v28
	v_sub_f32_e32 v20, -0.5, v20
	v_mul_f32_e32 v20, 0x3fb8aa3b, v20
	v_exp_f32_e32 v24, v20
	s_nop 0
	v_cmp_ngt_f32_e32 vcc, s12, v24
	s_and_saveexec_b64 s[6:7], vcc
	s_xor_b64 s[6:7], exec, s[6:7]
	v_mul_f32_e32 v20, 0xbfb8aa3b, v24
	v_exp_f32_e32 v20, v20
	s_nop 0
	v_sub_f32_e32 v20, 1.0, v20
	s_andn2_saveexec_b64 s[6:7], s[6:7]
	v_fmamk_f32 v20, v24, 0xbd2aaaab, v160
	v_fma_f32 v20, -v24, v20, 0.5
	v_fma_f32 v20, -v24, v20, 1.0
	v_mul_f32_e32 v20, v24, v20
	s_or_b64 exec, exec, s[6:7]
	v_add_f32_e32 v21, v21, v25
	v_mul_f32_e64 v24, |v21|, s48
	v_exp_f32_e32 v24, v24
	v_max_f32_e64 v21, -v21, 0
	v_add_f32_e32 v24, 1.0, v24
	v_log_f32_e32 v24, v24
	s_nop 0
	v_mul_f32_e32 v25, 0x3f317217, v24
	v_fma_f32 v25, v24, s49, -v25
	v_fmac_f32_e32 v25, 0x3377d1cf, v24
	v_fmac_f32_e32 v25, 0x3f317217, v24
	v_add_f32_e32 v21, v21, v25
	v_sub_f32_e32 v21, -0.5, v21
	v_mul_f32_e32 v21, 0x3fb8aa3b, v21
	v_exp_f32_e32 v24, v21
	s_nop 0
	v_cmp_ngt_f32_e32 vcc, s12, v24
	s_and_saveexec_b64 s[6:7], vcc
	s_xor_b64 s[6:7], exec, s[6:7]
	v_mul_f32_e32 v21, 0xbfb8aa3b, v24
	v_exp_f32_e32 v21, v21
	s_nop 0
	v_sub_f32_e32 v21, 1.0, v21
	s_andn2_saveexec_b64 s[6:7], s[6:7]
	v_fmamk_f32 v21, v24, 0xbd2aaaab, v160
	v_fma_f32 v21, -v24, v21, 0.5
	v_fma_f32 v21, -v24, v21, 1.0
	v_mul_f32_e32 v21, v24, v21
	s_or_b64 exec, exec, s[6:7]
	v_add_f32_e32 v22, v22, v26
	v_mul_f32_e64 v24, |v22|, s48
	v_exp_f32_e32 v24, v24
	v_max_f32_e64 v22, -v22, 0
	v_add_f32_e32 v24, 1.0, v24
	v_log_f32_e32 v24, v24
	s_nop 0
	v_mul_f32_e32 v25, 0x3f317217, v24
	v_fma_f32 v25, v24, s49, -v25
	v_fmac_f32_e32 v25, 0x3377d1cf, v24
	v_fmac_f32_e32 v25, 0x3f317217, v24
	v_add_f32_e32 v22, v22, v25
	v_sub_f32_e32 v22, -0.5, v22
	v_mul_f32_e32 v22, 0x3fb8aa3b, v22
	v_exp_f32_e32 v24, v22
	s_nop 0
	v_cmp_ngt_f32_e32 vcc, s12, v24
	s_and_saveexec_b64 s[6:7], vcc
	s_xor_b64 s[6:7], exec, s[6:7]
	v_mul_f32_e32 v22, 0xbfb8aa3b, v24
	v_exp_f32_e32 v22, v22
	s_nop 0
	v_sub_f32_e32 v22, 1.0, v22
	s_andn2_saveexec_b64 s[6:7], s[6:7]
	v_fmamk_f32 v22, v24, 0xbd2aaaab, v160
	v_fma_f32 v22, -v24, v22, 0.5
	v_fma_f32 v22, -v24, v22, 1.0
	v_mul_f32_e32 v22, v24, v22
	s_or_b64 exec, exec, s[6:7]
	v_add_f32_e32 v23, v23, v27
	v_mul_f32_e64 v24, |v23|, s48
	v_exp_f32_e32 v24, v24
	v_max_f32_e64 v23, -v23, 0
	v_add_f32_e32 v24, 1.0, v24
	v_log_f32_e32 v24, v24
	s_nop 0
	v_mul_f32_e32 v25, 0x3f317217, v24
	v_fma_f32 v25, v24, s49, -v25
	v_fmac_f32_e32 v25, 0x3377d1cf, v24
	v_fmac_f32_e32 v25, 0x3f317217, v24
	v_add_f32_e32 v23, v23, v25
	v_sub_f32_e32 v23, -0.5, v23
	v_mul_f32_e32 v23, 0x3fb8aa3b, v23
	v_exp_f32_e32 v23, v23
	s_nop 0
	v_cmp_ngt_f32_e32 vcc, s12, v23
	s_and_saveexec_b64 s[6:7], vcc
	s_xor_b64 s[6:7], exec, s[6:7]
	v_mul_f32_e32 v23, 0xbfb8aa3b, v23
	v_exp_f32_e32 v23, v23
	s_nop 0
	v_sub_f32_e32 v24, 1.0, v23
	s_andn2_saveexec_b64 s[6:7], s[6:7]
	v_fmamk_f32 v24, v23, 0xbd2aaaab, v160
	v_fma_f32 v24, -v23, v24, 0.5
	v_fma_f32 v24, -v23, v24, 1.0
	v_mul_f32_e32 v24, v23, v24
	s_or_b64 exec, exec, s[6:7]
	v_cvt_pk_f16_f32 v23, v22, v24
	v_cvt_pk_f16_f32 v22, v20, v21
	v_mov_b64_e32 v[20:21], v[132:133]
	v_ashrrev_i32_e32 v37, 31, v36
	v_lshlrev_b64 v[24:25], 11, v[36:37]
	v_lshl_add_u64 v[20:21], v[20:21], 0, v[24:25]
	s_lshl_b32 s52, s61, 10
	v_lshl_add_u64 v[20:21], v[20:21], 0, s[52:53]
	v_lshlrev_b32_e32 v134, 1, v140
	v_lshl_add_u64 v[20:21], v[20:21], 0, v[134:135]
	v_add_co_u32_e32 v20, vcc, 0x15a00000, v20
	s_nop 1
	v_addc_co_u32_e32 v21, vcc, 0, v21, vcc
	global_store_dwordx2 v[20:21], v[22:23], off offset:64
	s_and_b64 vcc, exec, s[4:5]
	s_mov_b64 s[6:7], -1
	s_cbranch_vccnz .LBB0_489

.LBB0_921:
	global_load_dwordx4 v[20:23], v141, s[54:55] offset:192
	s_waitcnt vmcnt(0)
	v_add_f32_e32 v16, v16, v20
	v_mul_f32_e64 v20, |v16|, s48
	v_exp_f32_e32 v20, v20
	v_max_f32_e64 v16, -v16, 0
	v_add_f32_e32 v20, 1.0, v20
	v_log_f32_e32 v20, v20
	s_nop 0
	v_mul_f32_e32 v24, 0x3f317217, v20
	v_fma_f32 v24, v20, s49, -v24
	v_fmac_f32_e32 v24, 0x3377d1cf, v20
	v_fmac_f32_e32 v24, 0x3f317217, v20
	v_add_f32_e32 v16, v16, v24
	v_sub_f32_e32 v16, -0.5, v16
	v_mul_f32_e32 v16, 0x3fb8aa3b, v16
	v_exp_f32_e32 v20, v16
	s_nop 0
	v_cmp_ngt_f32_e32 vcc, s12, v20
	s_and_saveexec_b64 s[6:7], vcc
	s_xor_b64 s[6:7], exec, s[6:7]
	v_mul_f32_e32 v16, 0xbfb8aa3b, v20
	v_exp_f32_e32 v16, v16
	s_nop 0
	v_sub_f32_e32 v16, 1.0, v16
	s_andn2_saveexec_b64 s[6:7], s[6:7]
	v_fmamk_f32 v16, v20, 0xbd2aaaab, v160
	v_fma_f32 v16, -v20, v16, 0.5
	v_fma_f32 v16, -v20, v16, 1.0
	v_mul_f32_e32 v16, v20, v16
	s_or_b64 exec, exec, s[6:7]
	v_add_f32_e32 v17, v17, v21
	v_mul_f32_e64 v20, |v17|, s48
	v_exp_f32_e32 v20, v20
	v_max_f32_e64 v17, -v17, 0
	v_add_f32_e32 v20, 1.0, v20
	v_log_f32_e32 v20, v20
	s_nop 0
	v_mul_f32_e32 v21, 0x3f317217, v20
	v_fma_f32 v21, v20, s49, -v21
	v_fmac_f32_e32 v21, 0x3377d1cf, v20
	v_fmac_f32_e32 v21, 0x3f317217, v20
	v_add_f32_e32 v17, v17, v21
	v_sub_f32_e32 v17, -0.5, v17
	v_mul_f32_e32 v17, 0x3fb8aa3b, v17
	v_exp_f32_e32 v20, v17
	s_nop 0
	v_cmp_ngt_f32_e32 vcc, s12, v20
	s_and_saveexec_b64 s[6:7], vcc
	s_xor_b64 s[6:7], exec, s[6:7]
	v_mul_f32_e32 v17, 0xbfb8aa3b, v20
	v_exp_f32_e32 v17, v17
	s_nop 0
	v_sub_f32_e32 v17, 1.0, v17
	s_andn2_saveexec_b64 s[6:7], s[6:7]
	v_fmamk_f32 v17, v20, 0xbd2aaaab, v160
	v_fma_f32 v17, -v20, v17, 0.5
	v_fma_f32 v17, -v20, v17, 1.0
	v_mul_f32_e32 v17, v20, v17
	s_or_b64 exec, exec, s[6:7]
	v_add_f32_e32 v18, v18, v22
	v_mul_f32_e64 v20, |v18|, s48
	v_exp_f32_e32 v20, v20
	v_max_f32_e64 v18, -v18, 0
	v_add_f32_e32 v20, 1.0, v20
	v_log_f32_e32 v20, v20
	s_nop 0
	v_mul_f32_e32 v21, 0x3f317217, v20
	v_fma_f32 v21, v20, s49, -v21
	v_fmac_f32_e32 v21, 0x3377d1cf, v20
	v_fmac_f32_e32 v21, 0x3f317217, v20
	v_add_f32_e32 v18, v18, v21
	v_sub_f32_e32 v18, -0.5, v18
	v_mul_f32_e32 v18, 0x3fb8aa3b, v18
	v_exp_f32_e32 v20, v18
	s_nop 0
	v_cmp_ngt_f32_e32 vcc, s12, v20
	s_and_saveexec_b64 s[6:7], vcc
	s_xor_b64 s[6:7], exec, s[6:7]
	v_mul_f32_e32 v18, 0xbfb8aa3b, v20
	v_exp_f32_e32 v18, v18
	s_nop 0
	v_sub_f32_e32 v18, 1.0, v18
	s_andn2_saveexec_b64 s[6:7], s[6:7]
	v_fmamk_f32 v18, v20, 0xbd2aaaab, v160
	v_fma_f32 v18, -v20, v18, 0.5
	v_fma_f32 v18, -v20, v18, 1.0
	v_mul_f32_e32 v18, v20, v18
	s_or_b64 exec, exec, s[6:7]
	v_add_f32_e32 v19, v19, v23
	v_mul_f32_e64 v20, |v19|, s48
	v_exp_f32_e32 v20, v20
	v_max_f32_e64 v19, -v19, 0
	v_add_f32_e32 v20, 1.0, v20
	v_log_f32_e32 v20, v20
	s_nop 0
	v_mul_f32_e32 v21, 0x3f317217, v20
	v_fma_f32 v21, v20, s49, -v21
	v_fmac_f32_e32 v21, 0x3377d1cf, v20
	v_fmac_f32_e32 v21, 0x3f317217, v20
	v_add_f32_e32 v19, v19, v21
	v_sub_f32_e32 v19, -0.5, v19
	v_mul_f32_e32 v19, 0x3fb8aa3b, v19
	v_exp_f32_e32 v19, v19
	s_nop 0
	v_cmp_ngt_f32_e32 vcc, s12, v19
	s_and_saveexec_b64 s[6:7], vcc
	s_xor_b64 s[6:7], exec, s[6:7]
	v_mul_f32_e32 v19, 0xbfb8aa3b, v19
	v_exp_f32_e32 v19, v19
	s_nop 0
	v_sub_f32_e32 v20, 1.0, v19
	s_andn2_saveexec_b64 s[6:7], s[6:7]
	v_fmamk_f32 v20, v19, 0xbd2aaaab, v160
	v_fma_f32 v20, -v19, v20, 0.5
	v_fma_f32 v20, -v19, v20, 1.0
	v_mul_f32_e32 v20, v19, v20
	s_or_b64 exec, exec, s[6:7]
	v_cvt_pk_f16_f32 v19, v18, v20
	v_cvt_pk_f16_f32 v18, v16, v17
	v_mov_b64_e32 v[16:17], v[132:133]
	v_ashrrev_i32_e32 v37, 31, v36
	v_lshlrev_b64 v[20:21], 11, v[36:37]
	v_lshl_add_u64 v[16:17], v[16:17], 0, v[20:21]
	s_lshl_b32 s52, s61, 10
	v_lshl_add_u64 v[16:17], v[16:17], 0, s[52:53]
	v_lshlrev_b32_e32 v134, 1, v140
	v_lshl_add_u64 v[16:17], v[16:17], 0, v[134:135]
	v_add_co_u32_e32 v16, vcc, 0x15a00000, v16
	s_nop 1
	v_addc_co_u32_e32 v17, vcc, 0, v17, vcc
	global_store_dwordx2 v[16:17], v[18:19], off offset:96
	s_and_b64 vcc, exec, s[4:5]
	s_mov_b64 s[6:7], -1
	s_cbranch_vccnz .LBB0_491

.LBB0_943:
	global_load_dwordx4 v[16:19], v141, s[54:55] offset:256
	s_waitcnt vmcnt(0)
	v_add_f32_e32 v12, v12, v16
	v_mul_f32_e64 v16, |v12|, s48
	v_exp_f32_e32 v16, v16
	v_max_f32_e64 v12, -v12, 0
	v_add_f32_e32 v16, 1.0, v16
	v_log_f32_e32 v16, v16
	s_nop 0
	v_mul_f32_e32 v20, 0x3f317217, v16
	v_fma_f32 v20, v16, s49, -v20
	v_fmac_f32_e32 v20, 0x3377d1cf, v16
	v_fmac_f32_e32 v20, 0x3f317217, v16
	v_add_f32_e32 v12, v12, v20
	v_sub_f32_e32 v12, -0.5, v12
	v_mul_f32_e32 v12, 0x3fb8aa3b, v12
	v_exp_f32_e32 v16, v12
	s_nop 0
	v_cmp_ngt_f32_e32 vcc, s12, v16
	s_and_saveexec_b64 s[6:7], vcc
	s_xor_b64 s[6:7], exec, s[6:7]
	v_mul_f32_e32 v12, 0xbfb8aa3b, v16
	v_exp_f32_e32 v12, v12
	s_nop 0
	v_sub_f32_e32 v12, 1.0, v12
	s_andn2_saveexec_b64 s[6:7], s[6:7]
	v_fmamk_f32 v12, v16, 0xbd2aaaab, v160
	v_fma_f32 v12, -v16, v12, 0.5
	v_fma_f32 v12, -v16, v12, 1.0
	v_mul_f32_e32 v12, v16, v12
	s_or_b64 exec, exec, s[6:7]
	v_add_f32_e32 v13, v13, v17
	v_mul_f32_e64 v16, |v13|, s48
	v_exp_f32_e32 v16, v16
	v_max_f32_e64 v13, -v13, 0
	v_add_f32_e32 v16, 1.0, v16
	v_log_f32_e32 v16, v16
	s_nop 0
	v_mul_f32_e32 v17, 0x3f317217, v16
	v_fma_f32 v17, v16, s49, -v17
	v_fmac_f32_e32 v17, 0x3377d1cf, v16
	v_fmac_f32_e32 v17, 0x3f317217, v16
	v_add_f32_e32 v13, v13, v17
	v_sub_f32_e32 v13, -0.5, v13
	v_mul_f32_e32 v13, 0x3fb8aa3b, v13
	v_exp_f32_e32 v16, v13
	s_nop 0
	v_cmp_ngt_f32_e32 vcc, s12, v16
	s_and_saveexec_b64 s[6:7], vcc
	s_xor_b64 s[6:7], exec, s[6:7]
	v_mul_f32_e32 v13, 0xbfb8aa3b, v16
	v_exp_f32_e32 v13, v13
	s_nop 0
	v_sub_f32_e32 v13, 1.0, v13
	s_andn2_saveexec_b64 s[6:7], s[6:7]
	v_fmamk_f32 v13, v16, 0xbd2aaaab, v160
	v_fma_f32 v13, -v16, v13, 0.5
	v_fma_f32 v13, -v16, v13, 1.0
	v_mul_f32_e32 v13, v16, v13
	s_or_b64 exec, exec, s[6:7]
	v_add_f32_e32 v14, v14, v18
	v_mul_f32_e64 v16, |v14|, s48
	v_exp_f32_e32 v16, v16
	v_max_f32_e64 v14, -v14, 0
	v_add_f32_e32 v16, 1.0, v16
	v_log_f32_e32 v16, v16
	s_nop 0
	v_mul_f32_e32 v17, 0x3f317217, v16
	v_fma_f32 v17, v16, s49, -v17
	v_fmac_f32_e32 v17, 0x3377d1cf, v16
	v_fmac_f32_e32 v17, 0x3f317217, v16
	v_add_f32_e32 v14, v14, v17
	v_sub_f32_e32 v14, -0.5, v14
	v_mul_f32_e32 v14, 0x3fb8aa3b, v14
	v_exp_f32_e32 v16, v14
	s_nop 0
	v_cmp_ngt_f32_e32 vcc, s12, v16
	s_and_saveexec_b64 s[6:7], vcc
	s_xor_b64 s[6:7], exec, s[6:7]
	v_mul_f32_e32 v14, 0xbfb8aa3b, v16
	v_exp_f32_e32 v14, v14
	s_nop 0
	v_sub_f32_e32 v14, 1.0, v14
	s_andn2_saveexec_b64 s[6:7], s[6:7]
	v_fmamk_f32 v14, v16, 0xbd2aaaab, v160
	v_fma_f32 v14, -v16, v14, 0.5
	v_fma_f32 v14, -v16, v14, 1.0
	v_mul_f32_e32 v14, v16, v14
	s_or_b64 exec, exec, s[6:7]
	v_add_f32_e32 v15, v15, v19
	v_mul_f32_e64 v16, |v15|, s48
	v_exp_f32_e32 v16, v16
	v_max_f32_e64 v15, -v15, 0
	v_add_f32_e32 v16, 1.0, v16
	v_log_f32_e32 v16, v16
	s_nop 0
	v_mul_f32_e32 v17, 0x3f317217, v16
	v_fma_f32 v17, v16, s49, -v17
	v_fmac_f32_e32 v17, 0x3377d1cf, v16
	v_fmac_f32_e32 v17, 0x3f317217, v16
	v_add_f32_e32 v15, v15, v17
	v_sub_f32_e32 v15, -0.5, v15
	v_mul_f32_e32 v15, 0x3fb8aa3b, v15
	v_exp_f32_e32 v15, v15
	s_nop 0
	v_cmp_ngt_f32_e32 vcc, s12, v15
	s_and_saveexec_b64 s[6:7], vcc
	s_xor_b64 s[6:7], exec, s[6:7]
	v_mul_f32_e32 v15, 0xbfb8aa3b, v15
	v_exp_f32_e32 v15, v15
	s_nop 0
	v_sub_f32_e32 v16, 1.0, v15
	s_andn2_saveexec_b64 s[6:7], s[6:7]
	v_fmamk_f32 v16, v15, 0xbd2aaaab, v160
	v_fma_f32 v16, -v15, v16, 0.5
	v_fma_f32 v16, -v15, v16, 1.0
	v_mul_f32_e32 v16, v15, v16
	s_or_b64 exec, exec, s[6:7]
	v_cvt_pk_f16_f32 v15, v14, v16
	v_cvt_pk_f16_f32 v14, v12, v13
	v_mov_b64_e32 v[12:13], v[132:133]
	v_ashrrev_i32_e32 v37, 31, v36
	v_lshlrev_b64 v[16:17], 11, v[36:37]
	v_lshl_add_u64 v[12:13], v[12:13], 0, v[16:17]
	s_lshl_b32 s52, s61, 10
	v_lshl_add_u64 v[12:13], v[12:13], 0, s[52:53]
	v_lshlrev_b32_e32 v134, 1, v140
	v_lshl_add_u64 v[12:13], v[12:13], 0, v[134:135]
	v_add_co_u32_e32 v12, vcc, 0x15a00000, v12
	s_nop 1
	v_addc_co_u32_e32 v13, vcc, 0, v13, vcc
	global_store_dwordx2 v[12:13], v[14:15], off offset:128
	s_and_b64 vcc, exec, s[4:5]
	s_mov_b64 s[6:7], -1
	s_cbranch_vccnz .LBB0_493

.LBB0_965:
	global_load_dwordx4 v[12:15], v141, s[54:55] offset:320
	s_waitcnt vmcnt(0)
	v_add_f32_e32 v8, v8, v12
	v_mul_f32_e64 v12, |v8|, s48
	v_exp_f32_e32 v12, v12
	v_max_f32_e64 v8, -v8, 0
	v_add_f32_e32 v12, 1.0, v12
	v_log_f32_e32 v12, v12
	s_nop 0
	v_mul_f32_e32 v16, 0x3f317217, v12
	v_fma_f32 v16, v12, s49, -v16
	v_fmac_f32_e32 v16, 0x3377d1cf, v12
	v_fmac_f32_e32 v16, 0x3f317217, v12
	v_add_f32_e32 v8, v8, v16
	v_sub_f32_e32 v8, -0.5, v8
	v_mul_f32_e32 v8, 0x3fb8aa3b, v8
	v_exp_f32_e32 v12, v8
	s_nop 0
	v_cmp_ngt_f32_e32 vcc, s12, v12
	s_and_saveexec_b64 s[6:7], vcc
	s_xor_b64 s[6:7], exec, s[6:7]
	v_mul_f32_e32 v8, 0xbfb8aa3b, v12
	v_exp_f32_e32 v8, v8
	s_nop 0
	v_sub_f32_e32 v8, 1.0, v8
	s_andn2_saveexec_b64 s[6:7], s[6:7]
	v_fmamk_f32 v8, v12, 0xbd2aaaab, v160
	v_fma_f32 v8, -v12, v8, 0.5
	v_fma_f32 v8, -v12, v8, 1.0
	v_mul_f32_e32 v8, v12, v8
	s_or_b64 exec, exec, s[6:7]
	v_add_f32_e32 v9, v9, v13
	v_mul_f32_e64 v12, |v9|, s48
	v_exp_f32_e32 v12, v12
	v_max_f32_e64 v9, -v9, 0
	v_add_f32_e32 v12, 1.0, v12
	v_log_f32_e32 v12, v12
	s_nop 0
	v_mul_f32_e32 v13, 0x3f317217, v12
	v_fma_f32 v13, v12, s49, -v13
	v_fmac_f32_e32 v13, 0x3377d1cf, v12
	v_fmac_f32_e32 v13, 0x3f317217, v12
	v_add_f32_e32 v9, v9, v13
	v_sub_f32_e32 v9, -0.5, v9
	v_mul_f32_e32 v9, 0x3fb8aa3b, v9
	v_exp_f32_e32 v12, v9
	s_nop 0
	v_cmp_ngt_f32_e32 vcc, s12, v12
	s_and_saveexec_b64 s[6:7], vcc
	s_xor_b64 s[6:7], exec, s[6:7]
	v_mul_f32_e32 v9, 0xbfb8aa3b, v12
	v_exp_f32_e32 v9, v9
	s_nop 0
	v_sub_f32_e32 v9, 1.0, v9
	s_andn2_saveexec_b64 s[6:7], s[6:7]
	v_fmamk_f32 v9, v12, 0xbd2aaaab, v160
	v_fma_f32 v9, -v12, v9, 0.5
	v_fma_f32 v9, -v12, v9, 1.0
	v_mul_f32_e32 v9, v12, v9
	s_or_b64 exec, exec, s[6:7]
	v_add_f32_e32 v10, v10, v14
	v_mul_f32_e64 v12, |v10|, s48
	v_exp_f32_e32 v12, v12
	v_max_f32_e64 v10, -v10, 0
	v_add_f32_e32 v12, 1.0, v12
	v_log_f32_e32 v12, v12
	s_nop 0
	v_mul_f32_e32 v13, 0x3f317217, v12
	v_fma_f32 v13, v12, s49, -v13
	v_fmac_f32_e32 v13, 0x3377d1cf, v12
	v_fmac_f32_e32 v13, 0x3f317217, v12
	v_add_f32_e32 v10, v10, v13
	v_sub_f32_e32 v10, -0.5, v10
	v_mul_f32_e32 v10, 0x3fb8aa3b, v10
	v_exp_f32_e32 v12, v10
	s_nop 0
	v_cmp_ngt_f32_e32 vcc, s12, v12
	s_and_saveexec_b64 s[6:7], vcc
	s_xor_b64 s[6:7], exec, s[6:7]
	v_mul_f32_e32 v10, 0xbfb8aa3b, v12
	v_exp_f32_e32 v10, v10
	s_nop 0
	v_sub_f32_e32 v10, 1.0, v10
	s_andn2_saveexec_b64 s[6:7], s[6:7]
	v_fmamk_f32 v10, v12, 0xbd2aaaab, v160
	v_fma_f32 v10, -v12, v10, 0.5
	v_fma_f32 v10, -v12, v10, 1.0
	v_mul_f32_e32 v10, v12, v10
	s_or_b64 exec, exec, s[6:7]
	v_add_f32_e32 v11, v11, v15
	v_mul_f32_e64 v12, |v11|, s48
	v_exp_f32_e32 v12, v12
	v_max_f32_e64 v11, -v11, 0
	v_add_f32_e32 v12, 1.0, v12
	v_log_f32_e32 v12, v12
	s_nop 0
	v_mul_f32_e32 v13, 0x3f317217, v12
	v_fma_f32 v13, v12, s49, -v13
	v_fmac_f32_e32 v13, 0x3377d1cf, v12
	v_fmac_f32_e32 v13, 0x3f317217, v12
	v_add_f32_e32 v11, v11, v13
	v_sub_f32_e32 v11, -0.5, v11
	v_mul_f32_e32 v11, 0x3fb8aa3b, v11
	v_exp_f32_e32 v11, v11
	s_nop 0
	v_cmp_ngt_f32_e32 vcc, s12, v11
	s_and_saveexec_b64 s[6:7], vcc
	s_xor_b64 s[6:7], exec, s[6:7]
	v_mul_f32_e32 v11, 0xbfb8aa3b, v11
	v_exp_f32_e32 v11, v11
	s_nop 0
	v_sub_f32_e32 v12, 1.0, v11
	s_andn2_saveexec_b64 s[6:7], s[6:7]
	v_fmamk_f32 v12, v11, 0xbd2aaaab, v160
	v_fma_f32 v12, -v11, v12, 0.5
	v_fma_f32 v12, -v11, v12, 1.0
	v_mul_f32_e32 v12, v11, v12
	s_or_b64 exec, exec, s[6:7]
	v_cvt_pk_f16_f32 v11, v10, v12
	v_cvt_pk_f16_f32 v10, v8, v9
	v_mov_b64_e32 v[8:9], v[132:133]
	v_ashrrev_i32_e32 v37, 31, v36
	v_lshlrev_b64 v[12:13], 11, v[36:37]
	v_lshl_add_u64 v[8:9], v[8:9], 0, v[12:13]
	s_lshl_b32 s52, s61, 10
	v_lshl_add_u64 v[8:9], v[8:9], 0, s[52:53]
	v_lshlrev_b32_e32 v134, 1, v140
	v_lshl_add_u64 v[8:9], v[8:9], 0, v[134:135]
	v_add_co_u32_e32 v8, vcc, 0x15a00000, v8
	s_nop 1
	v_addc_co_u32_e32 v9, vcc, 0, v9, vcc
	global_store_dwordx2 v[8:9], v[10:11], off offset:160
	s_and_b64 vcc, exec, s[4:5]
	s_mov_b64 s[6:7], -1
	s_cbranch_vccnz .LBB0_495

.LBB0_987:
	global_load_dwordx4 v[8:11], v141, s[54:55] offset:384
	s_waitcnt vmcnt(0)
	v_add_f32_e32 v4, v4, v8
	v_mul_f32_e64 v8, |v4|, s48
	v_exp_f32_e32 v8, v8
	v_max_f32_e64 v4, -v4, 0
	v_add_f32_e32 v8, 1.0, v8
	v_log_f32_e32 v8, v8
	s_nop 0
	v_mul_f32_e32 v12, 0x3f317217, v8
	v_fma_f32 v12, v8, s49, -v12
	v_fmac_f32_e32 v12, 0x3377d1cf, v8
	v_fmac_f32_e32 v12, 0x3f317217, v8
	v_add_f32_e32 v4, v4, v12
	v_sub_f32_e32 v4, -0.5, v4
	v_mul_f32_e32 v4, 0x3fb8aa3b, v4
	v_exp_f32_e32 v8, v4
	s_nop 0
	v_cmp_ngt_f32_e32 vcc, s12, v8
	s_and_saveexec_b64 s[6:7], vcc
	s_xor_b64 s[6:7], exec, s[6:7]
	v_mul_f32_e32 v4, 0xbfb8aa3b, v8
	v_exp_f32_e32 v4, v4
	s_nop 0
	v_sub_f32_e32 v4, 1.0, v4
	s_andn2_saveexec_b64 s[6:7], s[6:7]
	v_fmamk_f32 v4, v8, 0xbd2aaaab, v160
	v_fma_f32 v4, -v8, v4, 0.5
	v_fma_f32 v4, -v8, v4, 1.0
	v_mul_f32_e32 v4, v8, v4
	s_or_b64 exec, exec, s[6:7]
	v_add_f32_e32 v5, v5, v9
	v_mul_f32_e64 v8, |v5|, s48
	v_exp_f32_e32 v8, v8
	v_max_f32_e64 v5, -v5, 0
	v_add_f32_e32 v8, 1.0, v8
	v_log_f32_e32 v8, v8
	s_nop 0
	v_mul_f32_e32 v9, 0x3f317217, v8
	v_fma_f32 v9, v8, s49, -v9
	v_fmac_f32_e32 v9, 0x3377d1cf, v8
	v_fmac_f32_e32 v9, 0x3f317217, v8
	v_add_f32_e32 v5, v5, v9
	v_sub_f32_e32 v5, -0.5, v5
	v_mul_f32_e32 v5, 0x3fb8aa3b, v5
	v_exp_f32_e32 v8, v5
	s_nop 0
	v_cmp_ngt_f32_e32 vcc, s12, v8
	s_and_saveexec_b64 s[6:7], vcc
	s_xor_b64 s[6:7], exec, s[6:7]
	v_mul_f32_e32 v5, 0xbfb8aa3b, v8
	v_exp_f32_e32 v5, v5
	s_nop 0
	v_sub_f32_e32 v5, 1.0, v5
	s_andn2_saveexec_b64 s[6:7], s[6:7]
	v_fmamk_f32 v5, v8, 0xbd2aaaab, v160
	v_fma_f32 v5, -v8, v5, 0.5
	v_fma_f32 v5, -v8, v5, 1.0
	v_mul_f32_e32 v5, v8, v5
	s_or_b64 exec, exec, s[6:7]
	v_add_f32_e32 v6, v6, v10
	v_mul_f32_e64 v8, |v6|, s48
	v_exp_f32_e32 v8, v8
	v_max_f32_e64 v6, -v6, 0
	v_add_f32_e32 v8, 1.0, v8
	v_log_f32_e32 v8, v8
	s_nop 0
	v_mul_f32_e32 v9, 0x3f317217, v8
	v_fma_f32 v9, v8, s49, -v9
	v_fmac_f32_e32 v9, 0x3377d1cf, v8
	v_fmac_f32_e32 v9, 0x3f317217, v8
	v_add_f32_e32 v6, v6, v9
	v_sub_f32_e32 v6, -0.5, v6
	v_mul_f32_e32 v6, 0x3fb8aa3b, v6
	v_exp_f32_e32 v8, v6
	s_nop 0
	v_cmp_ngt_f32_e32 vcc, s12, v8
	s_and_saveexec_b64 s[6:7], vcc
	s_xor_b64 s[6:7], exec, s[6:7]
	v_mul_f32_e32 v6, 0xbfb8aa3b, v8
	v_exp_f32_e32 v6, v6
	s_nop 0
	v_sub_f32_e32 v6, 1.0, v6
	s_andn2_saveexec_b64 s[6:7], s[6:7]
	v_fmamk_f32 v6, v8, 0xbd2aaaab, v160
	v_fma_f32 v6, -v8, v6, 0.5
	v_fma_f32 v6, -v8, v6, 1.0
	v_mul_f32_e32 v6, v8, v6
	s_or_b64 exec, exec, s[6:7]
	v_add_f32_e32 v7, v7, v11
	v_mul_f32_e64 v8, |v7|, s48
	v_exp_f32_e32 v8, v8
	v_max_f32_e64 v7, -v7, 0
	v_add_f32_e32 v8, 1.0, v8
	v_log_f32_e32 v8, v8
	s_nop 0
	v_mul_f32_e32 v9, 0x3f317217, v8
	v_fma_f32 v9, v8, s49, -v9
	v_fmac_f32_e32 v9, 0x3377d1cf, v8
	v_fmac_f32_e32 v9, 0x3f317217, v8
	v_add_f32_e32 v7, v7, v9
	v_sub_f32_e32 v7, -0.5, v7
	v_mul_f32_e32 v7, 0x3fb8aa3b, v7
	v_exp_f32_e32 v7, v7
	s_nop 0
	v_cmp_ngt_f32_e32 vcc, s12, v7
	s_and_saveexec_b64 s[6:7], vcc
	s_xor_b64 s[6:7], exec, s[6:7]
	v_mul_f32_e32 v7, 0xbfb8aa3b, v7
	v_exp_f32_e32 v7, v7
	s_nop 0
	v_sub_f32_e32 v8, 1.0, v7
	s_andn2_saveexec_b64 s[6:7], s[6:7]
	v_fmamk_f32 v8, v7, 0xbd2aaaab, v160
	v_fma_f32 v8, -v7, v8, 0.5
	v_fma_f32 v8, -v7, v8, 1.0
	v_mul_f32_e32 v8, v7, v8
	s_or_b64 exec, exec, s[6:7]
	v_cvt_pk_f16_f32 v7, v6, v8
	v_cvt_pk_f16_f32 v6, v4, v5
	v_mov_b64_e32 v[4:5], v[132:133]
	v_ashrrev_i32_e32 v37, 31, v36
	v_lshlrev_b64 v[8:9], 11, v[36:37]
	v_lshl_add_u64 v[4:5], v[4:5], 0, v[8:9]
	s_lshl_b32 s52, s61, 10
	v_lshl_add_u64 v[4:5], v[4:5], 0, s[52:53]
	v_lshlrev_b32_e32 v134, 1, v140
	v_lshl_add_u64 v[4:5], v[4:5], 0, v[134:135]
	v_add_co_u32_e32 v4, vcc, 0x15a00000, v4
	s_nop 1
	v_addc_co_u32_e32 v5, vcc, 0, v5, vcc
	global_store_dwordx2 v[4:5], v[6:7], off offset:192
	s_and_b64 vcc, exec, s[4:5]
	s_mov_b64 s[4:5], -1
	s_cbranch_vccnz .LBB0_497

.LBB0_1009:
	global_load_dwordx4 v[4:7], v141, s[54:55] offset:448
	s_waitcnt vmcnt(0)
	v_add_f32_e32 v0, v0, v4
	v_mul_f32_e64 v4, |v0|, s48
	v_exp_f32_e32 v4, v4
	v_max_f32_e64 v0, -v0, 0
	v_add_f32_e32 v4, 1.0, v4
	v_log_f32_e32 v4, v4
	s_nop 0
	v_mul_f32_e32 v8, 0x3f317217, v4
	v_fma_f32 v8, v4, s49, -v8
	v_fmac_f32_e32 v8, 0x3377d1cf, v4
	v_fmac_f32_e32 v8, 0x3f317217, v4
	v_add_f32_e32 v0, v0, v8
	v_sub_f32_e32 v0, -0.5, v0
	v_mul_f32_e32 v0, 0x3fb8aa3b, v0
	v_exp_f32_e32 v4, v0
	s_nop 0
	v_cmp_ngt_f32_e32 vcc, s12, v4
	s_and_saveexec_b64 s[4:5], vcc
	s_xor_b64 s[4:5], exec, s[4:5]
	v_mul_f32_e32 v0, 0xbfb8aa3b, v4
	v_exp_f32_e32 v0, v0
	s_nop 0
	v_sub_f32_e32 v0, 1.0, v0
	s_andn2_saveexec_b64 s[4:5], s[4:5]
	v_fmamk_f32 v0, v4, 0xbd2aaaab, v160
	v_fma_f32 v0, -v4, v0, 0.5
	v_fma_f32 v0, -v4, v0, 1.0
	v_mul_f32_e32 v0, v4, v0
	s_or_b64 exec, exec, s[4:5]
	v_add_f32_e32 v1, v1, v5
	v_mul_f32_e64 v4, |v1|, s48
	v_exp_f32_e32 v4, v4
	v_max_f32_e64 v1, -v1, 0
	v_add_f32_e32 v4, 1.0, v4
	v_log_f32_e32 v4, v4
	s_nop 0
	v_mul_f32_e32 v5, 0x3f317217, v4
	v_fma_f32 v5, v4, s49, -v5
	v_fmac_f32_e32 v5, 0x3377d1cf, v4
	v_fmac_f32_e32 v5, 0x3f317217, v4
	v_add_f32_e32 v1, v1, v5
	v_sub_f32_e32 v1, -0.5, v1
	v_mul_f32_e32 v1, 0x3fb8aa3b, v1
	v_exp_f32_e32 v4, v1
	s_nop 0
	v_cmp_ngt_f32_e32 vcc, s12, v4
	s_and_saveexec_b64 s[4:5], vcc
	s_xor_b64 s[4:5], exec, s[4:5]
	v_mul_f32_e32 v1, 0xbfb8aa3b, v4
	v_exp_f32_e32 v1, v1
	s_nop 0
	v_sub_f32_e32 v1, 1.0, v1
	s_andn2_saveexec_b64 s[4:5], s[4:5]
	v_fmamk_f32 v1, v4, 0xbd2aaaab, v160
	v_fma_f32 v1, -v4, v1, 0.5
	v_fma_f32 v1, -v4, v1, 1.0
	v_mul_f32_e32 v1, v4, v1
	s_or_b64 exec, exec, s[4:5]
	v_add_f32_e32 v2, v2, v6
	v_mul_f32_e64 v4, |v2|, s48
	v_exp_f32_e32 v4, v4
	v_max_f32_e64 v2, -v2, 0
	v_add_f32_e32 v4, 1.0, v4
	v_log_f32_e32 v4, v4
	s_nop 0
	v_mul_f32_e32 v5, 0x3f317217, v4
	v_fma_f32 v5, v4, s49, -v5
	v_fmac_f32_e32 v5, 0x3377d1cf, v4
	v_fmac_f32_e32 v5, 0x3f317217, v4
	v_add_f32_e32 v2, v2, v5
	v_sub_f32_e32 v2, -0.5, v2
	v_mul_f32_e32 v2, 0x3fb8aa3b, v2
	v_exp_f32_e32 v4, v2
	s_nop 0
	v_cmp_ngt_f32_e32 vcc, s12, v4
	s_and_saveexec_b64 s[4:5], vcc
	s_xor_b64 s[4:5], exec, s[4:5]
	v_mul_f32_e32 v2, 0xbfb8aa3b, v4
	v_exp_f32_e32 v2, v2
	s_nop 0
	v_sub_f32_e32 v2, 1.0, v2
	s_andn2_saveexec_b64 s[4:5], s[4:5]
	v_fmamk_f32 v2, v4, 0xbd2aaaab, v160
	v_fma_f32 v2, -v4, v2, 0.5
	v_fma_f32 v2, -v4, v2, 1.0
	v_mul_f32_e32 v2, v4, v2
	s_or_b64 exec, exec, s[4:5]
	v_add_f32_e32 v3, v3, v7
	v_mul_f32_e64 v4, |v3|, s48
	v_exp_f32_e32 v4, v4
	v_max_f32_e64 v3, -v3, 0
	v_add_f32_e32 v4, 1.0, v4
	v_log_f32_e32 v4, v4
	s_nop 0
	v_mul_f32_e32 v5, 0x3f317217, v4
	v_fma_f32 v5, v4, s49, -v5
	v_fmac_f32_e32 v5, 0x3377d1cf, v4
	v_fmac_f32_e32 v5, 0x3f317217, v4
	v_add_f32_e32 v3, v3, v5
	v_sub_f32_e32 v3, -0.5, v3
	v_mul_f32_e32 v3, 0x3fb8aa3b, v3
	v_exp_f32_e32 v3, v3
	s_nop 0
	v_cmp_ngt_f32_e32 vcc, s12, v3
	s_and_saveexec_b64 s[4:5], vcc
	s_xor_b64 s[4:5], exec, s[4:5]
	v_mul_f32_e32 v3, 0xbfb8aa3b, v3
	v_exp_f32_e32 v3, v3
	s_nop 0
	v_sub_f32_e32 v4, 1.0, v3
	s_andn2_saveexec_b64 s[4:5], s[4:5]
	s_cbranch_execz .LBB0_244
	v_fmamk_f32 v4, v3, 0xbd2aaaab, v160
	v_fma_f32 v4, -v3, v4, 0.5
	v_fma_f32 v4, -v3, v4, 1.0
	v_mul_f32_e32 v4, v3, v4
	s_branch .LBB0_244

.LBB0_1104:
	v_mov_b64_e32 v[0:1], v[132:133]
	v_mov_b64_e32 v[2:3], v[132:133]
	v_mov_b32_e32 v4, v154
	s_lshl_b32 s6, s93, 8
	v_lshrrev_b32_e32 v6, 4, v4
	v_lshl_add_u64 v[0:1], v[0:1], 0, s[22:23]
	v_ashrrev_i32_e32 v7, 3, v4
	v_xor_b32_e32 v8, v6, v4
	v_add_u32_e32 v9, s6, v7
	v_lshlrev_b32_e32 v8, 4, v8
	s_lshl_b32 s7, s89, 8
	v_mad_i64_i32 v[0:1], s[4:5], v9, s50, v[0:1]
	v_and_b32_e32 v134, 0x70, v8
	v_lshl_add_u64 v[128:129], v[0:1], 0, v[134:135]
	v_add_u32_e32 v0, s7, v7
	v_ashrrev_i32_e32 v1, 31, v0
	v_lshl_add_u64 v[2:3], v[2:3], 0, s[16:17]
	v_lshlrev_b64 v[0:1], 11, v[0:1]
	v_ashrrev_i32_e32 v5, 6, v4
	v_lshl_add_u64 v[0:1], v[2:3], 0, v[0:1]
	v_lshl_add_u64 v[130:131], v[0:1], 0, v[134:135]
	v_ashrrev_i32_e32 v0, 1, v4
	v_and_b32_e32 v134, 0xffffffc0, v0
	v_lshlrev_b32_e32 v0, 7, v5
	v_and_b32_e32 v143, 0x80, v0
	v_lshlrev_b32_e32 v0, 10, v5
	v_add_u32_e32 v144, 0, v0
	v_add_u32_e32 v145, s79, v0
	v_readfirstlane_b32 s4, v144
	s_mov_b32 m0, s4
	v_readfirstlane_b32 s4, v145
	global_load_lds_dwordx4 v[128:129], off
	s_mov_b32 m0, s4
	s_mov_b64 s[4:5], 0x6c000
	v_add_u32_e32 v146, 0x2000, v144
	v_lshl_add_u64 v[0:1], v[128:129], 0, s[4:5]
	v_readfirstlane_b32 s4, v146
	global_load_lds_dwordx4 v[130:131], off
	s_mov_b32 m0, s4
	s_mov_b64 s[4:5], 0x20000
	v_add_u32_e32 v147, 0x2000, v145
	global_load_lds_dwordx4 v[0:1], off
	v_lshl_add_u64 v[0:1], v[130:131], 0, s[4:5]
	v_readfirstlane_b32 s4, v147
	s_mov_b32 m0, s4
	s_mov_b64 s[4:5], 0xd8000
	v_add_u32_e32 v148, 0x4000, v144
	global_load_lds_dwordx4 v[0:1], off
	v_lshl_add_u64 v[0:1], v[128:129], 0, s[4:5]
	v_readfirstlane_b32 s4, v148
	s_mov_b32 m0, s4
	s_mov_b64 s[4:5], 0x40000
	v_add_u32_e32 v149, 0x4000, v145
	global_load_lds_dwordx4 v[0:1], off
	v_lshl_add_u64 v[0:1], v[130:131], 0, s[4:5]
	v_readfirstlane_b32 s4, v149
	s_mov_b32 m0, s4
	s_mov_b64 s[4:5], 0x144000
	v_add_u32_e32 v151, 0x6000, v144
	global_load_lds_dwordx4 v[0:1], off
	v_lshl_add_u64 v[0:1], v[128:129], 0, s[4:5]
	v_readfirstlane_b32 s4, v151
	s_mov_b32 m0, s4
	s_mov_b64 s[4:5], 0x60000
	v_add_u32_e32 v152, 0x6000, v145
	global_load_lds_dwordx4 v[0:1], off
	v_lshl_add_u64 v[0:1], v[130:131], 0, s[4:5]
	v_readfirstlane_b32 s4, v152
	s_mov_b32 m0, s4
	v_bfe_u32 v150, v4, 4, 2
	global_load_lds_dwordx4 v[0:1], off
	s_mov_b64 s[100:101], 0x80
	v_lshl_add_u64 v[240:241], v[128:129], 0, s[100:101]
	s_mov_b64 s[100:101], 0x6c080
	v_lshl_add_u64 v[242:243], v[128:129], 0, s[100:101]
	s_mov_b64 s[100:101], 0xd8080
	v_lshl_add_u64 v[244:245], v[128:129], 0, s[100:101]
	s_mov_b64 s[100:101], 0x144080
	v_lshl_add_u64 v[246:247], v[128:129], 0, s[100:101]
	s_mov_b64 s[100:101], 0x80
	v_lshl_add_u64 v[138:139], v[130:131], 0, s[100:101]
	s_mov_b64 s[100:101], 0x20080
	v_lshl_add_u64 v[140:141], v[130:131], 0, s[100:101]
	s_mov_b64 s[100:101], 0x40080
	v_lshl_add_u64 v[250:251], v[130:131], 0, s[100:101]
	s_mov_b64 s[100:101], 0x60080
	v_lshl_add_u64 v[252:253], v[130:131], 0, s[100:101]
	v_readfirstlane_b32 s100, v144
	v_readfirstlane_b32 s101, v145
	s_nop 3
	s_add_u32 m0, s100, 0x8000
	s_nop 0
	global_load_lds_dwordx4 v[240:241], off
	v_lshl_add_u64 v[240:241], v[240:241], 0, s[34:35]
	s_add_u32 m0, s100, 0xa000
	s_nop 0
	global_load_lds_dwordx4 v[242:243], off
	v_lshl_add_u64 v[242:243], v[242:243], 0, s[34:35]
	s_add_u32 m0, s100, 0xc000
	s_nop 0
	global_load_lds_dwordx4 v[244:245], off
	v_lshl_add_u64 v[244:245], v[244:245], 0, s[34:35]
	s_add_u32 m0, s100, 0xe000
	s_nop 0
	global_load_lds_dwordx4 v[246:247], off
	v_lshl_add_u64 v[246:247], v[246:247], 0, s[34:35]
	s_add_u32 m0, s101, 0x8000
	s_nop 0
	global_load_lds_dwordx4 v[138:139], off
	v_lshl_add_u64 v[138:139], v[138:139], 0, s[34:35]
	s_add_u32 m0, s101, 0xa000
	s_nop 0
	global_load_lds_dwordx4 v[140:141], off
	v_lshl_add_u64 v[140:141], v[140:141], 0, s[34:35]
	s_add_u32 m0, s101, 0xc000
	s_nop 0
	global_load_lds_dwordx4 v[250:251], off
	v_lshl_add_u64 v[250:251], v[250:251], 0, s[34:35]
	s_add_u32 m0, s101, 0xe000
	s_nop 0
	global_load_lds_dwordx4 v[252:253], off
	v_lshl_add_u64 v[252:253], v[252:253], 0, s[34:35]
	s_add_u32 m0, s100, 0x20000
	s_nop 0
	global_load_lds_dwordx4 v[240:241], off
	v_lshl_add_u64 v[240:241], v[240:241], 0, s[34:35]
	s_add_u32 m0, s100, 0x22000
	s_nop 0
	global_load_lds_dwordx4 v[242:243], off
	v_lshl_add_u64 v[242:243], v[242:243], 0, s[34:35]
	s_add_u32 m0, s100, 0x24000
	s_nop 0
	global_load_lds_dwordx4 v[244:245], off
	v_lshl_add_u64 v[244:245], v[244:245], 0, s[34:35]
	s_add_u32 m0, s100, 0x26000
	s_nop 0
	global_load_lds_dwordx4 v[246:247], off
	v_lshl_add_u64 v[246:247], v[246:247], 0, s[34:35]
	v_bfe_u32 v0, v4, 1, 3
	v_and_b32_e32 v142, 15, v4
	v_bitop3_b32 v1, v6, v0, 3 bitop3:0x6c
	v_bitop3_b32 v0, v150, v0, 4 bitop3:0x36
	v_or_b32_e32 v2, v134, v142
	v_or_b32_e32 v3, v143, v142
	v_lshlrev_b32_e32 v171, 4, v0
	v_lshl_add_u32 v153, v2, 7, 0
	v_lshl_add_u32 v169, v3, 7, s79
	v_lshlrev_b32_e32 v170, 4, v1
	s_mov_b64 s[4:5], 0
	s_waitcnt vmcnt(12)
	s_waitcnt lgkmcnt(0)
	s_barrier
	s_branch .LBB0_1106
.LBB0_1106:
	v_add_u32_e32 v172, v153, v170
	v_add_u32_e32 v173, v153, v171
	v_add_u32_e32 v174, v169, v170
	v_add_u32_e32 v175, v169, v171
	v_add_u32_e32 v254, 0x20000, v172
	v_add_u32_e32 v255, 0x20000, v173
	s_nop 1
	ds_read_b128 v[176:179], v172 offset:0
	ds_read_b128 v[180:183], v172 offset:2048
	ds_read_b128 v[184:187], v172 offset:4096
	ds_read_b128 v[188:191], v172 offset:6144
	ds_read_b128 v[208:211], v174 offset:0
	ds_read_b128 v[212:215], v174 offset:2048
	ds_read_b128 v[216:219], v174 offset:4096
	ds_read_b128 v[220:223], v174 offset:6144
	s_waitcnt lgkmcnt(0)
	v_mfma_f32_16x16x32_bf16 v[124:127], v[208:211], v[176:179], 0
	ds_read_b128 v[224:227], v174 offset:8192
	v_mfma_f32_16x16x32_bf16 v[120:123], v[212:215], v[176:179], 0
	ds_read_b128 v[228:231], v174 offset:10240
	v_mfma_f32_16x16x32_bf16 v[116:119], v[216:219], v[176:179], 0
	ds_read_b128 v[232:235], v174 offset:12288
	v_mfma_f32_16x16x32_bf16 v[112:115], v[220:223], v[176:179], 0
	ds_read_b128 v[236:239], v174 offset:14336
	v_mfma_f32_16x16x32_bf16 v[92:95], v[208:211], v[180:183], 0
	v_mfma_f32_16x16x32_bf16 v[88:91], v[212:215], v[180:183], 0
	v_mfma_f32_16x16x32_bf16 v[84:87], v[216:219], v[180:183], 0
	v_mfma_f32_16x16x32_bf16 v[80:83], v[220:223], v[180:183], 0
	v_mfma_f32_16x16x32_bf16 v[60:63], v[208:211], v[184:187], 0
	v_mfma_f32_16x16x32_bf16 v[56:59], v[212:215], v[184:187], 0
	v_mfma_f32_16x16x32_bf16 v[52:55], v[216:219], v[184:187], 0
	v_mfma_f32_16x16x32_bf16 v[48:51], v[220:223], v[184:187], 0
	v_mfma_f32_16x16x32_bf16 v[28:31], v[208:211], v[188:191], 0
	v_mfma_f32_16x16x32_bf16 v[24:27], v[212:215], v[188:191], 0
	v_mfma_f32_16x16x32_bf16 v[20:23], v[216:219], v[188:191], 0
	v_mfma_f32_16x16x32_bf16 v[16:19], v[220:223], v[188:191], 0
	s_waitcnt lgkmcnt(0)
	v_mfma_f32_16x16x32_bf16 v[108:111], v[224:227], v[176:179], 0
	ds_read_b128 v[192:195], v173 offset:0
	v_mfma_f32_16x16x32_bf16 v[104:107], v[228:231], v[176:179], 0
	ds_read_b128 v[196:199], v173 offset:2048
	v_mfma_f32_16x16x32_bf16 v[100:103], v[232:235], v[176:179], 0
	ds_read_b128 v[200:203], v173 offset:4096
	v_mfma_f32_16x16x32_bf16 v[96:99], v[236:239], v[176:179], 0
	ds_read_b128 v[204:207], v173 offset:6144
	v_mfma_f32_16x16x32_bf16 v[76:79], v[224:227], v[180:183], 0
	ds_read_b128 v[208:211], v175 offset:0
	v_mfma_f32_16x16x32_bf16 v[72:75], v[228:231], v[180:183], 0
	ds_read_b128 v[212:215], v175 offset:2048
	v_mfma_f32_16x16x32_bf16 v[68:71], v[232:235], v[180:183], 0
	ds_read_b128 v[216:219], v175 offset:4096
	v_mfma_f32_16x16x32_bf16 v[64:67], v[236:239], v[180:183], 0
	ds_read_b128 v[220:223], v175 offset:6144
	v_mfma_f32_16x16x32_bf16 v[44:47], v[224:227], v[184:187], 0
	v_mfma_f32_16x16x32_bf16 v[40:43], v[228:231], v[184:187], 0
	v_mfma_f32_16x16x32_bf16 v[36:39], v[232:235], v[184:187], 0
	v_mfma_f32_16x16x32_bf16 v[32:35], v[236:239], v[184:187], 0
	v_mfma_f32_16x16x32_bf16 v[12:15], v[224:227], v[188:191], 0
	v_mfma_f32_16x16x32_bf16 v[8:11], v[228:231], v[188:191], 0
	v_mfma_f32_16x16x32_bf16 v[4:7], v[232:235], v[188:191], 0
	v_mfma_f32_16x16x32_bf16 v[0:3], v[236:239], v[188:191], 0
	s_waitcnt lgkmcnt(0)
	v_mfma_f32_16x16x32_bf16 v[124:127], v[208:211], v[192:195], v[124:127]
	ds_read_b128 v[224:227], v175 offset:8192
	v_mfma_f32_16x16x32_bf16 v[120:123], v[212:215], v[192:195], v[120:123]
	ds_read_b128 v[228:231], v175 offset:10240
	v_mfma_f32_16x16x32_bf16 v[116:119], v[216:219], v[192:195], v[116:119]
	ds_read_b128 v[232:235], v175 offset:12288
	v_mfma_f32_16x16x32_bf16 v[112:115], v[220:223], v[192:195], v[112:115]
	ds_read_b128 v[236:239], v175 offset:14336
	v_mfma_f32_16x16x32_bf16 v[92:95], v[208:211], v[196:199], v[92:95]
	v_mfma_f32_16x16x32_bf16 v[88:91], v[212:215], v[196:199], v[88:91]
	v_mfma_f32_16x16x32_bf16 v[84:87], v[216:219], v[196:199], v[84:87]
	v_mfma_f32_16x16x32_bf16 v[80:83], v[220:223], v[196:199], v[80:83]
	v_mfma_f32_16x16x32_bf16 v[60:63], v[208:211], v[200:203], v[60:63]
	v_mfma_f32_16x16x32_bf16 v[56:59], v[212:215], v[200:203], v[56:59]
	v_mfma_f32_16x16x32_bf16 v[52:55], v[216:219], v[200:203], v[52:55]
	v_mfma_f32_16x16x32_bf16 v[48:51], v[220:223], v[200:203], v[48:51]
	v_mfma_f32_16x16x32_bf16 v[28:31], v[208:211], v[204:207], v[28:31]
	v_mfma_f32_16x16x32_bf16 v[24:27], v[212:215], v[204:207], v[24:27]
	v_mfma_f32_16x16x32_bf16 v[20:23], v[216:219], v[204:207], v[20:23]
	v_mfma_f32_16x16x32_bf16 v[16:19], v[220:223], v[204:207], v[16:19]
	s_waitcnt lgkmcnt(0)
	s_waitcnt vmcnt(4)
	s_barrier
	s_mov_b32 s46, 2

.LBB0_1134:
	v_mov_b64_e32 v[0:1], v[132:133]
	v_mov_b64_e32 v[2:3], v[132:133]
	v_mov_b32_e32 v6, v154
	s_lshl_b32 s6, s88, 8
	s_mov_b64 s[4:5], 0x11a00000
	v_ashrrev_i32_e32 v9, 3, v6
	v_add_u32_e32 v4, s6, v9
	v_lshl_add_u64 v[0:1], v[0:1], 0, s[4:5]
	v_lshrrev_b32_e32 v8, 4, v6
	v_ashrrev_i32_e32 v5, 31, v4
	v_xor_b32_e32 v10, v8, v6
	v_lshlrev_b64 v[4:5], 11, v[4:5]
	v_lshl_add_u64 v[0:1], v[0:1], 0, v[4:5]
	v_lshlrev_b32_e32 v4, 4, v10
	s_lshl_b32 s7, s92, 8
	v_and_b32_e32 v134, 0x70, v4
	v_lshl_add_u64 v[128:129], v[0:1], 0, v[134:135]
	v_add_u32_e32 v0, s7, v9
	s_mov_b64 s[4:5], 0x8c0000
	v_ashrrev_i32_e32 v1, 31, v0
	v_lshl_add_u64 v[2:3], v[2:3], 0, s[4:5]
	v_lshlrev_b64 v[0:1], 11, v[0:1]
	v_ashrrev_i32_e32 v7, 6, v6
	v_lshl_add_u64 v[0:1], v[2:3], 0, v[0:1]
	v_lshl_add_u64 v[130:131], v[0:1], 0, v[134:135]
	v_ashrrev_i32_e32 v0, 1, v6
	v_and_b32_e32 v134, 0xffffffc0, v0
	v_lshlrev_b32_e32 v0, 7, v7
	v_and_b32_e32 v143, 0x80, v0
	v_lshlrev_b32_e32 v0, 10, v7
	v_add_u32_e32 v144, 0, v0
	v_add_u32_e32 v145, s79, v0
	v_readfirstlane_b32 s4, v144
	s_mov_b32 m0, s4
	v_readfirstlane_b32 s4, v145
	v_add_u32_e32 v146, 0x2000, v144
	global_load_lds_dwordx4 v[128:129], off
	s_mov_b32 m0, s4
	s_mov_b64 s[20:21], 0x20000
	v_readfirstlane_b32 s4, v146
	v_add_u32_e32 v147, 0x2000, v145
	global_load_lds_dwordx4 v[130:131], off
	v_lshl_add_u64 v[0:1], v[128:129], 0, s[20:21]
	s_mov_b32 m0, s4
	v_readfirstlane_b32 s4, v147
	v_add_u32_e32 v148, 0x4000, v144
	global_load_lds_dwordx4 v[0:1], off
	v_lshl_add_u64 v[0:1], v[130:131], 0, s[20:21]
	s_mov_b32 m0, s4
	s_mov_b64 s[20:21], 0x40000
	v_readfirstlane_b32 s4, v148
	v_add_u32_e32 v150, 0x4000, v145
	global_load_lds_dwordx4 v[0:1], off
	v_lshl_add_u64 v[0:1], v[128:129], 0, s[20:21]
	s_mov_b32 m0, s4
	v_readfirstlane_b32 s4, v150
	v_add_u32_e32 v151, 0x6000, v144
	global_load_lds_dwordx4 v[0:1], off
	v_lshl_add_u64 v[0:1], v[130:131], 0, s[20:21]
	s_mov_b32 m0, s4
	s_mov_b64 s[20:21], 0x60000
	v_readfirstlane_b32 s4, v151
	v_add_u32_e32 v152, 0x6000, v145
	global_load_lds_dwordx4 v[0:1], off
	v_lshl_add_u64 v[0:1], v[128:129], 0, s[20:21]
	s_mov_b32 m0, s4
	v_readfirstlane_b32 s4, v152
	global_load_lds_dwordx4 v[0:1], off
	v_lshl_add_u64 v[0:1], v[130:131], 0, s[20:21]
	s_mov_b32 m0, s4
	v_bfe_u32 v149, v6, 4, 2
	global_load_lds_dwordx4 v[0:1], off
	s_mov_b64 s[100:101], 0x80
	v_lshl_add_u64 v[240:241], v[128:129], 0, s[100:101]
	s_mov_b64 s[100:101], 0x20080
	v_lshl_add_u64 v[242:243], v[128:129], 0, s[100:101]
	s_mov_b64 s[100:101], 0x40080
	v_lshl_add_u64 v[244:245], v[128:129], 0, s[100:101]
	s_mov_b64 s[100:101], 0x60080
	v_lshl_add_u64 v[246:247], v[128:129], 0, s[100:101]
	s_mov_b64 s[100:101], 0x80
	v_lshl_add_u64 v[138:139], v[130:131], 0, s[100:101]
	s_mov_b64 s[100:101], 0x20080
	v_lshl_add_u64 v[140:141], v[130:131], 0, s[100:101]
	s_mov_b64 s[100:101], 0x40080
	v_lshl_add_u64 v[250:251], v[130:131], 0, s[100:101]
	s_mov_b64 s[100:101], 0x60080
	v_lshl_add_u64 v[252:253], v[130:131], 0, s[100:101]
	v_readfirstlane_b32 s100, v144
	v_readfirstlane_b32 s101, v145
	s_nop 3
	s_add_u32 m0, s100, 0x8000
	s_nop 0
	global_load_lds_dwordx4 v[240:241], off
	v_lshl_add_u64 v[240:241], v[240:241], 0, s[34:35]
	s_add_u32 m0, s100, 0xa000
	s_nop 0
	global_load_lds_dwordx4 v[242:243], off
	v_lshl_add_u64 v[242:243], v[242:243], 0, s[34:35]
	s_add_u32 m0, s100, 0xc000
	s_nop 0
	global_load_lds_dwordx4 v[244:245], off
	v_lshl_add_u64 v[244:245], v[244:245], 0, s[34:35]
	s_add_u32 m0, s100, 0xe000
	s_nop 0
	global_load_lds_dwordx4 v[246:247], off
	v_lshl_add_u64 v[246:247], v[246:247], 0, s[34:35]
	s_add_u32 m0, s101, 0x8000
	s_nop 0
	global_load_lds_dwordx4 v[138:139], off
	v_lshl_add_u64 v[138:139], v[138:139], 0, s[34:35]
	s_add_u32 m0, s101, 0xa000
	s_nop 0
	global_load_lds_dwordx4 v[140:141], off
	v_lshl_add_u64 v[140:141], v[140:141], 0, s[34:35]
	s_add_u32 m0, s101, 0xc000
	s_nop 0
	global_load_lds_dwordx4 v[250:251], off
	v_lshl_add_u64 v[250:251], v[250:251], 0, s[34:35]
	s_add_u32 m0, s101, 0xe000
	s_nop 0
	global_load_lds_dwordx4 v[252:253], off
	v_lshl_add_u64 v[252:253], v[252:253], 0, s[34:35]
	s_add_u32 m0, s100, 0x20000
	s_nop 0
	global_load_lds_dwordx4 v[240:241], off
	v_lshl_add_u64 v[240:241], v[240:241], 0, s[34:35]
	s_add_u32 m0, s100, 0x22000
	s_nop 0
	global_load_lds_dwordx4 v[242:243], off
	v_lshl_add_u64 v[242:243], v[242:243], 0, s[34:35]
	s_add_u32 m0, s100, 0x24000
	s_nop 0
	global_load_lds_dwordx4 v[244:245], off
	v_lshl_add_u64 v[244:245], v[244:245], 0, s[34:35]
	s_add_u32 m0, s100, 0x26000
	s_nop 0
	global_load_lds_dwordx4 v[246:247], off
	v_lshl_add_u64 v[246:247], v[246:247], 0, s[34:35]
	v_bfe_u32 v0, v6, 1, 3
	v_and_b32_e32 v142, 15, v6
	v_bitop3_b32 v1, v8, v0, 3 bitop3:0x6c
	v_bitop3_b32 v0, v149, v0, 4 bitop3:0x36
	v_or_b32_e32 v2, v134, v142
	v_or_b32_e32 v3, v143, v142
	v_lshlrev_b32_e32 v171, 4, v0
	v_lshl_add_u32 v153, v2, 7, 0
	v_lshl_add_u32 v169, v3, 7, s79
	v_lshlrev_b32_e32 v170, 4, v1
	s_mov_b64 s[4:5], 0
	s_waitcnt vmcnt(12) lgkmcnt(0)
	s_barrier
	s_branch .LBB0_1136
.LBB0_1136:
	v_add_u32_e32 v172, v153, v170
	v_add_u32_e32 v173, v153, v171
	v_add_u32_e32 v174, v169, v170
	v_add_u32_e32 v175, v169, v171
	v_add_u32_e32 v254, 0x20000, v172
	v_add_u32_e32 v255, 0x20000, v173
	s_nop 1
	ds_read_b128 v[176:179], v172 offset:0
	ds_read_b128 v[180:183], v172 offset:2048
	ds_read_b128 v[184:187], v172 offset:4096
	ds_read_b128 v[188:191], v172 offset:6144
	ds_read_b128 v[208:211], v174 offset:0
	ds_read_b128 v[212:215], v174 offset:2048
	ds_read_b128 v[216:219], v174 offset:4096
	ds_read_b128 v[220:223], v174 offset:6144
	s_waitcnt lgkmcnt(0)
	v_mfma_f32_16x16x32_bf16 v[124:127], v[208:211], v[176:179], 0
	ds_read_b128 v[224:227], v174 offset:8192
	v_mfma_f32_16x16x32_bf16 v[120:123], v[212:215], v[176:179], 0
	ds_read_b128 v[228:231], v174 offset:10240
	v_mfma_f32_16x16x32_bf16 v[116:119], v[216:219], v[176:179], 0
	ds_read_b128 v[232:235], v174 offset:12288
	v_mfma_f32_16x16x32_bf16 v[112:115], v[220:223], v[176:179], 0
	ds_read_b128 v[236:239], v174 offset:14336
	v_mfma_f32_16x16x32_bf16 v[92:95], v[208:211], v[180:183], 0
	v_mfma_f32_16x16x32_bf16 v[88:91], v[212:215], v[180:183], 0
	v_mfma_f32_16x16x32_bf16 v[84:87], v[216:219], v[180:183], 0
	v_mfma_f32_16x16x32_bf16 v[80:83], v[220:223], v[180:183], 0
	v_mfma_f32_16x16x32_bf16 v[60:63], v[208:211], v[184:187], 0
	v_mfma_f32_16x16x32_bf16 v[56:59], v[212:215], v[184:187], 0
	v_mfma_f32_16x16x32_bf16 v[52:55], v[216:219], v[184:187], 0
	v_mfma_f32_16x16x32_bf16 v[48:51], v[220:223], v[184:187], 0
	v_mfma_f32_16x16x32_bf16 v[28:31], v[208:211], v[188:191], 0
	v_mfma_f32_16x16x32_bf16 v[24:27], v[212:215], v[188:191], 0
	v_mfma_f32_16x16x32_bf16 v[20:23], v[216:219], v[188:191], 0
	v_mfma_f32_16x16x32_bf16 v[16:19], v[220:223], v[188:191], 0
	s_waitcnt lgkmcnt(0)
	v_mfma_f32_16x16x32_bf16 v[108:111], v[224:227], v[176:179], 0
	ds_read_b128 v[192:195], v173 offset:0
	v_mfma_f32_16x16x32_bf16 v[104:107], v[228:231], v[176:179], 0
	ds_read_b128 v[196:199], v173 offset:2048
	v_mfma_f32_16x16x32_bf16 v[100:103], v[232:235], v[176:179], 0
	ds_read_b128 v[200:203], v173 offset:4096
	v_mfma_f32_16x16x32_bf16 v[96:99], v[236:239], v[176:179], 0
	ds_read_b128 v[204:207], v173 offset:6144
	v_mfma_f32_16x16x32_bf16 v[76:79], v[224:227], v[180:183], 0
	ds_read_b128 v[208:211], v175 offset:0
	v_mfma_f32_16x16x32_bf16 v[72:75], v[228:231], v[180:183], 0
	ds_read_b128 v[212:215], v175 offset:2048
	v_mfma_f32_16x16x32_bf16 v[68:71], v[232:235], v[180:183], 0
	ds_read_b128 v[216:219], v175 offset:4096
	v_mfma_f32_16x16x32_bf16 v[64:67], v[236:239], v[180:183], 0
	ds_read_b128 v[220:223], v175 offset:6144
	v_mfma_f32_16x16x32_bf16 v[44:47], v[224:227], v[184:187], 0
	v_mfma_f32_16x16x32_bf16 v[40:43], v[228:231], v[184:187], 0
	v_mfma_f32_16x16x32_bf16 v[36:39], v[232:235], v[184:187], 0
	v_mfma_f32_16x16x32_bf16 v[32:35], v[236:239], v[184:187], 0
	v_mfma_f32_16x16x32_bf16 v[12:15], v[224:227], v[188:191], 0
	v_mfma_f32_16x16x32_bf16 v[8:11], v[228:231], v[188:191], 0
	v_mfma_f32_16x16x32_bf16 v[4:7], v[232:235], v[188:191], 0
	v_mfma_f32_16x16x32_bf16 v[0:3], v[236:239], v[188:191], 0
	s_waitcnt lgkmcnt(0)
	v_mfma_f32_16x16x32_bf16 v[124:127], v[208:211], v[192:195], v[124:127]
	ds_read_b128 v[224:227], v175 offset:8192
	v_mfma_f32_16x16x32_bf16 v[120:123], v[212:215], v[192:195], v[120:123]
	ds_read_b128 v[228:231], v175 offset:10240
	v_mfma_f32_16x16x32_bf16 v[116:119], v[216:219], v[192:195], v[116:119]
	ds_read_b128 v[232:235], v175 offset:12288
	v_mfma_f32_16x16x32_bf16 v[112:115], v[220:223], v[192:195], v[112:115]
	ds_read_b128 v[236:239], v175 offset:14336
	v_mfma_f32_16x16x32_bf16 v[92:95], v[208:211], v[196:199], v[92:95]
	v_mfma_f32_16x16x32_bf16 v[88:91], v[212:215], v[196:199], v[88:91]
	v_mfma_f32_16x16x32_bf16 v[84:87], v[216:219], v[196:199], v[84:87]
	v_mfma_f32_16x16x32_bf16 v[80:83], v[220:223], v[196:199], v[80:83]
	v_mfma_f32_16x16x32_bf16 v[60:63], v[208:211], v[200:203], v[60:63]
	v_mfma_f32_16x16x32_bf16 v[56:59], v[212:215], v[200:203], v[56:59]
	v_mfma_f32_16x16x32_bf16 v[52:55], v[216:219], v[200:203], v[52:55]
	v_mfma_f32_16x16x32_bf16 v[48:51], v[220:223], v[200:203], v[48:51]
	v_mfma_f32_16x16x32_bf16 v[28:31], v[208:211], v[204:207], v[28:31]
	v_mfma_f32_16x16x32_bf16 v[24:27], v[212:215], v[204:207], v[24:27]
	v_mfma_f32_16x16x32_bf16 v[20:23], v[216:219], v[204:207], v[20:23]
	v_mfma_f32_16x16x32_bf16 v[16:19], v[220:223], v[204:207], v[16:19]
	s_waitcnt lgkmcnt(0)
	s_waitcnt vmcnt(4)
	s_barrier
	s_mov_b32 s44, 2

.LBB0_1155:
	v_mov_b64_e32 v[0:1], v[132:133]
	v_mov_b64_e32 v[2:3], v[132:133]
	v_mov_b32_e32 v6, v154
	s_lshl_b32 s6, s76, 8
	v_lshl_add_u64 v[0:1], v[0:1], 0, s[22:23]
	v_ashrrev_i32_e32 v9, 3, v6
	v_add_u32_e32 v4, s6, v9
	v_lshrrev_b32_e32 v8, 4, v6
	v_ashrrev_i32_e32 v5, 31, v4
	v_xor_b32_e32 v10, v8, v6
	v_lshlrev_b64 v[4:5], 13, v[4:5]
	v_lshl_add_u64 v[0:1], v[0:1], 0, v[4:5]
	v_lshlrev_b32_e32 v4, 4, v10
	s_lshl_b32 s7, s3, 8
	v_and_b32_e32 v134, 0x70, v4
	v_lshl_add_u64 v[128:129], v[0:1], 0, v[134:135]
	v_add_u32_e32 v0, s7, v9
	v_ashrrev_i32_e32 v1, 31, v0
	v_lshl_add_u64 v[2:3], v[2:3], 0, s[16:17]
	v_lshlrev_b64 v[0:1], 13, v[0:1]
	v_ashrrev_i32_e32 v7, 6, v6
	v_lshl_add_u64 v[0:1], v[2:3], 0, v[0:1]
	v_lshl_add_u64 v[130:131], v[0:1], 0, v[134:135]
	v_ashrrev_i32_e32 v0, 1, v6
	v_and_b32_e32 v134, 0xffffffc0, v0
	v_lshlrev_b32_e32 v0, 7, v7
	v_and_b32_e32 v143, 0x80, v0
	v_lshlrev_b32_e32 v0, 10, v7
	v_add_u32_e32 v144, 0, v0
	v_add_u32_e32 v145, s79, v0
	v_readfirstlane_b32 s4, v144
	s_mov_b32 m0, s4
	v_readfirstlane_b32 s4, v145
	v_add_u32_e32 v146, 0x2000, v144
	global_load_lds_dwordx4 v[128:129], off
	s_mov_b32 m0, s4
	s_mov_b64 s[20:21], 0x80000
	v_readfirstlane_b32 s4, v146
	v_add_u32_e32 v147, 0x2000, v145
	global_load_lds_dwordx4 v[130:131], off
	v_lshl_add_u64 v[0:1], v[128:129], 0, s[20:21]
	s_mov_b32 m0, s4
	v_readfirstlane_b32 s4, v147
	v_add_u32_e32 v148, 0x4000, v144
	global_load_lds_dwordx4 v[0:1], off
	v_lshl_add_u64 v[0:1], v[130:131], 0, s[20:21]
	s_mov_b32 m0, s4
	s_mov_b64 s[20:21], 0x100000
	v_readfirstlane_b32 s4, v148
	v_add_u32_e32 v149, 0x4000, v145
	global_load_lds_dwordx4 v[0:1], off
	v_lshl_add_u64 v[0:1], v[128:129], 0, s[20:21]
	s_mov_b32 m0, s4
	v_readfirstlane_b32 s4, v149
	v_add_u32_e32 v151, 0x6000, v144
	global_load_lds_dwordx4 v[0:1], off
	v_lshl_add_u64 v[0:1], v[130:131], 0, s[20:21]
	s_mov_b32 m0, s4
	s_mov_b64 s[20:21], 0x180000
	v_readfirstlane_b32 s4, v151
	v_add_u32_e32 v152, 0x6000, v145
	global_load_lds_dwordx4 v[0:1], off
	v_lshl_add_u64 v[0:1], v[128:129], 0, s[20:21]
	s_mov_b32 m0, s4
	v_readfirstlane_b32 s4, v152
	global_load_lds_dwordx4 v[0:1], off
	v_lshl_add_u64 v[0:1], v[130:131], 0, s[20:21]
	s_mov_b32 m0, s4
	v_bfe_u32 v150, v6, 4, 2
	global_load_lds_dwordx4 v[0:1], off
	s_mov_b64 s[100:101], 0x80
	v_lshl_add_u64 v[240:241], v[128:129], 0, s[100:101]
	s_mov_b64 s[100:101], 0x80080
	v_lshl_add_u64 v[242:243], v[128:129], 0, s[100:101]
	s_mov_b64 s[100:101], 0x100080
	v_lshl_add_u64 v[244:245], v[128:129], 0, s[100:101]
	s_mov_b64 s[100:101], 0x180080
	v_lshl_add_u64 v[246:247], v[128:129], 0, s[100:101]
	s_mov_b64 s[100:101], 0x80
	v_lshl_add_u64 v[138:139], v[130:131], 0, s[100:101]
	s_mov_b64 s[100:101], 0x80080
	v_lshl_add_u64 v[140:141], v[130:131], 0, s[100:101]
	s_mov_b64 s[100:101], 0x100080
	v_lshl_add_u64 v[250:251], v[130:131], 0, s[100:101]
	s_mov_b64 s[100:101], 0x180080
	v_lshl_add_u64 v[252:253], v[130:131], 0, s[100:101]
	v_readfirstlane_b32 s100, v144
	v_readfirstlane_b32 s101, v145
	s_nop 3
	s_add_u32 m0, s100, 0x8000
	s_nop 0
	global_load_lds_dwordx4 v[240:241], off
	v_lshl_add_u64 v[240:241], v[240:241], 0, s[34:35]
	s_add_u32 m0, s100, 0xa000
	s_nop 0
	global_load_lds_dwordx4 v[242:243], off
	v_lshl_add_u64 v[242:243], v[242:243], 0, s[34:35]
	s_add_u32 m0, s100, 0xc000
	s_nop 0
	global_load_lds_dwordx4 v[244:245], off
	v_lshl_add_u64 v[244:245], v[244:245], 0, s[34:35]
	s_add_u32 m0, s100, 0xe000
	s_nop 0
	global_load_lds_dwordx4 v[246:247], off
	v_lshl_add_u64 v[246:247], v[246:247], 0, s[34:35]
	s_add_u32 m0, s101, 0x8000
	s_nop 0
	global_load_lds_dwordx4 v[138:139], off
	v_lshl_add_u64 v[138:139], v[138:139], 0, s[34:35]
	s_add_u32 m0, s101, 0xa000
	s_nop 0
	global_load_lds_dwordx4 v[140:141], off
	v_lshl_add_u64 v[140:141], v[140:141], 0, s[34:35]
	s_add_u32 m0, s101, 0xc000
	s_nop 0
	global_load_lds_dwordx4 v[250:251], off
	v_lshl_add_u64 v[250:251], v[250:251], 0, s[34:35]
	s_add_u32 m0, s101, 0xe000
	s_nop 0
	global_load_lds_dwordx4 v[252:253], off
	v_lshl_add_u64 v[252:253], v[252:253], 0, s[34:35]
	s_add_u32 m0, s100, 0x20000
	s_nop 0
	global_load_lds_dwordx4 v[240:241], off
	v_lshl_add_u64 v[240:241], v[240:241], 0, s[34:35]
	s_add_u32 m0, s100, 0x22000
	s_nop 0
	global_load_lds_dwordx4 v[242:243], off
	v_lshl_add_u64 v[242:243], v[242:243], 0, s[34:35]
	s_add_u32 m0, s100, 0x24000
	s_nop 0
	global_load_lds_dwordx4 v[244:245], off
	v_lshl_add_u64 v[244:245], v[244:245], 0, s[34:35]
	s_add_u32 m0, s100, 0x26000
	s_nop 0
	global_load_lds_dwordx4 v[246:247], off
	v_lshl_add_u64 v[246:247], v[246:247], 0, s[34:35]
	v_bfe_u32 v0, v6, 1, 3
	v_and_b32_e32 v142, 15, v6
	v_bitop3_b32 v1, v8, v0, 3 bitop3:0x6c
	v_bitop3_b32 v0, v150, v0, 4 bitop3:0x36
	v_or_b32_e32 v2, v134, v142
	v_or_b32_e32 v3, v143, v142
	v_lshlrev_b32_e32 v171, 4, v0
	v_lshl_add_u32 v153, v2, 7, 0
	v_lshl_add_u32 v169, v3, 7, s79
	v_lshlrev_b32_e32 v170, 4, v1
	s_mov_b64 s[4:5], 0
	s_waitcnt vmcnt(12) lgkmcnt(0)
	s_barrier
	s_branch .LBB0_1157
.LBB0_1157:
	v_add_u32_e32 v172, v153, v170
	v_add_u32_e32 v173, v153, v171
	v_add_u32_e32 v174, v169, v170
	v_add_u32_e32 v175, v169, v171
	v_add_u32_e32 v254, 0x20000, v172
	v_add_u32_e32 v255, 0x20000, v173
	s_nop 1
	ds_read_b128 v[176:179], v172 offset:0
	ds_read_b128 v[180:183], v172 offset:2048
	ds_read_b128 v[184:187], v172 offset:4096
	ds_read_b128 v[188:191], v172 offset:6144
	ds_read_b128 v[208:211], v174 offset:0
	ds_read_b128 v[212:215], v174 offset:2048
	ds_read_b128 v[216:219], v174 offset:4096
	ds_read_b128 v[220:223], v174 offset:6144
	s_waitcnt lgkmcnt(0)
	v_mfma_f32_16x16x32_bf16 v[124:127], v[208:211], v[176:179], 0
	ds_read_b128 v[224:227], v174 offset:8192
	v_mfma_f32_16x16x32_bf16 v[120:123], v[212:215], v[176:179], 0
	ds_read_b128 v[228:231], v174 offset:10240
	v_mfma_f32_16x16x32_bf16 v[116:119], v[216:219], v[176:179], 0
	ds_read_b128 v[232:235], v174 offset:12288
	v_mfma_f32_16x16x32_bf16 v[112:115], v[220:223], v[176:179], 0
	ds_read_b128 v[236:239], v174 offset:14336
	v_mfma_f32_16x16x32_bf16 v[92:95], v[208:211], v[180:183], 0
	v_mfma_f32_16x16x32_bf16 v[88:91], v[212:215], v[180:183], 0
	v_mfma_f32_16x16x32_bf16 v[84:87], v[216:219], v[180:183], 0
	v_mfma_f32_16x16x32_bf16 v[80:83], v[220:223], v[180:183], 0
	v_mfma_f32_16x16x32_bf16 v[60:63], v[208:211], v[184:187], 0
	v_mfma_f32_16x16x32_bf16 v[56:59], v[212:215], v[184:187], 0
	v_mfma_f32_16x16x32_bf16 v[52:55], v[216:219], v[184:187], 0
	v_mfma_f32_16x16x32_bf16 v[48:51], v[220:223], v[184:187], 0
	v_mfma_f32_16x16x32_bf16 v[28:31], v[208:211], v[188:191], 0
	v_mfma_f32_16x16x32_bf16 v[24:27], v[212:215], v[188:191], 0
	v_mfma_f32_16x16x32_bf16 v[20:23], v[216:219], v[188:191], 0
	v_mfma_f32_16x16x32_bf16 v[16:19], v[220:223], v[188:191], 0
	s_waitcnt lgkmcnt(0)
	v_mfma_f32_16x16x32_bf16 v[108:111], v[224:227], v[176:179], 0
	ds_read_b128 v[192:195], v173 offset:0
	v_mfma_f32_16x16x32_bf16 v[104:107], v[228:231], v[176:179], 0
	ds_read_b128 v[196:199], v173 offset:2048
	v_mfma_f32_16x16x32_bf16 v[100:103], v[232:235], v[176:179], 0
	ds_read_b128 v[200:203], v173 offset:4096
	v_mfma_f32_16x16x32_bf16 v[96:99], v[236:239], v[176:179], 0
	ds_read_b128 v[204:207], v173 offset:6144
	v_mfma_f32_16x16x32_bf16 v[76:79], v[224:227], v[180:183], 0
	ds_read_b128 v[208:211], v175 offset:0
	v_mfma_f32_16x16x32_bf16 v[72:75], v[228:231], v[180:183], 0
	ds_read_b128 v[212:215], v175 offset:2048
	v_mfma_f32_16x16x32_bf16 v[68:71], v[232:235], v[180:183], 0
	ds_read_b128 v[216:219], v175 offset:4096
	v_mfma_f32_16x16x32_bf16 v[64:67], v[236:239], v[180:183], 0
	ds_read_b128 v[220:223], v175 offset:6144
	v_mfma_f32_16x16x32_bf16 v[44:47], v[224:227], v[184:187], 0
	v_mfma_f32_16x16x32_bf16 v[40:43], v[228:231], v[184:187], 0
	v_mfma_f32_16x16x32_bf16 v[36:39], v[232:235], v[184:187], 0
	v_mfma_f32_16x16x32_bf16 v[32:35], v[236:239], v[184:187], 0
	v_mfma_f32_16x16x32_bf16 v[12:15], v[224:227], v[188:191], 0
	v_mfma_f32_16x16x32_bf16 v[8:11], v[228:231], v[188:191], 0
	v_mfma_f32_16x16x32_bf16 v[4:7], v[232:235], v[188:191], 0
	v_mfma_f32_16x16x32_bf16 v[0:3], v[236:239], v[188:191], 0
	s_waitcnt lgkmcnt(0)
	v_mfma_f32_16x16x32_bf16 v[124:127], v[208:211], v[192:195], v[124:127]
	ds_read_b128 v[224:227], v175 offset:8192
	v_mfma_f32_16x16x32_bf16 v[120:123], v[212:215], v[192:195], v[120:123]
	ds_read_b128 v[228:231], v175 offset:10240
	v_mfma_f32_16x16x32_bf16 v[116:119], v[216:219], v[192:195], v[116:119]
	ds_read_b128 v[232:235], v175 offset:12288
	v_mfma_f32_16x16x32_bf16 v[112:115], v[220:223], v[192:195], v[112:115]
	ds_read_b128 v[236:239], v175 offset:14336
	v_mfma_f32_16x16x32_bf16 v[92:95], v[208:211], v[196:199], v[92:95]
	v_mfma_f32_16x16x32_bf16 v[88:91], v[212:215], v[196:199], v[88:91]
	v_mfma_f32_16x16x32_bf16 v[84:87], v[216:219], v[196:199], v[84:87]
	v_mfma_f32_16x16x32_bf16 v[80:83], v[220:223], v[196:199], v[80:83]
	v_mfma_f32_16x16x32_bf16 v[60:63], v[208:211], v[200:203], v[60:63]
	v_mfma_f32_16x16x32_bf16 v[56:59], v[212:215], v[200:203], v[56:59]
	v_mfma_f32_16x16x32_bf16 v[52:55], v[216:219], v[200:203], v[52:55]
	v_mfma_f32_16x16x32_bf16 v[48:51], v[220:223], v[200:203], v[48:51]
	v_mfma_f32_16x16x32_bf16 v[28:31], v[208:211], v[204:207], v[28:31]
	v_mfma_f32_16x16x32_bf16 v[24:27], v[212:215], v[204:207], v[24:27]
	v_mfma_f32_16x16x32_bf16 v[20:23], v[216:219], v[204:207], v[20:23]
	v_mfma_f32_16x16x32_bf16 v[16:19], v[220:223], v[204:207], v[16:19]
	s_waitcnt lgkmcnt(0)
	s_waitcnt vmcnt(4)
	s_barrier
	s_mov_b32 s44, 10
